# tile start: trailing half's re-entry barrier moved from epilogue end to just before its first load segment (header+acc zeroing now overlap the leading half); leading half issues first-iteration DMA/ds
# baseline (speedup 1.0000x reference)
.LBB0_207:
	s_add_u32 s50, s54, 0xc000000
	s_addc_u32 s51, s55, 0
	s_lshl_b32 s5, s5, 5
	s_mov_b64 s[12:13], 0x80
	s_and_b32 s5, s5, 0x60
	s_add_i32 m0, s31, 0x18000
	v_lshl_add_u64 v[6:7], v[6:7], 0, s[12:13]
	s_lshl_b32 s7, s4, 13
	s_lshl_b32 s15, s5, 7
	s_waitcnt vmcnt(2)
	s_barrier
	global_load_lds_dwordx4 v[6:7], off
	v_lshl_add_u64 v[2:3], v[2:3], 0, s[12:13]
	s_add_i32 m0, s31, 0x1a000
	s_add_i32 s60, s31, 0x8000
	s_add_i32 s61, s31, 0xa000
	global_load_lds_dwordx4 v[2:3], off
	v_lshl_add_u64 v[0:1], v[0:1], 0, s[12:13]
	s_mov_b32 m0, s60
	s_add_u32 s16, s36, 0x40080
	global_load_lds_dwordx4 v[0:1], off
	v_lshl_add_u64 v[0:1], v[4:5], 0, s[12:13]
	s_mov_b32 m0, s61
	s_addc_u32 s17, s37, 0
	global_load_lds_dwordx4 v[0:1], off
	s_add_i32 m0, s31, 0x1c000
	v_lshl_add_u64 v[0:1], s[16:17], 0, v[130:131]
	global_load_lds_dwordx4 v[0:1], off
	v_lshl_add_u64 v[0:1], s[16:17], 0, v[134:135]
	s_add_i32 m0, s31, 0x1e000
	s_cmpk_lt_u32 s14, 0x100
	global_load_lds_dwordx4 v[0:1], off
	v_lshrrev_b32_e32 v1, 1, v8
	v_and_b32_e32 v1, 24, v1
	v_and_b32_e32 v0, 15, v8
	v_lshlrev_b32_e32 v2, 1, v1
	v_lshl_or_b32 v152, s4, 6, v0
	v_lshl_or_b32 v0, v0, 6, v2
	v_lshlrev_b32_e32 v2, 2, v8
	v_and_b32_e32 v2, 32, v2
	v_bitop3_b32 v3, v0, s7, v2 bitop3:0xde
	v_bitop3_b32 v153, v0, s15, v2 bitop3:0xde
	v_lshlrev_b32_e32 v0, 14, v9
	v_and_b32_e32 v0, 0xffff8000, v0
	v_or_b32_e32 v154, s5, v1
	v_lshl_add_u32 v0, v10, 11, v0
	v_and_b32_e32 v1, 1, v9
	v_lshl_or_b32 v0, v1, 6, v0
	v_lshl_add_u32 v138, v11, 1, v0
	v_lshlrev_b32_e32 v0, 14, v12
	v_and_b32_e32 v0, 0xffff8000, v0
	s_waitcnt vmcnt(6)
	v_lshl_add_u32 v0, v13, 11, v0
	v_and_b32_e32 v1, 1, v12
	s_cselect_b64 s[14:15], -1, 0
	v_lshl_or_b32 v0, v1, 6, v0
	s_add_i32 s65, 0, 0x10000
	s_add_i32 s67, 0, 0x14000
	s_ashr_i32 s62, s52, 31
	s_mov_b32 s63, s52
	s_ashr_i32 s64, s33, 31
	v_mov_b32_e32 v139, v137
	v_lshl_add_u32 v140, v14, 1, v0
	v_mov_b32_e32 v141, v137
	v_mov_b64_e32 v[142:143], 0x400
	v_mov_b64_e32 v[144:145], 0x3ff
	v_add_u32_e32 v155, s65, v153
	v_add_u32_e32 v156, s67, v153
	v_add_u32_e32 v157, 0, v3
	s_mov_b64 s[16:17], 0x48000
	s_mov_b64 s[18:19], 0x50000
	s_mov_b64 s[20:21], 0x58000
	s_barrier
	s_mov_b32 s101, 0
	s_branch .LBB0_210

.LBB0_216:
	s_ashr_i32 s25, s24, 31
	s_lshl_b64 s[26:27], s[24:25], 19
	s_add_u32 s26, s58, s26
	s_addc_u32 s27, s59, s27
	s_and_b64 s[28:29], s[4:5], exec
	s_cselect_b32 s7, s27, s35
	s_cselect_b32 s25, s26, s34
	s_ashr_i32 s23, s22, 31
	s_lshl_b64 s[28:29], s[22:23], 19
	s_add_u32 s28, s41, s28
	s_addc_u32 s29, s42, s29
	s_and_b64 s[38:39], s[4:5], exec
	s_cselect_b32 s23, s29, s37
	s_cselect_b32 s68, s28, s36
	s_add_u32 s34, s34, 0x40080
	s_addc_u32 s35, s35, 0
	s_add_u32 s69, s36, 0x100
	v_mov_b32_e32 v0, 0
	s_addc_u32 s70, s37, 0
	s_mov_b32 s71, -2
	s_cmp_lg_u32 s101, 0
	s_cbranch_scc0 .Lph217_a
	v_mov_b32_e32 v1, v0
	v_mov_b32_e32 v2, v0
	v_mov_b32_e32 v3, v0
	v_mov_b32_e32 v4, v0
	v_mov_b32_e32 v5, v0
	v_mov_b32_e32 v6, v0
	v_mov_b32_e32 v7, v0
	v_mov_b32_e32 v16, v0
	v_mov_b32_e32 v17, v0
	v_mov_b32_e32 v18, v0
	v_mov_b32_e32 v19, v0
	v_mov_b32_e32 v20, v0
	v_mov_b32_e32 v21, v0
	v_mov_b32_e32 v22, v0
	v_mov_b32_e32 v23, v0
	v_mov_b32_e32 v32, v0
	v_mov_b32_e32 v33, v0
	v_mov_b32_e32 v34, v0
	v_mov_b32_e32 v35, v0
	v_mov_b32_e32 v36, v0
	v_mov_b32_e32 v37, v0
	v_mov_b32_e32 v38, v0
	v_mov_b32_e32 v39, v0
	v_mov_b32_e32 v48, v0
	v_mov_b32_e32 v49, v0
	v_mov_b32_e32 v50, v0
	v_mov_b32_e32 v51, v0
	v_mov_b32_e32 v52, v0
	v_mov_b32_e32 v53, v0
	v_mov_b32_e32 v54, v0
	v_mov_b32_e32 v55, v0
	v_mov_b32_e32 v8, v0
	v_mov_b32_e32 v9, v0
	v_mov_b32_e32 v10, v0
	v_mov_b32_e32 v11, v0
	v_mov_b32_e32 v12, v0
	v_mov_b32_e32 v13, v0
	v_mov_b32_e32 v14, v0
	v_mov_b32_e32 v15, v0
	v_mov_b32_e32 v24, v0
	v_mov_b32_e32 v25, v0
	v_mov_b32_e32 v26, v0
	v_mov_b32_e32 v27, v0
	v_mov_b32_e32 v28, v0
	v_mov_b32_e32 v29, v0
	v_mov_b32_e32 v30, v0
	v_mov_b32_e32 v31, v0
	v_mov_b32_e32 v40, v0
	v_mov_b32_e32 v41, v0
	v_mov_b32_e32 v42, v0
	v_mov_b32_e32 v43, v0
	v_mov_b32_e32 v44, v0
	v_mov_b32_e32 v45, v0
	v_mov_b32_e32 v46, v0
	v_mov_b32_e32 v47, v0
	v_mov_b32_e32 v56, v0
	v_mov_b32_e32 v57, v0
	v_mov_b32_e32 v58, v0
	v_mov_b32_e32 v59, v0
	v_mov_b32_e32 v60, v0
	v_mov_b32_e32 v61, v0
	v_mov_b32_e32 v62, v0
	v_mov_b32_e32 v63, v0
	v_mov_b32_e32 v64, v0
	v_mov_b32_e32 v65, v0
	v_mov_b32_e32 v66, v0
	v_mov_b32_e32 v67, v0
	v_mov_b32_e32 v68, v0
	v_mov_b32_e32 v69, v0
	v_mov_b32_e32 v70, v0
	v_mov_b32_e32 v71, v0
	v_mov_b32_e32 v80, v0
	v_mov_b32_e32 v81, v0
	v_mov_b32_e32 v82, v0
	v_mov_b32_e32 v83, v0
	v_mov_b32_e32 v84, v0
	v_mov_b32_e32 v85, v0
	v_mov_b32_e32 v86, v0
	v_mov_b32_e32 v87, v0
	v_mov_b32_e32 v96, v0
	v_mov_b32_e32 v97, v0
	v_mov_b32_e32 v98, v0
	v_mov_b32_e32 v99, v0
	v_mov_b32_e32 v100, v0
	v_mov_b32_e32 v101, v0
	v_mov_b32_e32 v102, v0
	v_mov_b32_e32 v103, v0
	v_mov_b32_e32 v112, v0
	v_mov_b32_e32 v113, v0
	v_mov_b32_e32 v114, v0
	v_mov_b32_e32 v115, v0
	v_mov_b32_e32 v116, v0
	v_mov_b32_e32 v117, v0
	v_mov_b32_e32 v118, v0
	v_mov_b32_e32 v119, v0
	v_mov_b32_e32 v72, v0
	v_mov_b32_e32 v73, v0
	v_mov_b32_e32 v74, v0
	v_mov_b32_e32 v75, v0
	v_mov_b32_e32 v76, v0
	v_mov_b32_e32 v77, v0
	v_mov_b32_e32 v78, v0
	v_mov_b32_e32 v79, v0
	v_mov_b32_e32 v88, v0
	v_mov_b32_e32 v89, v0
	v_mov_b32_e32 v90, v0
	v_mov_b32_e32 v91, v0
	v_mov_b32_e32 v92, v0
	v_mov_b32_e32 v93, v0
	v_mov_b32_e32 v94, v0
	v_mov_b32_e32 v95, v0
	v_mov_b32_e32 v104, v0
	v_mov_b32_e32 v105, v0
	v_mov_b32_e32 v106, v0
	v_mov_b32_e32 v107, v0
	v_mov_b32_e32 v108, v0
	v_mov_b32_e32 v109, v0
	v_mov_b32_e32 v110, v0
	v_mov_b32_e32 v111, v0
	v_mov_b32_e32 v120, v0
	v_mov_b32_e32 v121, v0
	v_mov_b32_e32 v122, v0
	v_mov_b32_e32 v123, v0
	v_mov_b32_e32 v124, v0
	v_mov_b32_e32 v125, v0
	v_mov_b32_e32 v126, v0
	v_mov_b32_e32 v127, v0
	s_barrier
	s_mov_b32 s101, 0
	s_branch .LBB0_217
.Lph217_a:
	s_add_u32 s36, s34, 0xfffc0080
	s_addc_u32 s37, s35, -1
	s_cmp_eq_u32 s71, 12
	s_cselect_b32 s39, s7, s37
	s_cselect_b32 s38, s25, s36
	s_cselect_b32 s37, s23, s70
	s_cselect_b32 s36, s68, s69
	v_lshl_add_u64 v[150:151], s[34:35], 0, v[138:139]
	s_add_i32 m0, s31, 0xc000
	s_nop 0
	global_load_lds_dwordx4 v[150:151], off
	v_lshl_add_u64 v[150:151], s[34:35], 0, v[140:141]
	s_add_i32 m0, s31, 0xe000
	s_nop 0
	global_load_lds_dwordx4 v[150:151], off
	ds_read_b128 v[146:149], v155
	ds_read_b128 v[158:161], v155 offset:1024
	ds_read_b128 v[162:165], v155 offset:2048
	ds_read_b128 v[166:169], v155 offset:3072
	ds_read_b128 v[170:173], v156
	ds_read_b128 v[174:177], v156 offset:1024
	ds_read_b128 v[178:181], v156 offset:2048
	ds_read_b128 v[182:185], v156 offset:3072
	ds_read_b128 v[186:189], v157
	ds_read_b128 v[190:193], v157 offset:1024
	ds_read_b128 v[194:197], v157 offset:2048
	ds_read_b128 v[198:201], v157 offset:3072
	ds_read_b128 v[202:205], v157 offset:4096
	ds_read_b128 v[206:209], v157 offset:5120
	ds_read_b128 v[210:213], v157 offset:6144
	ds_read_b128 v[214:217], v157 offset:7168
	v_mov_b32_e32 v1, v0
	v_mov_b32_e32 v2, v0
	v_mov_b32_e32 v3, v0
	v_mov_b32_e32 v4, v0
	v_mov_b32_e32 v5, v0
	v_mov_b32_e32 v6, v0
	v_mov_b32_e32 v7, v0
	v_mov_b32_e32 v16, v0
	v_mov_b32_e32 v17, v0
	v_mov_b32_e32 v18, v0
	v_mov_b32_e32 v19, v0
	v_mov_b32_e32 v20, v0
	v_mov_b32_e32 v21, v0
	v_mov_b32_e32 v22, v0
	v_mov_b32_e32 v23, v0
	v_mov_b32_e32 v32, v0
	v_mov_b32_e32 v33, v0
	v_mov_b32_e32 v34, v0
	v_mov_b32_e32 v35, v0
	v_mov_b32_e32 v36, v0
	v_mov_b32_e32 v37, v0
	v_mov_b32_e32 v38, v0
	v_mov_b32_e32 v39, v0
	v_mov_b32_e32 v48, v0
	v_mov_b32_e32 v49, v0
	v_mov_b32_e32 v50, v0
	v_mov_b32_e32 v51, v0
	v_mov_b32_e32 v52, v0
	v_mov_b32_e32 v53, v0
	v_mov_b32_e32 v54, v0
	v_mov_b32_e32 v55, v0
	v_mov_b32_e32 v8, v0
	v_mov_b32_e32 v9, v0
	v_mov_b32_e32 v10, v0
	v_mov_b32_e32 v11, v0
	v_mov_b32_e32 v12, v0
	v_mov_b32_e32 v13, v0
	v_mov_b32_e32 v14, v0
	v_mov_b32_e32 v15, v0
	v_mov_b32_e32 v24, v0
	v_mov_b32_e32 v25, v0
	v_mov_b32_e32 v26, v0
	v_mov_b32_e32 v27, v0
	v_mov_b32_e32 v28, v0
	v_mov_b32_e32 v29, v0
	v_mov_b32_e32 v30, v0
	v_mov_b32_e32 v31, v0
	v_mov_b32_e32 v40, v0
	v_mov_b32_e32 v41, v0
	v_mov_b32_e32 v42, v0
	v_mov_b32_e32 v43, v0
	v_mov_b32_e32 v44, v0
	v_mov_b32_e32 v45, v0
	v_mov_b32_e32 v46, v0
	v_mov_b32_e32 v47, v0
	v_mov_b32_e32 v56, v0
	v_mov_b32_e32 v57, v0
	v_mov_b32_e32 v58, v0
	v_mov_b32_e32 v59, v0
	v_mov_b32_e32 v60, v0
	v_mov_b32_e32 v61, v0
	v_mov_b32_e32 v62, v0
	v_mov_b32_e32 v63, v0
	v_mov_b32_e32 v64, v0
	v_mov_b32_e32 v65, v0
	v_mov_b32_e32 v66, v0
	v_mov_b32_e32 v67, v0
	v_mov_b32_e32 v68, v0
	v_mov_b32_e32 v69, v0
	v_mov_b32_e32 v70, v0
	v_mov_b32_e32 v71, v0
	v_mov_b32_e32 v80, v0
	v_mov_b32_e32 v81, v0
	v_mov_b32_e32 v82, v0
	v_mov_b32_e32 v83, v0
	v_mov_b32_e32 v84, v0
	v_mov_b32_e32 v85, v0
	v_mov_b32_e32 v86, v0
	v_mov_b32_e32 v87, v0
	v_mov_b32_e32 v96, v0
	v_mov_b32_e32 v97, v0
	v_mov_b32_e32 v98, v0
	v_mov_b32_e32 v99, v0
	v_mov_b32_e32 v100, v0
	v_mov_b32_e32 v101, v0
	v_mov_b32_e32 v102, v0
	v_mov_b32_e32 v103, v0
	v_mov_b32_e32 v112, v0
	v_mov_b32_e32 v113, v0
	v_mov_b32_e32 v114, v0
	v_mov_b32_e32 v115, v0
	v_mov_b32_e32 v116, v0
	v_mov_b32_e32 v117, v0
	v_mov_b32_e32 v118, v0
	v_mov_b32_e32 v119, v0
	v_mov_b32_e32 v72, v0
	v_mov_b32_e32 v73, v0
	v_mov_b32_e32 v74, v0
	v_mov_b32_e32 v75, v0
	v_mov_b32_e32 v76, v0
	v_mov_b32_e32 v77, v0
	v_mov_b32_e32 v78, v0
	v_mov_b32_e32 v79, v0
	v_mov_b32_e32 v88, v0
	v_mov_b32_e32 v89, v0
	v_mov_b32_e32 v90, v0
	v_mov_b32_e32 v91, v0
	v_mov_b32_e32 v92, v0
	v_mov_b32_e32 v93, v0
	v_mov_b32_e32 v94, v0
	v_mov_b32_e32 v95, v0
	v_mov_b32_e32 v104, v0
	v_mov_b32_e32 v105, v0
	v_mov_b32_e32 v106, v0
	v_mov_b32_e32 v107, v0
	v_mov_b32_e32 v108, v0
	v_mov_b32_e32 v109, v0
	v_mov_b32_e32 v110, v0
	v_mov_b32_e32 v111, v0
	v_mov_b32_e32 v120, v0
	v_mov_b32_e32 v121, v0
	v_mov_b32_e32 v122, v0
	v_mov_b32_e32 v123, v0
	v_mov_b32_e32 v124, v0
	v_mov_b32_e32 v125, v0
	v_mov_b32_e32 v126, v0
	v_mov_b32_e32 v127, v0
	s_branch .Lph217_w

.Lph217_w:
	s_nop 0
	s_nop 0
	s_waitcnt vmcnt(8)
	s_waitcnt lgkmcnt(0)
	s_setprio 1
	s_barrier
	v_mfma_f32_16x16x32_bf16 v[124:127], v[146:149], v[186:189], v[124:127]
	v_mfma_f32_16x16x32_bf16 v[120:123], v[162:165], v[186:189], v[120:123]
	v_mfma_f32_16x16x32_bf16 v[108:111], v[146:149], v[194:197], v[108:111]
	v_mfma_f32_16x16x32_bf16 v[104:107], v[162:165], v[194:197], v[104:107]
	v_mfma_f32_16x16x32_bf16 v[92:95], v[146:149], v[202:205], v[92:95]
	v_mfma_f32_16x16x32_bf16 v[88:91], v[162:165], v[202:205], v[88:91]
	v_mfma_f32_16x16x32_bf16 v[76:79], v[146:149], v[210:213], v[76:79]
	v_mfma_f32_16x16x32_bf16 v[72:75], v[162:165], v[210:213], v[72:75]
	v_mfma_f32_16x16x32_bf16 v[124:127], v[158:161], v[190:193], v[124:127]
	v_mfma_f32_16x16x32_bf16 v[120:123], v[166:169], v[190:193], v[120:123]
	v_mfma_f32_16x16x32_bf16 v[108:111], v[158:161], v[198:201], v[108:111]
	v_mfma_f32_16x16x32_bf16 v[104:107], v[166:169], v[198:201], v[104:107]
	v_mfma_f32_16x16x32_bf16 v[92:95], v[158:161], v[206:209], v[92:95]
	v_mfma_f32_16x16x32_bf16 v[88:91], v[166:169], v[206:209], v[88:91]
	v_mfma_f32_16x16x32_bf16 v[76:79], v[158:161], v[214:217], v[76:79]
	v_mfma_f32_16x16x32_bf16 v[72:75], v[166:169], v[214:217], v[72:75]
	s_setprio 0
	s_setprio 1
	v_mfma_f32_16x16x32_bf16 v[116:119], v[170:173], v[186:189], v[116:119]
	v_mfma_f32_16x16x32_bf16 v[112:115], v[178:181], v[186:189], v[112:115]
	v_mfma_f32_16x16x32_bf16 v[100:103], v[170:173], v[194:197], v[100:103]
	v_mfma_f32_16x16x32_bf16 v[96:99], v[178:181], v[194:197], v[96:99]
	v_mfma_f32_16x16x32_bf16 v[84:87], v[170:173], v[202:205], v[84:87]
	v_mfma_f32_16x16x32_bf16 v[80:83], v[178:181], v[202:205], v[80:83]
	v_mfma_f32_16x16x32_bf16 v[68:71], v[170:173], v[210:213], v[68:71]
	v_mfma_f32_16x16x32_bf16 v[64:67], v[178:181], v[210:213], v[64:67]
	v_mfma_f32_16x16x32_bf16 v[116:119], v[174:177], v[190:193], v[116:119]
	v_mfma_f32_16x16x32_bf16 v[112:115], v[182:185], v[190:193], v[112:115]
	v_mfma_f32_16x16x32_bf16 v[100:103], v[174:177], v[198:201], v[100:103]
	v_mfma_f32_16x16x32_bf16 v[96:99], v[182:185], v[198:201], v[96:99]
	v_mfma_f32_16x16x32_bf16 v[84:87], v[174:177], v[206:209], v[84:87]
	v_mfma_f32_16x16x32_bf16 v[80:83], v[182:185], v[206:209], v[80:83]
	v_mfma_f32_16x16x32_bf16 v[68:71], v[174:177], v[214:217], v[68:71]
	v_mfma_f32_16x16x32_bf16 v[64:67], v[182:185], v[214:217], v[64:67]
	s_barrier
	s_setprio 0
	s_add_i32 s72, s65, s43
	v_lshl_add_u64 v[150:151], s[36:37], 0, v[130:131]
	s_mov_b32 m0, s72
	s_nop 0
	global_load_lds_dwordx4 v[150:151], off
	s_add_i32 m0, s72, 0x2000
	s_add_u32 s72, s36, 0x40000
	v_lshl_add_u64 v[218:219], s[36:37], 0, v[134:135]
	s_addc_u32 s73, s37, 0
	s_add_i32 s74, s67, s43
	global_load_lds_dwordx4 v[218:219], off
	v_lshl_add_u64 v[220:221], s[72:73], 0, v[130:131]
	s_mov_b32 m0, s74
	v_lshl_add_u64 v[222:223], s[38:39], 0, v[132:133]
	global_load_lds_dwordx4 v[220:221], off
	v_lshl_add_u64 v[220:221], s[72:73], 0, v[134:135]
	s_add_i32 m0, s74, 0x2000
	s_nop 0
	global_load_lds_dwordx4 v[220:221], off
	v_lshl_add_u64 v[220:221], s[38:39], 0, v[128:129]
	s_mov_b32 m0, s31
	s_nop 0
	global_load_lds_dwordx4 v[220:221], off
	s_mov_b32 m0, s46
	s_nop 0
	global_load_lds_dwordx4 v[222:223], off
	ds_read_b128 v[186:189], v157 offset:16384
	ds_read_b128 v[190:193], v157 offset:17408
	ds_read_b128 v[194:197], v157 offset:18432
	ds_read_b128 v[198:201], v157 offset:19456
	ds_read_b128 v[202:205], v157 offset:20480
	ds_read_b128 v[206:209], v157 offset:21504
	ds_read_b128 v[210:213], v157 offset:22528
	ds_read_b128 v[214:217], v157 offset:23552
	s_nop 0
	s_waitcnt vmcnt(8)
	s_waitcnt lgkmcnt(0)
	s_setprio 1
	s_barrier
	v_mfma_f32_16x16x32_bf16 v[60:63], v[146:149], v[186:189], v[60:63]
	v_mfma_f32_16x16x32_bf16 v[56:59], v[162:165], v[186:189], v[56:59]
	v_mfma_f32_16x16x32_bf16 v[44:47], v[146:149], v[194:197], v[44:47]
	v_mfma_f32_16x16x32_bf16 v[40:43], v[162:165], v[194:197], v[40:43]
	v_mfma_f32_16x16x32_bf16 v[28:31], v[146:149], v[202:205], v[28:31]
	v_mfma_f32_16x16x32_bf16 v[24:27], v[162:165], v[202:205], v[24:27]
	v_mfma_f32_16x16x32_bf16 v[12:15], v[146:149], v[210:213], v[12:15]
	v_mfma_f32_16x16x32_bf16 v[8:11], v[162:165], v[210:213], v[8:11]
	v_mfma_f32_16x16x32_bf16 v[60:63], v[158:161], v[190:193], v[60:63]
	v_mfma_f32_16x16x32_bf16 v[56:59], v[166:169], v[190:193], v[56:59]
	v_mfma_f32_16x16x32_bf16 v[44:47], v[158:161], v[198:201], v[44:47]
	v_mfma_f32_16x16x32_bf16 v[40:43], v[166:169], v[198:201], v[40:43]
	v_mfma_f32_16x16x32_bf16 v[28:31], v[158:161], v[206:209], v[28:31]
	v_mfma_f32_16x16x32_bf16 v[24:27], v[166:169], v[206:209], v[24:27]
	v_mfma_f32_16x16x32_bf16 v[12:15], v[158:161], v[214:217], v[12:15]
	v_mfma_f32_16x16x32_bf16 v[8:11], v[166:169], v[214:217], v[8:11]
	s_setprio 0
	s_setprio 1
	v_mfma_f32_16x16x32_bf16 v[52:55], v[170:173], v[186:189], v[52:55]
	v_mfma_f32_16x16x32_bf16 v[48:51], v[178:181], v[186:189], v[48:51]
	v_mfma_f32_16x16x32_bf16 v[36:39], v[170:173], v[194:197], v[36:39]
	v_mfma_f32_16x16x32_bf16 v[32:35], v[178:181], v[194:197], v[32:35]
	v_mfma_f32_16x16x32_bf16 v[20:23], v[170:173], v[202:205], v[20:23]
	v_mfma_f32_16x16x32_bf16 v[16:19], v[178:181], v[202:205], v[16:19]
	v_mfma_f32_16x16x32_bf16 v[4:7], v[170:173], v[210:213], v[4:7]
	v_mfma_f32_16x16x32_bf16 v[0:3], v[178:181], v[210:213], v[0:3]
	v_mfma_f32_16x16x32_bf16 v[52:55], v[174:177], v[190:193], v[52:55]
	v_mfma_f32_16x16x32_bf16 v[48:51], v[182:185], v[190:193], v[48:51]
	v_mfma_f32_16x16x32_bf16 v[36:39], v[174:177], v[198:201], v[36:39]
	v_mfma_f32_16x16x32_bf16 v[32:35], v[182:185], v[198:201], v[32:35]
	v_mfma_f32_16x16x32_bf16 v[20:23], v[174:177], v[206:209], v[20:23]
	v_mfma_f32_16x16x32_bf16 v[16:19], v[182:185], v[206:209], v[16:19]
	v_mfma_f32_16x16x32_bf16 v[4:7], v[174:177], v[214:217], v[4:7]
	v_mfma_f32_16x16x32_bf16 v[0:3], v[182:185], v[214:217], v[0:3]
	s_barrier
	s_setprio 0
	s_add_i32 s72, 0, 0x18000
	s_add_i32 s73, 0, 0x1c000
	s_add_u32 s38, s38, 0x40000
	s_addc_u32 s39, s39, 0
	s_mov_b32 m0, s47
	v_lshl_add_u64 v[224:225], s[38:39], 0, v[128:129]
	global_load_lds_dwordx4 v[224:225], off
	v_lshl_add_u64 v[224:225], s[38:39], 0, v[132:133]
	s_mov_b32 m0, s48
	s_nop 0
	global_load_lds_dwordx4 v[224:225], off
	v_add_u32_e32 v136, s72, v153
	ds_read_b128 v[146:149], v136
	ds_read_b128 v[158:161], v136 offset:1024
	ds_read_b128 v[162:165], v136 offset:2048
	ds_read_b128 v[166:169], v136 offset:3072
	v_add_u32_e32 v136, s73, v153
	ds_read_b128 v[170:173], v136
	ds_read_b128 v[174:177], v136 offset:1024
	ds_read_b128 v[178:181], v136 offset:2048
	ds_read_b128 v[182:185], v136 offset:3072
	ds_read_b128 v[186:189], v157 offset:32768
	ds_read_b128 v[190:193], v157 offset:33792
	ds_read_b128 v[194:197], v157 offset:34816
	ds_read_b128 v[198:201], v157 offset:35840
	ds_read_b128 v[202:205], v157 offset:36864
	ds_read_b128 v[206:209], v157 offset:37888
	ds_read_b128 v[210:213], v157 offset:38912
	ds_read_b128 v[214:217], v157 offset:39936
	s_waitcnt vmcnt(8)
	s_waitcnt lgkmcnt(0)
	s_setprio 1
	s_barrier
	v_mfma_f32_16x16x32_bf16 v[124:127], v[146:149], v[186:189], v[124:127]
	v_mfma_f32_16x16x32_bf16 v[120:123], v[162:165], v[186:189], v[120:123]
	v_mfma_f32_16x16x32_bf16 v[108:111], v[146:149], v[194:197], v[108:111]
	v_mfma_f32_16x16x32_bf16 v[104:107], v[162:165], v[194:197], v[104:107]
	v_mfma_f32_16x16x32_bf16 v[92:95], v[146:149], v[202:205], v[92:95]
	v_mfma_f32_16x16x32_bf16 v[88:91], v[162:165], v[202:205], v[88:91]
	v_mfma_f32_16x16x32_bf16 v[76:79], v[146:149], v[210:213], v[76:79]
	v_mfma_f32_16x16x32_bf16 v[72:75], v[162:165], v[210:213], v[72:75]
	v_mfma_f32_16x16x32_bf16 v[124:127], v[158:161], v[190:193], v[124:127]
	v_mfma_f32_16x16x32_bf16 v[120:123], v[166:169], v[190:193], v[120:123]
	v_mfma_f32_16x16x32_bf16 v[108:111], v[158:161], v[198:201], v[108:111]
	v_mfma_f32_16x16x32_bf16 v[104:107], v[166:169], v[198:201], v[104:107]
	v_mfma_f32_16x16x32_bf16 v[92:95], v[158:161], v[206:209], v[92:95]
	v_mfma_f32_16x16x32_bf16 v[88:91], v[166:169], v[206:209], v[88:91]
	v_mfma_f32_16x16x32_bf16 v[76:79], v[158:161], v[214:217], v[76:79]
	v_mfma_f32_16x16x32_bf16 v[72:75], v[166:169], v[214:217], v[72:75]
	s_setprio 0
	s_setprio 1
	v_mfma_f32_16x16x32_bf16 v[116:119], v[170:173], v[186:189], v[116:119]
	v_mfma_f32_16x16x32_bf16 v[112:115], v[178:181], v[186:189], v[112:115]
	v_mfma_f32_16x16x32_bf16 v[100:103], v[170:173], v[194:197], v[100:103]
	v_mfma_f32_16x16x32_bf16 v[96:99], v[178:181], v[194:197], v[96:99]
	v_mfma_f32_16x16x32_bf16 v[84:87], v[170:173], v[202:205], v[84:87]
	v_mfma_f32_16x16x32_bf16 v[80:83], v[178:181], v[202:205], v[80:83]
	v_mfma_f32_16x16x32_bf16 v[68:71], v[170:173], v[210:213], v[68:71]
	v_mfma_f32_16x16x32_bf16 v[64:67], v[178:181], v[210:213], v[64:67]
	v_mfma_f32_16x16x32_bf16 v[116:119], v[174:177], v[190:193], v[116:119]
	v_mfma_f32_16x16x32_bf16 v[112:115], v[182:185], v[190:193], v[112:115]
	v_mfma_f32_16x16x32_bf16 v[100:103], v[174:177], v[198:201], v[100:103]
	v_mfma_f32_16x16x32_bf16 v[96:99], v[182:185], v[198:201], v[96:99]
	v_mfma_f32_16x16x32_bf16 v[84:87], v[174:177], v[206:209], v[84:87]
	v_mfma_f32_16x16x32_bf16 v[80:83], v[182:185], v[206:209], v[80:83]
	v_mfma_f32_16x16x32_bf16 v[68:71], v[174:177], v[214:217], v[68:71]
	v_mfma_f32_16x16x32_bf16 v[64:67], v[182:185], v[214:217], v[64:67]
	s_barrier
	s_setprio 0
	s_add_i32 s38, s72, s43
	v_lshl_add_u64 v[150:151], v[150:151], 0, s[12:13]
	s_mov_b32 m0, s38
	s_nop 0
	global_load_lds_dwordx4 v[150:151], off
	s_add_i32 m0, s38, 0x2000
	s_add_u32 s36, s36, 0x40080
	v_lshl_add_u64 v[150:151], v[218:219], 0, s[12:13]
	s_addc_u32 s37, s37, 0
	s_add_i32 s38, s73, s43
	global_load_lds_dwordx4 v[150:151], off
	v_lshl_add_u64 v[150:151], s[36:37], 0, v[130:131]
	s_mov_b32 m0, s38
	s_nop 0
	global_load_lds_dwordx4 v[150:151], off
	v_lshl_add_u64 v[150:151], s[36:37], 0, v[134:135]
	s_add_i32 m0, s38, 0x2000
	s_nop 0
	global_load_lds_dwordx4 v[150:151], off
	v_lshl_add_u64 v[150:151], v[220:221], 0, s[12:13]
	s_mov_b32 m0, s60
	s_nop 0
	global_load_lds_dwordx4 v[150:151], off
	v_lshl_add_u64 v[150:151], v[222:223], 0, s[12:13]
	s_mov_b32 m0, s61
	s_nop 0
	global_load_lds_dwordx4 v[150:151], off
	ds_read_b128 v[186:189], v157 offset:49152
	ds_read_b128 v[190:193], v157 offset:50176
	ds_read_b128 v[194:197], v157 offset:51200
	ds_read_b128 v[198:201], v157 offset:52224
	ds_read_b128 v[202:205], v157 offset:53248
	ds_read_b128 v[206:209], v157 offset:54272
	ds_read_b128 v[210:213], v157 offset:55296
	ds_read_b128 v[214:217], v157 offset:56320
	s_waitcnt vmcnt(8)
	s_waitcnt lgkmcnt(0)
	s_setprio 1
	s_barrier
	v_mfma_f32_16x16x32_bf16 v[60:63], v[146:149], v[186:189], v[60:63]
	v_mfma_f32_16x16x32_bf16 v[56:59], v[162:165], v[186:189], v[56:59]
	v_mfma_f32_16x16x32_bf16 v[44:47], v[146:149], v[194:197], v[44:47]
	v_mfma_f32_16x16x32_bf16 v[40:43], v[162:165], v[194:197], v[40:43]
	v_mfma_f32_16x16x32_bf16 v[28:31], v[146:149], v[202:205], v[28:31]
	v_mfma_f32_16x16x32_bf16 v[24:27], v[162:165], v[202:205], v[24:27]
	v_mfma_f32_16x16x32_bf16 v[12:15], v[146:149], v[210:213], v[12:15]
	v_mfma_f32_16x16x32_bf16 v[8:11], v[162:165], v[210:213], v[8:11]
	v_mfma_f32_16x16x32_bf16 v[60:63], v[158:161], v[190:193], v[60:63]
	v_mfma_f32_16x16x32_bf16 v[56:59], v[166:169], v[190:193], v[56:59]
	v_mfma_f32_16x16x32_bf16 v[44:47], v[158:161], v[198:201], v[44:47]
	v_mfma_f32_16x16x32_bf16 v[40:43], v[166:169], v[198:201], v[40:43]
	v_mfma_f32_16x16x32_bf16 v[28:31], v[158:161], v[206:209], v[28:31]
	v_mfma_f32_16x16x32_bf16 v[24:27], v[166:169], v[206:209], v[24:27]
	v_mfma_f32_16x16x32_bf16 v[12:15], v[158:161], v[214:217], v[12:15]
	v_mfma_f32_16x16x32_bf16 v[8:11], v[166:169], v[214:217], v[8:11]
	s_setprio 0
	s_setprio 1
	v_mfma_f32_16x16x32_bf16 v[52:55], v[170:173], v[186:189], v[52:55]
	v_mfma_f32_16x16x32_bf16 v[48:51], v[178:181], v[186:189], v[48:51]
	v_mfma_f32_16x16x32_bf16 v[36:39], v[170:173], v[194:197], v[36:39]
	v_mfma_f32_16x16x32_bf16 v[32:35], v[178:181], v[194:197], v[32:35]
	v_mfma_f32_16x16x32_bf16 v[20:23], v[170:173], v[202:205], v[20:23]
	v_mfma_f32_16x16x32_bf16 v[16:19], v[178:181], v[202:205], v[16:19]
	v_mfma_f32_16x16x32_bf16 v[4:7], v[170:173], v[210:213], v[4:7]
	v_mfma_f32_16x16x32_bf16 v[0:3], v[178:181], v[210:213], v[0:3]
	v_mfma_f32_16x16x32_bf16 v[52:55], v[174:177], v[190:193], v[52:55]
	v_mfma_f32_16x16x32_bf16 v[48:51], v[182:185], v[190:193], v[48:51]
	v_mfma_f32_16x16x32_bf16 v[36:39], v[174:177], v[198:201], v[36:39]
	v_mfma_f32_16x16x32_bf16 v[32:35], v[182:185], v[198:201], v[32:35]
	v_mfma_f32_16x16x32_bf16 v[20:23], v[174:177], v[206:209], v[20:23]
	v_mfma_f32_16x16x32_bf16 v[16:19], v[182:185], v[206:209], v[16:19]
	v_mfma_f32_16x16x32_bf16 v[4:7], v[174:177], v[214:217], v[4:7]
	v_mfma_f32_16x16x32_bf16 v[0:3], v[182:185], v[214:217], v[0:3]
	s_barrier
	s_setprio 0
	s_add_i32 s71, s71, 2
	s_add_u32 s34, s34, 0x100
	s_addc_u32 s35, s35, 0
	s_add_u32 s69, s69, 0x100
	s_addc_u32 s70, s70, 0
	s_cmp_gt_u32 s71, 13
	s_cbranch_scc0 .LBB0_217
	s_and_b64 vcc, exec, s[14:15]
	s_cbranch_vccz .LBB0_220
	s_barrier

.LBB0_252:
	v_lshl_add_u64 v[8:9], v[16:17], 0, s[20:21]
	s_andn2_b64 vcc, exec, s[4:5]
	s_mov_b64 s[4:5], -1
	v_cvt_pk_bf16_f32 v4, v4, v5
	v_cvt_pk_bf16_f32 v5, v6, v7
	v_cvt_pk_bf16_f32 v6, v0, v1
	v_cvt_pk_bf16_f32 v7, v2, v3
	global_store_dwordx4 v[8:9], v[4:7], off offset:256
	s_cbranch_vccnz .LBB0_209
	s_mov_b32 s101, 0
	s_andn2_b64 vcc, exec, s[10:11]
	s_cbranch_vccnz .LBB0_208
	s_mov_b32 s101, 1
	s_branch .LBB0_208

.LBB0_461:
	s_lshl_b32 s47, s6, 6
	s_lshl_b32 s17, s6, 13
	s_lshl_b32 s6, s7, 5
	s_mov_b64 s[14:15], 0x80
	s_and_b32 s48, s6, 0x60
	s_add_i32 m0, s29, 0x18000
	v_lshl_add_u64 v[6:7], v[6:7], 0, s[14:15]
	s_lshl_b32 s18, s48, 7
	s_waitcnt vmcnt(2)
	s_barrier
	global_load_lds_dwordx4 v[6:7], off
	v_lshl_add_u64 v[4:5], v[4:5], 0, s[14:15]
	s_add_i32 m0, s29, 0x1a000
	s_add_i32 s49, s29, 0x8000
	s_add_i32 s50, s29, 0xa000
	global_load_lds_dwordx4 v[4:5], off
	v_lshl_add_u64 v[0:1], v[0:1], 0, s[14:15]
	s_mov_b32 m0, s49
	s_add_u32 s6, s34, 0x40080
	global_load_lds_dwordx4 v[0:1], off
	v_lshl_add_u64 v[0:1], v[2:3], 0, s[14:15]
	s_mov_b32 m0, s50
	s_addc_u32 s7, s35, 0
	global_load_lds_dwordx4 v[0:1], off
	s_add_i32 m0, s29, 0x1c000
	v_lshl_add_u64 v[0:1], s[6:7], 0, v[178:179]
	global_load_lds_dwordx4 v[0:1], off
	v_lshl_add_u64 v[0:1], s[6:7], 0, v[182:183]
	s_add_i32 m0, s29, 0x1e000
	v_bfe_u32 v205, v8, 4, 2
	global_load_lds_dwordx4 v[0:1], off
	v_and_b32_e32 v204, 15, v8
	v_lshlrev_b32_e32 v0, 4, v205
	v_lshlrev_b32_e32 v1, 2, v8
	v_lshl_or_b32 v0, v204, 6, v0
	v_and_b32_e32 v1, 32, v1
	v_bitop3_b32 v2, v0, s17, v1 bitop3:0xde
	v_bitop3_b32 v206, v0, s18, v1 bitop3:0xde
	v_lshlrev_b32_e32 v0, 14, v9
	v_and_b32_e32 v0, 0xffff8000, v0
	v_lshl_add_u32 v0, v10, 11, v0
	v_and_b32_e32 v1, 1, v9
	v_lshl_or_b32 v0, v1, 6, v0
	v_lshl_add_u32 v184, v11, 1, v0
	v_lshlrev_b32_e32 v0, 14, v12
	v_and_b32_e32 v0, 0xffff8000, v0
	s_waitcnt vmcnt(6)
	s_cmpk_lt_u32 s16, 0x100
	v_lshl_add_u32 v0, v13, 11, v0
	v_and_b32_e32 v1, 1, v12
	s_cselect_b64 s[16:17], -1, 0
	v_lshl_or_b32 v0, v1, 6, v0
	s_add_i32 s62, 0, 0x10000
	s_add_i32 s63, 0, 0x14000
	s_ashr_i32 s51, s52, 31
	s_mov_b32 s60, s52
	s_ashr_i32 s61, s33, 31
	v_mov_b32_e32 v185, v179
	v_lshl_add_u32 v186, v14, 1, v0
	v_mov_b32_e32 v187, v179
	v_mov_b64_e32 v[188:189], 0x200
	v_mov_b64_e32 v[190:191], 0x1ff
	v_add_u32_e32 v207, s62, v206
	v_add_u32_e32 v208, s63, v206
	v_add_u32_e32 v209, 0, v2
	s_barrier
	s_mov_b32 s101, 0
	s_branch .LBB0_464

.LBB0_470:
	s_ashr_i32 s21, s20, 31
	s_lshl_b64 s[22:23], s[20:21], 19
	s_add_u32 s22, s4, s22
	s_addc_u32 s23, s5, s23
	s_and_b64 s[24:25], s[6:7], exec
	s_cselect_b32 s21, s23, s31
	s_cselect_b32 s27, s22, s30
	s_ashr_i32 s19, s18, 31
	s_lshl_b64 s[24:25], s[18:19], 19
	s_add_u32 s24, s38, s24
	s_addc_u32 s25, s39, s25
	s_and_b64 s[36:37], s[6:7], exec
	s_cselect_b32 s19, s25, s35
	s_cselect_b32 s64, s24, s34
	s_add_u32 s30, s30, 0x40080
	s_addc_u32 s31, s31, 0
	s_add_u32 s65, s34, 0x100
	v_mov_b32_e32 v0, 0
	s_addc_u32 s68, s35, 0
	s_mov_b32 s69, -2
	s_waitcnt vmcnt(0)
	s_cmp_lg_u32 s101, 0
	s_cbranch_scc0 .Lph471_a
	v_mov_b32_e32 v1, v0
	v_mov_b32_e32 v2, v0
	v_mov_b32_e32 v3, v0
	v_mov_b32_e32 v4, v0
	v_mov_b32_e32 v5, v0
	v_mov_b32_e32 v6, v0
	v_mov_b32_e32 v7, v0
	v_mov_b32_e32 v16, v0
	v_mov_b32_e32 v17, v0
	v_mov_b32_e32 v18, v0
	v_mov_b32_e32 v19, v0
	v_mov_b32_e32 v20, v0
	v_mov_b32_e32 v21, v0
	v_mov_b32_e32 v22, v0
	v_mov_b32_e32 v23, v0
	v_mov_b32_e32 v32, v0
	v_mov_b32_e32 v33, v0
	v_mov_b32_e32 v34, v0
	v_mov_b32_e32 v35, v0
	v_mov_b32_e32 v36, v0
	v_mov_b32_e32 v37, v0
	v_mov_b32_e32 v38, v0
	v_mov_b32_e32 v39, v0
	v_mov_b32_e32 v48, v0
	v_mov_b32_e32 v49, v0
	v_mov_b32_e32 v50, v0
	v_mov_b32_e32 v51, v0
	v_mov_b32_e32 v52, v0
	v_mov_b32_e32 v53, v0
	v_mov_b32_e32 v54, v0
	v_mov_b32_e32 v55, v0
	v_mov_b32_e32 v8, v0
	v_mov_b32_e32 v9, v0
	v_mov_b32_e32 v10, v0
	v_mov_b32_e32 v11, v0
	v_mov_b32_e32 v12, v0
	v_mov_b32_e32 v13, v0
	v_mov_b32_e32 v14, v0
	v_mov_b32_e32 v15, v0
	v_mov_b32_e32 v24, v0
	v_mov_b32_e32 v25, v0
	v_mov_b32_e32 v26, v0
	v_mov_b32_e32 v27, v0
	v_mov_b32_e32 v28, v0
	v_mov_b32_e32 v29, v0
	v_mov_b32_e32 v30, v0
	v_mov_b32_e32 v31, v0
	v_mov_b32_e32 v40, v0
	v_mov_b32_e32 v41, v0
	v_mov_b32_e32 v42, v0
	v_mov_b32_e32 v43, v0
	v_mov_b32_e32 v44, v0
	v_mov_b32_e32 v45, v0
	v_mov_b32_e32 v46, v0
	v_mov_b32_e32 v47, v0
	v_mov_b32_e32 v56, v0
	v_mov_b32_e32 v57, v0
	v_mov_b32_e32 v58, v0
	v_mov_b32_e32 v59, v0
	v_mov_b32_e32 v60, v0
	v_mov_b32_e32 v61, v0
	v_mov_b32_e32 v62, v0
	v_mov_b32_e32 v63, v0
	v_mov_b32_e32 v64, v0
	v_mov_b32_e32 v65, v0
	v_mov_b32_e32 v66, v0
	v_mov_b32_e32 v67, v0
	v_mov_b32_e32 v68, v0
	v_mov_b32_e32 v69, v0
	v_mov_b32_e32 v70, v0
	v_mov_b32_e32 v71, v0
	v_mov_b32_e32 v80, v0
	v_mov_b32_e32 v81, v0
	v_mov_b32_e32 v82, v0
	v_mov_b32_e32 v83, v0
	v_mov_b32_e32 v84, v0
	v_mov_b32_e32 v85, v0
	v_mov_b32_e32 v86, v0
	v_mov_b32_e32 v87, v0
	v_mov_b32_e32 v96, v0
	v_mov_b32_e32 v97, v0
	v_mov_b32_e32 v98, v0
	v_mov_b32_e32 v99, v0
	v_mov_b32_e32 v100, v0
	v_mov_b32_e32 v101, v0
	v_mov_b32_e32 v102, v0
	v_mov_b32_e32 v103, v0
	v_mov_b32_e32 v112, v0
	v_mov_b32_e32 v113, v0
	v_mov_b32_e32 v114, v0
	v_mov_b32_e32 v115, v0
	v_mov_b32_e32 v116, v0
	v_mov_b32_e32 v117, v0
	v_mov_b32_e32 v118, v0
	v_mov_b32_e32 v119, v0
	v_mov_b32_e32 v72, v0
	v_mov_b32_e32 v73, v0
	v_mov_b32_e32 v74, v0
	v_mov_b32_e32 v75, v0
	v_mov_b32_e32 v76, v0
	v_mov_b32_e32 v77, v0
	v_mov_b32_e32 v78, v0
	v_mov_b32_e32 v79, v0
	v_mov_b32_e32 v88, v0
	v_mov_b32_e32 v89, v0
	v_mov_b32_e32 v90, v0
	v_mov_b32_e32 v91, v0
	v_mov_b32_e32 v92, v0
	v_mov_b32_e32 v93, v0
	v_mov_b32_e32 v94, v0
	v_mov_b32_e32 v95, v0
	v_mov_b32_e32 v104, v0
	v_mov_b32_e32 v105, v0
	v_mov_b32_e32 v106, v0
	v_mov_b32_e32 v107, v0
	v_mov_b32_e32 v108, v0
	v_mov_b32_e32 v109, v0
	v_mov_b32_e32 v110, v0
	v_mov_b32_e32 v111, v0
	v_mov_b32_e32 v120, v0
	v_mov_b32_e32 v121, v0
	v_mov_b32_e32 v122, v0
	v_mov_b32_e32 v123, v0
	v_mov_b32_e32 v124, v0
	v_mov_b32_e32 v125, v0
	v_mov_b32_e32 v126, v0
	v_mov_b32_e32 v127, v0
	s_barrier
	s_mov_b32 s101, 0
	s_branch .LBB0_471
.Lph471_a:
	s_add_u32 s34, s30, 0xfffc0080
	s_addc_u32 s35, s31, -1
	s_cmp_eq_u32 s69, 12
	s_cselect_b32 s37, s21, s35
	s_cselect_b32 s36, s27, s34
	s_cselect_b32 s35, s19, s68
	s_cselect_b32 s34, s64, s65
	v_lshl_add_u64 v[214:215], s[30:31], 0, v[184:185]
	s_add_i32 m0, s29, 0xc000
	s_nop 0
	global_load_lds_dwordx4 v[214:215], off
	v_lshl_add_u64 v[214:215], s[30:31], 0, v[186:187]
	s_add_i32 m0, s29, 0xe000
	s_nop 0
	global_load_lds_dwordx4 v[214:215], off
	ds_read_b128 v[128:131], v207
	ds_read_b128 v[132:135], v207 offset:1024
	ds_read_b128 v[136:139], v207 offset:2048
	ds_read_b128 v[140:143], v207 offset:3072
	ds_read_b128 v[144:147], v208
	ds_read_b128 v[148:151], v208 offset:1024
	ds_read_b128 v[152:155], v208 offset:2048
	ds_read_b128 v[156:159], v208 offset:3072
	ds_read_b128 v[160:163], v209
	ds_read_b128 v[164:167], v209 offset:1024
	ds_read_b128 v[168:171], v209 offset:2048
	ds_read_b128 v[172:175], v209 offset:3072
	ds_read_b128 v[192:195], v209 offset:4096
	ds_read_b128 v[196:199], v209 offset:5120
	ds_read_b128 v[200:203], v209 offset:6144
	ds_read_b128 v[210:213], v209 offset:7168
	v_mov_b32_e32 v1, v0
	v_mov_b32_e32 v2, v0
	v_mov_b32_e32 v3, v0
	v_mov_b32_e32 v4, v0
	v_mov_b32_e32 v5, v0
	v_mov_b32_e32 v6, v0
	v_mov_b32_e32 v7, v0
	v_mov_b32_e32 v16, v0
	v_mov_b32_e32 v17, v0
	v_mov_b32_e32 v18, v0
	v_mov_b32_e32 v19, v0
	v_mov_b32_e32 v20, v0
	v_mov_b32_e32 v21, v0
	v_mov_b32_e32 v22, v0
	v_mov_b32_e32 v23, v0
	v_mov_b32_e32 v32, v0
	v_mov_b32_e32 v33, v0
	v_mov_b32_e32 v34, v0
	v_mov_b32_e32 v35, v0
	v_mov_b32_e32 v36, v0
	v_mov_b32_e32 v37, v0
	v_mov_b32_e32 v38, v0
	v_mov_b32_e32 v39, v0
	v_mov_b32_e32 v48, v0
	v_mov_b32_e32 v49, v0
	v_mov_b32_e32 v50, v0
	v_mov_b32_e32 v51, v0
	v_mov_b32_e32 v52, v0
	v_mov_b32_e32 v53, v0
	v_mov_b32_e32 v54, v0
	v_mov_b32_e32 v55, v0
	v_mov_b32_e32 v8, v0
	v_mov_b32_e32 v9, v0
	v_mov_b32_e32 v10, v0
	v_mov_b32_e32 v11, v0
	v_mov_b32_e32 v12, v0
	v_mov_b32_e32 v13, v0
	v_mov_b32_e32 v14, v0
	v_mov_b32_e32 v15, v0
	v_mov_b32_e32 v24, v0
	v_mov_b32_e32 v25, v0
	v_mov_b32_e32 v26, v0
	v_mov_b32_e32 v27, v0
	v_mov_b32_e32 v28, v0
	v_mov_b32_e32 v29, v0
	v_mov_b32_e32 v30, v0
	v_mov_b32_e32 v31, v0
	v_mov_b32_e32 v40, v0
	v_mov_b32_e32 v41, v0
	v_mov_b32_e32 v42, v0
	v_mov_b32_e32 v43, v0
	v_mov_b32_e32 v44, v0
	v_mov_b32_e32 v45, v0
	v_mov_b32_e32 v46, v0
	v_mov_b32_e32 v47, v0
	v_mov_b32_e32 v56, v0
	v_mov_b32_e32 v57, v0
	v_mov_b32_e32 v58, v0
	v_mov_b32_e32 v59, v0
	v_mov_b32_e32 v60, v0
	v_mov_b32_e32 v61, v0
	v_mov_b32_e32 v62, v0
	v_mov_b32_e32 v63, v0
	v_mov_b32_e32 v64, v0
	v_mov_b32_e32 v65, v0
	v_mov_b32_e32 v66, v0
	v_mov_b32_e32 v67, v0
	v_mov_b32_e32 v68, v0
	v_mov_b32_e32 v69, v0
	v_mov_b32_e32 v70, v0
	v_mov_b32_e32 v71, v0
	v_mov_b32_e32 v80, v0
	v_mov_b32_e32 v81, v0
	v_mov_b32_e32 v82, v0
	v_mov_b32_e32 v83, v0
	v_mov_b32_e32 v84, v0
	v_mov_b32_e32 v85, v0
	v_mov_b32_e32 v86, v0
	v_mov_b32_e32 v87, v0
	v_mov_b32_e32 v96, v0
	v_mov_b32_e32 v97, v0
	v_mov_b32_e32 v98, v0
	v_mov_b32_e32 v99, v0
	v_mov_b32_e32 v100, v0
	v_mov_b32_e32 v101, v0
	v_mov_b32_e32 v102, v0
	v_mov_b32_e32 v103, v0
	v_mov_b32_e32 v112, v0
	v_mov_b32_e32 v113, v0
	v_mov_b32_e32 v114, v0
	v_mov_b32_e32 v115, v0
	v_mov_b32_e32 v116, v0
	v_mov_b32_e32 v117, v0
	v_mov_b32_e32 v118, v0
	v_mov_b32_e32 v119, v0
	v_mov_b32_e32 v72, v0
	v_mov_b32_e32 v73, v0
	v_mov_b32_e32 v74, v0
	v_mov_b32_e32 v75, v0
	v_mov_b32_e32 v76, v0
	v_mov_b32_e32 v77, v0
	v_mov_b32_e32 v78, v0
	v_mov_b32_e32 v79, v0
	v_mov_b32_e32 v88, v0
	v_mov_b32_e32 v89, v0
	v_mov_b32_e32 v90, v0
	v_mov_b32_e32 v91, v0
	v_mov_b32_e32 v92, v0
	v_mov_b32_e32 v93, v0
	v_mov_b32_e32 v94, v0
	v_mov_b32_e32 v95, v0
	v_mov_b32_e32 v104, v0
	v_mov_b32_e32 v105, v0
	v_mov_b32_e32 v106, v0
	v_mov_b32_e32 v107, v0
	v_mov_b32_e32 v108, v0
	v_mov_b32_e32 v109, v0
	v_mov_b32_e32 v110, v0
	v_mov_b32_e32 v111, v0
	v_mov_b32_e32 v120, v0
	v_mov_b32_e32 v121, v0
	v_mov_b32_e32 v122, v0
	v_mov_b32_e32 v123, v0
	v_mov_b32_e32 v124, v0
	v_mov_b32_e32 v125, v0
	v_mov_b32_e32 v126, v0
	v_mov_b32_e32 v127, v0
	s_branch .Lph471_w

.Lph471_w:
	s_nop 0
	s_nop 0
	s_nop 0
	s_waitcnt vmcnt(8)
	s_waitcnt lgkmcnt(0)
	s_setprio 1
	s_barrier
	v_mfma_f32_16x16x32_bf16 v[124:127], v[128:131], v[160:163], v[124:127]
	v_mfma_f32_16x16x32_bf16 v[120:123], v[136:139], v[160:163], v[120:123]
	v_mfma_f32_16x16x32_bf16 v[108:111], v[128:131], v[168:171], v[108:111]
	v_mfma_f32_16x16x32_bf16 v[104:107], v[136:139], v[168:171], v[104:107]
	v_mfma_f32_16x16x32_bf16 v[92:95], v[128:131], v[192:195], v[92:95]
	v_mfma_f32_16x16x32_bf16 v[88:91], v[136:139], v[192:195], v[88:91]
	v_mfma_f32_16x16x32_bf16 v[76:79], v[128:131], v[200:203], v[76:79]
	v_mfma_f32_16x16x32_bf16 v[72:75], v[136:139], v[200:203], v[72:75]
	v_mfma_f32_16x16x32_bf16 v[124:127], v[132:135], v[164:167], v[124:127]
	v_mfma_f32_16x16x32_bf16 v[120:123], v[140:143], v[164:167], v[120:123]
	v_mfma_f32_16x16x32_bf16 v[108:111], v[132:135], v[172:175], v[108:111]
	v_mfma_f32_16x16x32_bf16 v[104:107], v[140:143], v[172:175], v[104:107]
	v_mfma_f32_16x16x32_bf16 v[92:95], v[132:135], v[196:199], v[92:95]
	v_mfma_f32_16x16x32_bf16 v[88:91], v[140:143], v[196:199], v[88:91]
	v_mfma_f32_16x16x32_bf16 v[76:79], v[132:135], v[210:213], v[76:79]
	v_mfma_f32_16x16x32_bf16 v[72:75], v[140:143], v[210:213], v[72:75]
	s_setprio 0
	s_setprio 1
	v_mfma_f32_16x16x32_bf16 v[116:119], v[144:147], v[160:163], v[116:119]
	v_mfma_f32_16x16x32_bf16 v[112:115], v[152:155], v[160:163], v[112:115]
	v_mfma_f32_16x16x32_bf16 v[100:103], v[144:147], v[168:171], v[100:103]
	v_mfma_f32_16x16x32_bf16 v[96:99], v[152:155], v[168:171], v[96:99]
	v_mfma_f32_16x16x32_bf16 v[84:87], v[144:147], v[192:195], v[84:87]
	v_mfma_f32_16x16x32_bf16 v[80:83], v[152:155], v[192:195], v[80:83]
	v_mfma_f32_16x16x32_bf16 v[68:71], v[144:147], v[200:203], v[68:71]
	v_mfma_f32_16x16x32_bf16 v[64:67], v[152:155], v[200:203], v[64:67]
	v_mfma_f32_16x16x32_bf16 v[116:119], v[148:151], v[164:167], v[116:119]
	v_mfma_f32_16x16x32_bf16 v[112:115], v[156:159], v[164:167], v[112:115]
	v_mfma_f32_16x16x32_bf16 v[100:103], v[148:151], v[172:175], v[100:103]
	v_mfma_f32_16x16x32_bf16 v[96:99], v[156:159], v[172:175], v[96:99]
	v_mfma_f32_16x16x32_bf16 v[84:87], v[148:151], v[196:199], v[84:87]
	v_mfma_f32_16x16x32_bf16 v[80:83], v[156:159], v[196:199], v[80:83]
	v_mfma_f32_16x16x32_bf16 v[68:71], v[148:151], v[210:213], v[68:71]
	v_mfma_f32_16x16x32_bf16 v[64:67], v[156:159], v[210:213], v[64:67]
	s_barrier
	s_setprio 0
	s_add_i32 s70, s62, s40
	v_lshl_add_u64 v[214:215], s[34:35], 0, v[178:179]
	s_mov_b32 m0, s70
	s_nop 0
	global_load_lds_dwordx4 v[214:215], off
	s_add_i32 m0, s70, 0x2000
	s_add_u32 s70, s34, 0x40000
	v_lshl_add_u64 v[216:217], s[34:35], 0, v[182:183]
	s_addc_u32 s71, s35, 0
	s_add_i32 s72, s63, s40
	global_load_lds_dwordx4 v[216:217], off
	v_lshl_add_u64 v[218:219], s[70:71], 0, v[178:179]
	s_mov_b32 m0, s72
	v_lshl_add_u64 v[220:221], s[36:37], 0, v[180:181]
	global_load_lds_dwordx4 v[218:219], off
	v_lshl_add_u64 v[218:219], s[70:71], 0, v[182:183]
	s_add_i32 m0, s72, 0x2000
	s_nop 0
	global_load_lds_dwordx4 v[218:219], off
	v_lshl_add_u64 v[218:219], s[36:37], 0, v[176:177]
	s_mov_b32 m0, s29
	s_nop 0
	global_load_lds_dwordx4 v[218:219], off
	s_mov_b32 m0, s41
	s_nop 0
	global_load_lds_dwordx4 v[220:221], off
	ds_read_b128 v[160:163], v209 offset:16384
	ds_read_b128 v[164:167], v209 offset:17408
	ds_read_b128 v[168:171], v209 offset:18432
	ds_read_b128 v[172:175], v209 offset:19456
	ds_read_b128 v[192:195], v209 offset:20480
	ds_read_b128 v[196:199], v209 offset:21504
	ds_read_b128 v[200:203], v209 offset:22528
	ds_read_b128 v[210:213], v209 offset:23552
	s_nop 0
	s_waitcnt vmcnt(8)
	s_waitcnt lgkmcnt(0)
	s_setprio 1
	s_barrier
	v_mfma_f32_16x16x32_bf16 v[60:63], v[128:131], v[160:163], v[60:63]
	v_mfma_f32_16x16x32_bf16 v[56:59], v[136:139], v[160:163], v[56:59]
	v_mfma_f32_16x16x32_bf16 v[44:47], v[128:131], v[168:171], v[44:47]
	v_mfma_f32_16x16x32_bf16 v[40:43], v[136:139], v[168:171], v[40:43]
	v_mfma_f32_16x16x32_bf16 v[28:31], v[128:131], v[192:195], v[28:31]
	v_mfma_f32_16x16x32_bf16 v[24:27], v[136:139], v[192:195], v[24:27]
	v_mfma_f32_16x16x32_bf16 v[12:15], v[128:131], v[200:203], v[12:15]
	v_mfma_f32_16x16x32_bf16 v[8:11], v[136:139], v[200:203], v[8:11]
	v_mfma_f32_16x16x32_bf16 v[60:63], v[132:135], v[164:167], v[60:63]
	v_mfma_f32_16x16x32_bf16 v[56:59], v[140:143], v[164:167], v[56:59]
	v_mfma_f32_16x16x32_bf16 v[44:47], v[132:135], v[172:175], v[44:47]
	v_mfma_f32_16x16x32_bf16 v[40:43], v[140:143], v[172:175], v[40:43]
	v_mfma_f32_16x16x32_bf16 v[28:31], v[132:135], v[196:199], v[28:31]
	v_mfma_f32_16x16x32_bf16 v[24:27], v[140:143], v[196:199], v[24:27]
	v_mfma_f32_16x16x32_bf16 v[12:15], v[132:135], v[210:213], v[12:15]
	v_mfma_f32_16x16x32_bf16 v[8:11], v[140:143], v[210:213], v[8:11]
	s_setprio 0
	s_setprio 1
	v_mfma_f32_16x16x32_bf16 v[52:55], v[144:147], v[160:163], v[52:55]
	v_mfma_f32_16x16x32_bf16 v[48:51], v[152:155], v[160:163], v[48:51]
	v_mfma_f32_16x16x32_bf16 v[36:39], v[144:147], v[168:171], v[36:39]
	v_mfma_f32_16x16x32_bf16 v[32:35], v[152:155], v[168:171], v[32:35]
	v_mfma_f32_16x16x32_bf16 v[20:23], v[144:147], v[192:195], v[20:23]
	v_mfma_f32_16x16x32_bf16 v[16:19], v[152:155], v[192:195], v[16:19]
	v_mfma_f32_16x16x32_bf16 v[4:7], v[144:147], v[200:203], v[4:7]
	v_mfma_f32_16x16x32_bf16 v[0:3], v[152:155], v[200:203], v[0:3]
	v_mfma_f32_16x16x32_bf16 v[52:55], v[148:151], v[164:167], v[52:55]
	v_mfma_f32_16x16x32_bf16 v[48:51], v[156:159], v[164:167], v[48:51]
	v_mfma_f32_16x16x32_bf16 v[36:39], v[148:151], v[172:175], v[36:39]
	v_mfma_f32_16x16x32_bf16 v[32:35], v[156:159], v[172:175], v[32:35]
	v_mfma_f32_16x16x32_bf16 v[20:23], v[148:151], v[196:199], v[20:23]
	v_mfma_f32_16x16x32_bf16 v[16:19], v[156:159], v[196:199], v[16:19]
	v_mfma_f32_16x16x32_bf16 v[4:7], v[148:151], v[210:213], v[4:7]
	v_mfma_f32_16x16x32_bf16 v[0:3], v[156:159], v[210:213], v[0:3]
	s_barrier
	s_setprio 0
	s_add_i32 s70, 0, 0x18000
	s_add_i32 s71, 0, 0x1c000
	s_add_u32 s36, s36, 0x40000
	s_addc_u32 s37, s37, 0
	s_mov_b32 m0, s42
	v_lshl_add_u64 v[222:223], s[36:37], 0, v[176:177]
	global_load_lds_dwordx4 v[222:223], off
	v_lshl_add_u64 v[222:223], s[36:37], 0, v[180:181]
	s_mov_b32 m0, s43
	s_nop 0
	global_load_lds_dwordx4 v[222:223], off
	v_add_u32_e32 v140, s70, v206
	v_add_u32_e32 v156, s71, v206
	ds_read_b128 v[128:131], v140
	ds_read_b128 v[132:135], v140 offset:1024
	ds_read_b128 v[136:139], v140 offset:2048
	ds_read_b128 v[140:143], v140 offset:3072
	ds_read_b128 v[144:147], v156
	ds_read_b128 v[148:151], v156 offset:1024
	ds_read_b128 v[152:155], v156 offset:2048
	ds_read_b128 v[156:159], v156 offset:3072
	ds_read_b128 v[160:163], v209 offset:32768
	ds_read_b128 v[164:167], v209 offset:33792
	ds_read_b128 v[168:171], v209 offset:34816
	ds_read_b128 v[172:175], v209 offset:35840
	ds_read_b128 v[192:195], v209 offset:36864
	ds_read_b128 v[196:199], v209 offset:37888
	ds_read_b128 v[200:203], v209 offset:38912
	ds_read_b128 v[210:213], v209 offset:39936
	s_waitcnt vmcnt(8)
	s_waitcnt lgkmcnt(0)
	s_setprio 1
	s_barrier
	v_mfma_f32_16x16x32_bf16 v[124:127], v[128:131], v[160:163], v[124:127]
	v_mfma_f32_16x16x32_bf16 v[120:123], v[136:139], v[160:163], v[120:123]
	v_mfma_f32_16x16x32_bf16 v[108:111], v[128:131], v[168:171], v[108:111]
	v_mfma_f32_16x16x32_bf16 v[104:107], v[136:139], v[168:171], v[104:107]
	v_mfma_f32_16x16x32_bf16 v[92:95], v[128:131], v[192:195], v[92:95]
	v_mfma_f32_16x16x32_bf16 v[88:91], v[136:139], v[192:195], v[88:91]
	v_mfma_f32_16x16x32_bf16 v[76:79], v[128:131], v[200:203], v[76:79]
	v_mfma_f32_16x16x32_bf16 v[72:75], v[136:139], v[200:203], v[72:75]
	v_mfma_f32_16x16x32_bf16 v[124:127], v[132:135], v[164:167], v[124:127]
	v_mfma_f32_16x16x32_bf16 v[120:123], v[140:143], v[164:167], v[120:123]
	v_mfma_f32_16x16x32_bf16 v[108:111], v[132:135], v[172:175], v[108:111]
	v_mfma_f32_16x16x32_bf16 v[104:107], v[140:143], v[172:175], v[104:107]
	v_mfma_f32_16x16x32_bf16 v[92:95], v[132:135], v[196:199], v[92:95]
	v_mfma_f32_16x16x32_bf16 v[88:91], v[140:143], v[196:199], v[88:91]
	v_mfma_f32_16x16x32_bf16 v[76:79], v[132:135], v[210:213], v[76:79]
	v_mfma_f32_16x16x32_bf16 v[72:75], v[140:143], v[210:213], v[72:75]
	s_setprio 0
	s_setprio 1
	v_mfma_f32_16x16x32_bf16 v[116:119], v[144:147], v[160:163], v[116:119]
	v_mfma_f32_16x16x32_bf16 v[112:115], v[152:155], v[160:163], v[112:115]
	v_mfma_f32_16x16x32_bf16 v[100:103], v[144:147], v[168:171], v[100:103]
	v_mfma_f32_16x16x32_bf16 v[96:99], v[152:155], v[168:171], v[96:99]
	v_mfma_f32_16x16x32_bf16 v[84:87], v[144:147], v[192:195], v[84:87]
	v_mfma_f32_16x16x32_bf16 v[80:83], v[152:155], v[192:195], v[80:83]
	v_mfma_f32_16x16x32_bf16 v[68:71], v[144:147], v[200:203], v[68:71]
	v_mfma_f32_16x16x32_bf16 v[64:67], v[152:155], v[200:203], v[64:67]
	v_mfma_f32_16x16x32_bf16 v[116:119], v[148:151], v[164:167], v[116:119]
	v_mfma_f32_16x16x32_bf16 v[112:115], v[156:159], v[164:167], v[112:115]
	v_mfma_f32_16x16x32_bf16 v[100:103], v[148:151], v[172:175], v[100:103]
	v_mfma_f32_16x16x32_bf16 v[96:99], v[156:159], v[172:175], v[96:99]
	v_mfma_f32_16x16x32_bf16 v[84:87], v[148:151], v[196:199], v[84:87]
	v_mfma_f32_16x16x32_bf16 v[80:83], v[156:159], v[196:199], v[80:83]
	v_mfma_f32_16x16x32_bf16 v[68:71], v[148:151], v[210:213], v[68:71]
	v_mfma_f32_16x16x32_bf16 v[64:67], v[156:159], v[210:213], v[64:67]
	s_barrier
	s_setprio 0
	s_add_i32 s36, s70, s40
	v_lshl_add_u64 v[214:215], v[214:215], 0, s[14:15]
	s_mov_b32 m0, s36
	s_nop 0
	global_load_lds_dwordx4 v[214:215], off
	s_add_i32 m0, s36, 0x2000
	s_add_u32 s34, s34, 0x40080
	v_lshl_add_u64 v[214:215], v[216:217], 0, s[14:15]
	s_addc_u32 s35, s35, 0
	s_add_i32 s36, s71, s40
	global_load_lds_dwordx4 v[214:215], off
	v_lshl_add_u64 v[214:215], s[34:35], 0, v[178:179]
	s_mov_b32 m0, s36
	s_nop 0
	global_load_lds_dwordx4 v[214:215], off
	v_lshl_add_u64 v[214:215], s[34:35], 0, v[182:183]
	s_add_i32 m0, s36, 0x2000
	s_nop 0
	global_load_lds_dwordx4 v[214:215], off
	v_lshl_add_u64 v[214:215], v[218:219], 0, s[14:15]
	s_mov_b32 m0, s49
	s_nop 0
	global_load_lds_dwordx4 v[214:215], off
	v_lshl_add_u64 v[214:215], v[220:221], 0, s[14:15]
	s_mov_b32 m0, s50
	s_nop 0
	global_load_lds_dwordx4 v[214:215], off
	ds_read_b128 v[160:163], v209 offset:49152
	ds_read_b128 v[164:167], v209 offset:50176
	ds_read_b128 v[168:171], v209 offset:51200
	ds_read_b128 v[172:175], v209 offset:52224
	ds_read_b128 v[192:195], v209 offset:53248
	ds_read_b128 v[196:199], v209 offset:54272
	ds_read_b128 v[200:203], v209 offset:55296
	ds_read_b128 v[210:213], v209 offset:56320
	s_waitcnt vmcnt(8)
	s_waitcnt lgkmcnt(0)
	s_setprio 1
	s_barrier
	v_mfma_f32_16x16x32_bf16 v[60:63], v[128:131], v[160:163], v[60:63]
	v_mfma_f32_16x16x32_bf16 v[56:59], v[136:139], v[160:163], v[56:59]
	v_mfma_f32_16x16x32_bf16 v[44:47], v[128:131], v[168:171], v[44:47]
	v_mfma_f32_16x16x32_bf16 v[40:43], v[136:139], v[168:171], v[40:43]
	v_mfma_f32_16x16x32_bf16 v[28:31], v[128:131], v[192:195], v[28:31]
	v_mfma_f32_16x16x32_bf16 v[24:27], v[136:139], v[192:195], v[24:27]
	v_mfma_f32_16x16x32_bf16 v[12:15], v[128:131], v[200:203], v[12:15]
	v_mfma_f32_16x16x32_bf16 v[8:11], v[136:139], v[200:203], v[8:11]
	v_mfma_f32_16x16x32_bf16 v[60:63], v[132:135], v[164:167], v[60:63]
	v_mfma_f32_16x16x32_bf16 v[56:59], v[140:143], v[164:167], v[56:59]
	v_mfma_f32_16x16x32_bf16 v[44:47], v[132:135], v[172:175], v[44:47]
	v_mfma_f32_16x16x32_bf16 v[40:43], v[140:143], v[172:175], v[40:43]
	v_mfma_f32_16x16x32_bf16 v[28:31], v[132:135], v[196:199], v[28:31]
	v_mfma_f32_16x16x32_bf16 v[24:27], v[140:143], v[196:199], v[24:27]
	v_mfma_f32_16x16x32_bf16 v[12:15], v[132:135], v[210:213], v[12:15]
	v_mfma_f32_16x16x32_bf16 v[8:11], v[140:143], v[210:213], v[8:11]
	s_setprio 0
	s_setprio 1
	v_mfma_f32_16x16x32_bf16 v[52:55], v[144:147], v[160:163], v[52:55]
	v_mfma_f32_16x16x32_bf16 v[48:51], v[152:155], v[160:163], v[48:51]
	v_mfma_f32_16x16x32_bf16 v[36:39], v[144:147], v[168:171], v[36:39]
	v_mfma_f32_16x16x32_bf16 v[32:35], v[152:155], v[168:171], v[32:35]
	v_mfma_f32_16x16x32_bf16 v[20:23], v[144:147], v[192:195], v[20:23]
	v_mfma_f32_16x16x32_bf16 v[16:19], v[152:155], v[192:195], v[16:19]
	v_mfma_f32_16x16x32_bf16 v[4:7], v[144:147], v[200:203], v[4:7]
	v_mfma_f32_16x16x32_bf16 v[0:3], v[152:155], v[200:203], v[0:3]
	v_mfma_f32_16x16x32_bf16 v[52:55], v[148:151], v[164:167], v[52:55]
	v_mfma_f32_16x16x32_bf16 v[48:51], v[156:159], v[164:167], v[48:51]
	v_mfma_f32_16x16x32_bf16 v[36:39], v[148:151], v[172:175], v[36:39]
	v_mfma_f32_16x16x32_bf16 v[32:35], v[156:159], v[172:175], v[32:35]
	v_mfma_f32_16x16x32_bf16 v[20:23], v[148:151], v[196:199], v[20:23]
	v_mfma_f32_16x16x32_bf16 v[16:19], v[156:159], v[196:199], v[16:19]
	v_mfma_f32_16x16x32_bf16 v[4:7], v[148:151], v[210:213], v[4:7]
	v_mfma_f32_16x16x32_bf16 v[0:3], v[156:159], v[210:213], v[0:3]
	s_barrier
	s_setprio 0
	s_add_i32 s69, s69, 2
	s_add_u32 s30, s30, 0x100
	s_addc_u32 s31, s31, 0
	s_add_u32 s65, s65, 0x100
	s_addc_u32 s68, s68, 0
	s_cmp_gt_u32 s69, 13
	s_cbranch_scc0 .LBB0_471
	s_and_b64 vcc, exec, s[16:17]
	s_cbranch_vccz .LBB0_474
	s_barrier

.LBB0_490:
	s_or_b64 exec, exec, s[26:27]
	s_andn2_b64 vcc, exec, s[6:7]
	s_mov_b64 s[6:7], -1
	s_cbranch_vccnz .LBB0_463
	s_mov_b32 s101, 0
	s_andn2_b64 vcc, exec, s[12:13]
	s_cbranch_vccnz .LBB0_462
	s_mov_b32 s101, 1
	s_branch .LBB0_462

.LBB0_549:
	s_lshl_b32 s12, s12, 5
	s_and_b32 s17, s12, 0x60
	s_mov_b64 s[12:13], 0x80
	s_add_i32 m0, s25, 0x18000
	v_lshl_add_u64 v[6:7], v[6:7], 0, s[12:13]
	s_lshl_b32 s16, s7, 13
	s_lshl_b32 s18, s17, 7
	s_waitcnt vmcnt(2)
	s_barrier
	global_load_lds_dwordx4 v[6:7], off
	v_lshl_add_u64 v[4:5], v[4:5], 0, s[12:13]
	s_add_i32 m0, s25, 0x1a000
	s_add_i32 s42, s25, 0x8000
	s_add_i32 s43, s25, 0xa000
	global_load_lds_dwordx4 v[4:5], off
	v_lshl_add_u64 v[0:1], v[0:1], 0, s[12:13]
	s_mov_b32 m0, s42
	s_add_u32 s14, s30, 0x40080
	global_load_lds_dwordx4 v[0:1], off
	v_lshl_add_u64 v[0:1], v[2:3], 0, s[12:13]
	s_mov_b32 m0, s43
	s_addc_u32 s15, s31, 0
	global_load_lds_dwordx4 v[0:1], off
	s_add_i32 m0, s25, 0x1c000
	v_lshl_add_u64 v[0:1], s[14:15], 0, v[132:133]
	global_load_lds_dwordx4 v[0:1], off
	v_lshl_add_u64 v[0:1], s[14:15], 0, v[128:129]
	s_add_i32 m0, s25, 0x1e000
	s_cmpk_lt_u32 s6, 0x100
	global_load_lds_dwordx4 v[0:1], off
	v_lshrrev_b32_e32 v1, 1, v9
	v_and_b32_e32 v1, 24, v1
	v_and_b32_e32 v0, 15, v9
	v_lshlrev_b32_e32 v2, 1, v1
	v_lshl_or_b32 v146, s7, 6, v0
	v_lshl_or_b32 v0, v0, 6, v2
	v_lshlrev_b32_e32 v2, 2, v9
	v_and_b32_e32 v2, 32, v2
	v_bitop3_b32 v3, v0, s16, v2 bitop3:0xde
	v_bitop3_b32 v147, v0, s18, v2 bitop3:0xde
	v_lshlrev_b32_e32 v0, 14, v13
	v_and_b32_e32 v0, 0xffff8000, v0
	v_or_b32_e32 v148, s17, v1
	v_lshl_add_u32 v0, v12, 11, v0
	v_and_b32_e32 v1, 1, v13
	v_lshl_or_b32 v0, v1, 6, v0
	v_lshl_add_u32 v136, v14, 1, v0
	v_lshlrev_b32_e32 v0, 14, v8
	v_and_b32_e32 v0, 0xffff8000, v0
	s_waitcnt vmcnt(6)
	v_lshl_add_u32 v0, v10, 11, v0
	v_and_b32_e32 v1, 1, v8
	s_cselect_b64 s[14:15], -1, 0
	v_lshl_or_b32 v0, v1, 6, v0
	s_add_i32 s48, 0, 0x10000
	s_add_i32 s49, 0, 0x14000
	s_ashr_i32 s46, s52, 31
	s_mov_b32 s47, s52
	v_mov_b32_e32 v137, v133
	v_lshl_add_u32 v138, v11, 1, v0
	v_mov_b32_e32 v139, v133
	v_mov_b64_e32 v[140:141], 0xb00
	v_mov_b64_e32 v[142:143], 0xaff
	v_add_u32_e32 v149, s48, v147
	v_add_u32_e32 v150, s49, v147
	v_add_u32_e32 v151, 0, v3
	v_mov_b32_e32 v152, 0x358637bd
	s_movk_i32 s50, 0x1600
	s_barrier
	v_lshl_add_u32 v238, s26, 8, v146
	v_ashrrev_i32_e32 v239, 31, v238
	v_lshl_add_u64 v[238:239], v[238:239], 2, s[8:9]
	global_load_dword v230, v[238:239], off sc1
	global_load_dword v231, v[238:239], off offset:64 sc1
	global_load_dword v232, v[238:239], off offset:128 sc1
	global_load_dword v233, v[238:239], off offset:192 sc1
	global_load_dword v234, v[238:239], off offset:512 sc1
	global_load_dword v235, v[238:239], off offset:576 sc1
	global_load_dword v236, v[238:239], off offset:640 sc1
	global_load_dword v237, v[238:239], off offset:704 sc1
	s_mov_b32 s101, 0
	s_branch .LBB0_552

.LBB0_554:
	s_ashr_i32 s19, s18, 31
	s_lshl_b64 s[20:21], s[18:19], 19
	s_add_u32 s20, s58, s20
	s_addc_u32 s21, s59, s21
	s_and_b64 s[22:23], s[6:7], exec
	s_cselect_b32 s19, s21, s29
	s_cselect_b32 s51, s20, s28
	s_ashr_i32 s17, s16, 31
	s_lshl_b64 s[22:23], s[16:17], 19
	s_add_u32 s22, s4, s22
	s_addc_u32 s23, s5, s23
	s_and_b64 s[34:35], s[6:7], exec
	s_cselect_b32 s17, s23, s31
	s_cselect_b32 s60, s22, s30
	s_add_u32 s28, s28, 0x40080
	s_addc_u32 s29, s29, 0
	s_add_u32 s61, s30, 0x100
	v_mov_b32_e32 v0, 0
	s_addc_u32 s62, s31, 0
	s_mov_b32 s63, -2
	s_waitcnt vmcnt(0)
	s_cmp_lg_u32 s101, 0
	s_cbranch_scc0 .Lph555_a
	v_mov_b32_e32 v1, v0
	v_mov_b32_e32 v2, v0
	v_mov_b32_e32 v3, v0
	v_mov_b32_e32 v8, v0
	v_mov_b32_e32 v9, v0
	v_mov_b32_e32 v10, v0
	v_mov_b32_e32 v11, v0
	v_mov_b32_e32 v16, v0
	v_mov_b32_e32 v17, v0
	v_mov_b32_e32 v18, v0
	v_mov_b32_e32 v19, v0
	v_mov_b32_e32 v24, v0
	v_mov_b32_e32 v25, v0
	v_mov_b32_e32 v26, v0
	v_mov_b32_e32 v27, v0
	v_mov_b32_e32 v32, v0
	v_mov_b32_e32 v33, v0
	v_mov_b32_e32 v34, v0
	v_mov_b32_e32 v35, v0
	v_mov_b32_e32 v40, v0
	v_mov_b32_e32 v41, v0
	v_mov_b32_e32 v42, v0
	v_mov_b32_e32 v43, v0
	v_mov_b32_e32 v48, v0
	v_mov_b32_e32 v49, v0
	v_mov_b32_e32 v50, v0
	v_mov_b32_e32 v51, v0
	v_mov_b32_e32 v56, v0
	v_mov_b32_e32 v57, v0
	v_mov_b32_e32 v58, v0
	v_mov_b32_e32 v59, v0
	v_mov_b32_e32 v4, v0
	v_mov_b32_e32 v5, v0
	v_mov_b32_e32 v6, v0
	v_mov_b32_e32 v7, v0
	v_mov_b32_e32 v12, v0
	v_mov_b32_e32 v13, v0
	v_mov_b32_e32 v14, v0
	v_mov_b32_e32 v15, v0
	v_mov_b32_e32 v20, v0
	v_mov_b32_e32 v21, v0
	v_mov_b32_e32 v22, v0
	v_mov_b32_e32 v23, v0
	v_mov_b32_e32 v28, v0
	v_mov_b32_e32 v29, v0
	v_mov_b32_e32 v30, v0
	v_mov_b32_e32 v31, v0
	v_mov_b32_e32 v36, v0
	v_mov_b32_e32 v37, v0
	v_mov_b32_e32 v38, v0
	v_mov_b32_e32 v39, v0
	v_mov_b32_e32 v44, v0
	v_mov_b32_e32 v45, v0
	v_mov_b32_e32 v46, v0
	v_mov_b32_e32 v47, v0
	v_mov_b32_e32 v52, v0
	v_mov_b32_e32 v53, v0
	v_mov_b32_e32 v54, v0
	v_mov_b32_e32 v55, v0
	v_mov_b32_e32 v60, v0
	v_mov_b32_e32 v61, v0
	v_mov_b32_e32 v62, v0
	v_mov_b32_e32 v63, v0
	v_mov_b32_e32 v64, v0
	v_mov_b32_e32 v65, v0
	v_mov_b32_e32 v66, v0
	v_mov_b32_e32 v67, v0
	v_mov_b32_e32 v72, v0
	v_mov_b32_e32 v73, v0
	v_mov_b32_e32 v74, v0
	v_mov_b32_e32 v75, v0
	v_mov_b32_e32 v80, v0
	v_mov_b32_e32 v81, v0
	v_mov_b32_e32 v82, v0
	v_mov_b32_e32 v83, v0
	v_mov_b32_e32 v88, v0
	v_mov_b32_e32 v89, v0
	v_mov_b32_e32 v90, v0
	v_mov_b32_e32 v91, v0
	v_mov_b32_e32 v96, v0
	v_mov_b32_e32 v97, v0
	v_mov_b32_e32 v98, v0
	v_mov_b32_e32 v99, v0
	v_mov_b32_e32 v104, v0
	v_mov_b32_e32 v105, v0
	v_mov_b32_e32 v106, v0
	v_mov_b32_e32 v107, v0
	v_mov_b32_e32 v120, v0
	v_mov_b32_e32 v121, v0
	v_mov_b32_e32 v122, v0
	v_mov_b32_e32 v123, v0
	v_mov_b32_e32 v124, v0
	v_mov_b32_e32 v125, v0
	v_mov_b32_e32 v126, v0
	v_mov_b32_e32 v127, v0
	v_mov_b32_e32 v68, v0
	v_mov_b32_e32 v69, v0
	v_mov_b32_e32 v70, v0
	v_mov_b32_e32 v71, v0
	v_mov_b32_e32 v76, v0
	v_mov_b32_e32 v77, v0
	v_mov_b32_e32 v78, v0
	v_mov_b32_e32 v79, v0
	v_mov_b32_e32 v84, v0
	v_mov_b32_e32 v85, v0
	v_mov_b32_e32 v86, v0
	v_mov_b32_e32 v87, v0
	v_mov_b32_e32 v92, v0
	v_mov_b32_e32 v93, v0
	v_mov_b32_e32 v94, v0
	v_mov_b32_e32 v95, v0
	v_mov_b32_e32 v100, v0
	v_mov_b32_e32 v101, v0
	v_mov_b32_e32 v102, v0
	v_mov_b32_e32 v103, v0
	v_mov_b32_e32 v108, v0
	v_mov_b32_e32 v109, v0
	v_mov_b32_e32 v110, v0
	v_mov_b32_e32 v111, v0
	v_mov_b32_e32 v112, v0
	v_mov_b32_e32 v113, v0
	v_mov_b32_e32 v114, v0
	v_mov_b32_e32 v115, v0
	v_mov_b32_e32 v116, v0
	v_mov_b32_e32 v117, v0
	v_mov_b32_e32 v118, v0
	v_mov_b32_e32 v119, v0
	s_barrier
	s_mov_b32 s101, 0
	s_branch .LBB0_555
.Lph555_a:
	s_add_u32 s30, s28, 0xfffc0080
	s_addc_u32 s31, s29, -1
	s_cmp_eq_u32 s63, 12
	s_cselect_b32 s35, s19, s31
	s_cselect_b32 s34, s51, s30
	s_cselect_b32 s31, s17, s62
	s_cselect_b32 s30, s60, s61
	v_lshl_add_u64 v[144:145], s[28:29], 0, v[136:137]
	s_add_i32 m0, s25, 0xc000
	s_nop 0
	global_load_lds_dwordx4 v[144:145], off
	v_lshl_add_u64 v[144:145], s[28:29], 0, v[138:139]
	s_add_i32 m0, s25, 0xe000
	s_nop 0
	global_load_lds_dwordx4 v[144:145], off
	ds_read_b128 v[154:157], v149
	ds_read_b128 v[158:161], v149 offset:1024
	ds_read_b128 v[162:165], v149 offset:2048
	ds_read_b128 v[166:169], v149 offset:3072
	ds_read_b128 v[170:173], v150
	ds_read_b128 v[174:177], v150 offset:1024
	ds_read_b128 v[178:181], v150 offset:2048
	ds_read_b128 v[182:185], v150 offset:3072
	ds_read_b128 v[186:189], v151
	ds_read_b128 v[190:193], v151 offset:1024
	ds_read_b128 v[194:197], v151 offset:2048
	ds_read_b128 v[198:201], v151 offset:3072
	ds_read_b128 v[202:205], v151 offset:4096
	ds_read_b128 v[206:209], v151 offset:5120
	ds_read_b128 v[210:213], v151 offset:6144
	ds_read_b128 v[214:217], v151 offset:7168
	v_mov_b32_e32 v1, v0
	v_mov_b32_e32 v2, v0
	v_mov_b32_e32 v3, v0
	v_mov_b32_e32 v8, v0
	v_mov_b32_e32 v9, v0
	v_mov_b32_e32 v10, v0
	v_mov_b32_e32 v11, v0
	v_mov_b32_e32 v16, v0
	v_mov_b32_e32 v17, v0
	v_mov_b32_e32 v18, v0
	v_mov_b32_e32 v19, v0
	v_mov_b32_e32 v24, v0
	v_mov_b32_e32 v25, v0
	v_mov_b32_e32 v26, v0
	v_mov_b32_e32 v27, v0
	v_mov_b32_e32 v32, v0
	v_mov_b32_e32 v33, v0
	v_mov_b32_e32 v34, v0
	v_mov_b32_e32 v35, v0
	v_mov_b32_e32 v40, v0
	v_mov_b32_e32 v41, v0
	v_mov_b32_e32 v42, v0
	v_mov_b32_e32 v43, v0
	v_mov_b32_e32 v48, v0
	v_mov_b32_e32 v49, v0
	v_mov_b32_e32 v50, v0
	v_mov_b32_e32 v51, v0
	v_mov_b32_e32 v56, v0
	v_mov_b32_e32 v57, v0
	v_mov_b32_e32 v58, v0
	v_mov_b32_e32 v59, v0
	v_mov_b32_e32 v4, v0
	v_mov_b32_e32 v5, v0
	v_mov_b32_e32 v6, v0
	v_mov_b32_e32 v7, v0
	v_mov_b32_e32 v12, v0
	v_mov_b32_e32 v13, v0
	v_mov_b32_e32 v14, v0
	v_mov_b32_e32 v15, v0
	v_mov_b32_e32 v20, v0
	v_mov_b32_e32 v21, v0
	v_mov_b32_e32 v22, v0
	v_mov_b32_e32 v23, v0
	v_mov_b32_e32 v28, v0
	v_mov_b32_e32 v29, v0
	v_mov_b32_e32 v30, v0
	v_mov_b32_e32 v31, v0
	v_mov_b32_e32 v36, v0
	v_mov_b32_e32 v37, v0
	v_mov_b32_e32 v38, v0
	v_mov_b32_e32 v39, v0
	v_mov_b32_e32 v44, v0
	v_mov_b32_e32 v45, v0
	v_mov_b32_e32 v46, v0
	v_mov_b32_e32 v47, v0
	v_mov_b32_e32 v52, v0
	v_mov_b32_e32 v53, v0
	v_mov_b32_e32 v54, v0
	v_mov_b32_e32 v55, v0
	v_mov_b32_e32 v60, v0
	v_mov_b32_e32 v61, v0
	v_mov_b32_e32 v62, v0
	v_mov_b32_e32 v63, v0
	v_mov_b32_e32 v64, v0
	v_mov_b32_e32 v65, v0
	v_mov_b32_e32 v66, v0
	v_mov_b32_e32 v67, v0
	v_mov_b32_e32 v72, v0
	v_mov_b32_e32 v73, v0
	v_mov_b32_e32 v74, v0
	v_mov_b32_e32 v75, v0
	v_mov_b32_e32 v80, v0
	v_mov_b32_e32 v81, v0
	v_mov_b32_e32 v82, v0
	v_mov_b32_e32 v83, v0
	v_mov_b32_e32 v88, v0
	v_mov_b32_e32 v89, v0
	v_mov_b32_e32 v90, v0
	v_mov_b32_e32 v91, v0
	v_mov_b32_e32 v96, v0
	v_mov_b32_e32 v97, v0
	v_mov_b32_e32 v98, v0
	v_mov_b32_e32 v99, v0
	v_mov_b32_e32 v104, v0
	v_mov_b32_e32 v105, v0
	v_mov_b32_e32 v106, v0
	v_mov_b32_e32 v107, v0
	v_mov_b32_e32 v120, v0
	v_mov_b32_e32 v121, v0
	v_mov_b32_e32 v122, v0
	v_mov_b32_e32 v123, v0
	v_mov_b32_e32 v124, v0
	v_mov_b32_e32 v125, v0
	v_mov_b32_e32 v126, v0
	v_mov_b32_e32 v127, v0
	v_mov_b32_e32 v68, v0
	v_mov_b32_e32 v69, v0
	v_mov_b32_e32 v70, v0
	v_mov_b32_e32 v71, v0
	v_mov_b32_e32 v76, v0
	v_mov_b32_e32 v77, v0
	v_mov_b32_e32 v78, v0
	v_mov_b32_e32 v79, v0
	v_mov_b32_e32 v84, v0
	v_mov_b32_e32 v85, v0
	v_mov_b32_e32 v86, v0
	v_mov_b32_e32 v87, v0
	v_mov_b32_e32 v92, v0
	v_mov_b32_e32 v93, v0
	v_mov_b32_e32 v94, v0
	v_mov_b32_e32 v95, v0
	v_mov_b32_e32 v100, v0
	v_mov_b32_e32 v101, v0
	v_mov_b32_e32 v102, v0
	v_mov_b32_e32 v103, v0
	v_mov_b32_e32 v108, v0
	v_mov_b32_e32 v109, v0
	v_mov_b32_e32 v110, v0
	v_mov_b32_e32 v111, v0
	v_mov_b32_e32 v112, v0
	v_mov_b32_e32 v113, v0
	v_mov_b32_e32 v114, v0
	v_mov_b32_e32 v115, v0
	v_mov_b32_e32 v116, v0
	v_mov_b32_e32 v117, v0
	v_mov_b32_e32 v118, v0
	v_mov_b32_e32 v119, v0
	s_branch .Lph555_w

.Lph555_w:
	s_nop 0
	s_nop 0
	s_waitcnt vmcnt(8)
	s_waitcnt lgkmcnt(0)
	s_setprio 1
	s_barrier
	v_mfma_f32_16x16x32_bf16 v[116:119], v[154:157], v[186:189], v[116:119]
	v_mfma_f32_16x16x32_bf16 v[112:115], v[162:165], v[186:189], v[112:115]
	v_mfma_f32_16x16x32_bf16 v[108:111], v[154:157], v[194:197], v[108:111]
	v_mfma_f32_16x16x32_bf16 v[100:103], v[162:165], v[194:197], v[100:103]
	v_mfma_f32_16x16x32_bf16 v[92:95], v[154:157], v[202:205], v[92:95]
	v_mfma_f32_16x16x32_bf16 v[84:87], v[162:165], v[202:205], v[84:87]
	v_mfma_f32_16x16x32_bf16 v[76:79], v[154:157], v[210:213], v[76:79]
	v_mfma_f32_16x16x32_bf16 v[68:71], v[162:165], v[210:213], v[68:71]
	v_mfma_f32_16x16x32_bf16 v[116:119], v[158:161], v[190:193], v[116:119]
	v_mfma_f32_16x16x32_bf16 v[112:115], v[166:169], v[190:193], v[112:115]
	v_mfma_f32_16x16x32_bf16 v[108:111], v[158:161], v[198:201], v[108:111]
	v_mfma_f32_16x16x32_bf16 v[100:103], v[166:169], v[198:201], v[100:103]
	v_mfma_f32_16x16x32_bf16 v[92:95], v[158:161], v[206:209], v[92:95]
	v_mfma_f32_16x16x32_bf16 v[84:87], v[166:169], v[206:209], v[84:87]
	v_mfma_f32_16x16x32_bf16 v[76:79], v[158:161], v[214:217], v[76:79]
	v_mfma_f32_16x16x32_bf16 v[68:71], v[166:169], v[214:217], v[68:71]
	s_setprio 0
	s_setprio 1
	v_mfma_f32_16x16x32_bf16 v[124:127], v[170:173], v[186:189], v[124:127]
	v_mfma_f32_16x16x32_bf16 v[120:123], v[178:181], v[186:189], v[120:123]
	v_mfma_f32_16x16x32_bf16 v[104:107], v[170:173], v[194:197], v[104:107]
	v_mfma_f32_16x16x32_bf16 v[96:99], v[178:181], v[194:197], v[96:99]
	v_mfma_f32_16x16x32_bf16 v[88:91], v[170:173], v[202:205], v[88:91]
	v_mfma_f32_16x16x32_bf16 v[80:83], v[178:181], v[202:205], v[80:83]
	v_mfma_f32_16x16x32_bf16 v[72:75], v[170:173], v[210:213], v[72:75]
	v_mfma_f32_16x16x32_bf16 v[64:67], v[178:181], v[210:213], v[64:67]
	v_mfma_f32_16x16x32_bf16 v[124:127], v[174:177], v[190:193], v[124:127]
	v_mfma_f32_16x16x32_bf16 v[120:123], v[182:185], v[190:193], v[120:123]
	v_mfma_f32_16x16x32_bf16 v[104:107], v[174:177], v[198:201], v[104:107]
	v_mfma_f32_16x16x32_bf16 v[96:99], v[182:185], v[198:201], v[96:99]
	v_mfma_f32_16x16x32_bf16 v[88:91], v[174:177], v[206:209], v[88:91]
	v_mfma_f32_16x16x32_bf16 v[80:83], v[182:185], v[206:209], v[80:83]
	v_mfma_f32_16x16x32_bf16 v[72:75], v[174:177], v[214:217], v[72:75]
	v_mfma_f32_16x16x32_bf16 v[64:67], v[182:185], v[214:217], v[64:67]
	s_barrier
	s_setprio 0
	s_add_i32 s64, s48, s36
	v_lshl_add_u64 v[144:145], s[30:31], 0, v[132:133]
	s_mov_b32 m0, s64
	s_nop 0
	global_load_lds_dwordx4 v[144:145], off
	s_add_i32 m0, s64, 0x2000
	s_add_u32 s64, s30, 0x40000
	v_lshl_add_u64 v[218:219], s[30:31], 0, v[128:129]
	s_addc_u32 s65, s31, 0
	s_add_i32 s68, s49, s36
	global_load_lds_dwordx4 v[218:219], off
	v_lshl_add_u64 v[220:221], s[64:65], 0, v[132:133]
	s_mov_b32 m0, s68
	v_lshl_add_u64 v[222:223], s[34:35], 0, v[130:131]
	global_load_lds_dwordx4 v[220:221], off
	v_lshl_add_u64 v[220:221], s[64:65], 0, v[128:129]
	s_add_i32 m0, s68, 0x2000
	s_nop 0
	global_load_lds_dwordx4 v[220:221], off
	v_lshl_add_u64 v[220:221], s[34:35], 0, v[134:135]
	s_mov_b32 m0, s25
	s_nop 0
	global_load_lds_dwordx4 v[220:221], off
	s_mov_b32 m0, s27
	s_nop 0
	global_load_lds_dwordx4 v[222:223], off
	ds_read_b128 v[186:189], v151 offset:16384
	ds_read_b128 v[190:193], v151 offset:17408
	ds_read_b128 v[194:197], v151 offset:18432
	ds_read_b128 v[198:201], v151 offset:19456
	ds_read_b128 v[202:205], v151 offset:20480
	ds_read_b128 v[206:209], v151 offset:21504
	ds_read_b128 v[210:213], v151 offset:22528
	ds_read_b128 v[214:217], v151 offset:23552
	s_nop 0
	s_waitcnt vmcnt(8)
	s_waitcnt lgkmcnt(0)
	s_setprio 1
	s_barrier
	v_mfma_f32_16x16x32_bf16 v[60:63], v[154:157], v[186:189], v[60:63]
	v_mfma_f32_16x16x32_bf16 v[52:55], v[162:165], v[186:189], v[52:55]
	v_mfma_f32_16x16x32_bf16 v[44:47], v[154:157], v[194:197], v[44:47]
	v_mfma_f32_16x16x32_bf16 v[36:39], v[162:165], v[194:197], v[36:39]
	v_mfma_f32_16x16x32_bf16 v[28:31], v[154:157], v[202:205], v[28:31]
	v_mfma_f32_16x16x32_bf16 v[20:23], v[162:165], v[202:205], v[20:23]
	v_mfma_f32_16x16x32_bf16 v[12:15], v[154:157], v[210:213], v[12:15]
	v_mfma_f32_16x16x32_bf16 v[4:7], v[162:165], v[210:213], v[4:7]
	v_mfma_f32_16x16x32_bf16 v[60:63], v[158:161], v[190:193], v[60:63]
	v_mfma_f32_16x16x32_bf16 v[52:55], v[166:169], v[190:193], v[52:55]
	v_mfma_f32_16x16x32_bf16 v[44:47], v[158:161], v[198:201], v[44:47]
	v_mfma_f32_16x16x32_bf16 v[36:39], v[166:169], v[198:201], v[36:39]
	v_mfma_f32_16x16x32_bf16 v[28:31], v[158:161], v[206:209], v[28:31]
	v_mfma_f32_16x16x32_bf16 v[20:23], v[166:169], v[206:209], v[20:23]
	v_mfma_f32_16x16x32_bf16 v[12:15], v[158:161], v[214:217], v[12:15]
	v_mfma_f32_16x16x32_bf16 v[4:7], v[166:169], v[214:217], v[4:7]
	s_setprio 0
	s_setprio 1
	v_mfma_f32_16x16x32_bf16 v[56:59], v[170:173], v[186:189], v[56:59]
	v_mfma_f32_16x16x32_bf16 v[48:51], v[178:181], v[186:189], v[48:51]
	v_mfma_f32_16x16x32_bf16 v[40:43], v[170:173], v[194:197], v[40:43]
	v_mfma_f32_16x16x32_bf16 v[32:35], v[178:181], v[194:197], v[32:35]
	v_mfma_f32_16x16x32_bf16 v[24:27], v[170:173], v[202:205], v[24:27]
	v_mfma_f32_16x16x32_bf16 v[16:19], v[178:181], v[202:205], v[16:19]
	v_mfma_f32_16x16x32_bf16 v[8:11], v[170:173], v[210:213], v[8:11]
	v_mfma_f32_16x16x32_bf16 v[0:3], v[178:181], v[210:213], v[0:3]
	v_mfma_f32_16x16x32_bf16 v[56:59], v[174:177], v[190:193], v[56:59]
	v_mfma_f32_16x16x32_bf16 v[48:51], v[182:185], v[190:193], v[48:51]
	v_mfma_f32_16x16x32_bf16 v[40:43], v[174:177], v[198:201], v[40:43]
	v_mfma_f32_16x16x32_bf16 v[32:35], v[182:185], v[198:201], v[32:35]
	v_mfma_f32_16x16x32_bf16 v[24:27], v[174:177], v[206:209], v[24:27]
	v_mfma_f32_16x16x32_bf16 v[16:19], v[182:185], v[206:209], v[16:19]
	v_mfma_f32_16x16x32_bf16 v[8:11], v[174:177], v[214:217], v[8:11]
	v_mfma_f32_16x16x32_bf16 v[0:3], v[182:185], v[214:217], v[0:3]
	s_barrier
	s_setprio 0
	s_add_i32 s64, 0, 0x18000
	s_add_i32 s65, 0, 0x1c000
	s_add_u32 s34, s34, 0x40000
	s_addc_u32 s35, s35, 0
	s_mov_b32 m0, s39
	v_lshl_add_u64 v[224:225], s[34:35], 0, v[134:135]
	global_load_lds_dwordx4 v[224:225], off
	v_lshl_add_u64 v[224:225], s[34:35], 0, v[130:131]
	s_mov_b32 m0, s40
	s_nop 0
	global_load_lds_dwordx4 v[224:225], off
	v_add_u32_e32 v153, s64, v147
	ds_read_b128 v[154:157], v153
	ds_read_b128 v[158:161], v153 offset:1024
	ds_read_b128 v[162:165], v153 offset:2048
	ds_read_b128 v[166:169], v153 offset:3072
	v_add_u32_e32 v153, s65, v147
	ds_read_b128 v[170:173], v153
	ds_read_b128 v[174:177], v153 offset:1024
	ds_read_b128 v[178:181], v153 offset:2048
	ds_read_b128 v[182:185], v153 offset:3072
	ds_read_b128 v[186:189], v151 offset:32768
	ds_read_b128 v[190:193], v151 offset:33792
	ds_read_b128 v[194:197], v151 offset:34816
	ds_read_b128 v[198:201], v151 offset:35840
	ds_read_b128 v[202:205], v151 offset:36864
	ds_read_b128 v[206:209], v151 offset:37888
	ds_read_b128 v[210:213], v151 offset:38912
	ds_read_b128 v[214:217], v151 offset:39936
	s_waitcnt vmcnt(8)
	s_waitcnt lgkmcnt(0)
	s_setprio 1
	s_barrier
	v_mfma_f32_16x16x32_bf16 v[116:119], v[154:157], v[186:189], v[116:119]
	v_mfma_f32_16x16x32_bf16 v[112:115], v[162:165], v[186:189], v[112:115]
	v_mfma_f32_16x16x32_bf16 v[108:111], v[154:157], v[194:197], v[108:111]
	v_mfma_f32_16x16x32_bf16 v[100:103], v[162:165], v[194:197], v[100:103]
	v_mfma_f32_16x16x32_bf16 v[92:95], v[154:157], v[202:205], v[92:95]
	v_mfma_f32_16x16x32_bf16 v[84:87], v[162:165], v[202:205], v[84:87]
	v_mfma_f32_16x16x32_bf16 v[76:79], v[154:157], v[210:213], v[76:79]
	v_mfma_f32_16x16x32_bf16 v[68:71], v[162:165], v[210:213], v[68:71]
	v_mfma_f32_16x16x32_bf16 v[116:119], v[158:161], v[190:193], v[116:119]
	v_mfma_f32_16x16x32_bf16 v[112:115], v[166:169], v[190:193], v[112:115]
	v_mfma_f32_16x16x32_bf16 v[108:111], v[158:161], v[198:201], v[108:111]
	v_mfma_f32_16x16x32_bf16 v[100:103], v[166:169], v[198:201], v[100:103]
	v_mfma_f32_16x16x32_bf16 v[92:95], v[158:161], v[206:209], v[92:95]
	v_mfma_f32_16x16x32_bf16 v[84:87], v[166:169], v[206:209], v[84:87]
	v_mfma_f32_16x16x32_bf16 v[76:79], v[158:161], v[214:217], v[76:79]
	v_mfma_f32_16x16x32_bf16 v[68:71], v[166:169], v[214:217], v[68:71]
	s_setprio 0
	s_setprio 1
	v_mfma_f32_16x16x32_bf16 v[124:127], v[170:173], v[186:189], v[124:127]
	v_mfma_f32_16x16x32_bf16 v[120:123], v[178:181], v[186:189], v[120:123]
	v_mfma_f32_16x16x32_bf16 v[104:107], v[170:173], v[194:197], v[104:107]
	v_mfma_f32_16x16x32_bf16 v[96:99], v[178:181], v[194:197], v[96:99]
	v_mfma_f32_16x16x32_bf16 v[88:91], v[170:173], v[202:205], v[88:91]
	v_mfma_f32_16x16x32_bf16 v[80:83], v[178:181], v[202:205], v[80:83]
	v_mfma_f32_16x16x32_bf16 v[72:75], v[170:173], v[210:213], v[72:75]
	v_mfma_f32_16x16x32_bf16 v[64:67], v[178:181], v[210:213], v[64:67]
	v_mfma_f32_16x16x32_bf16 v[124:127], v[174:177], v[190:193], v[124:127]
	v_mfma_f32_16x16x32_bf16 v[120:123], v[182:185], v[190:193], v[120:123]
	v_mfma_f32_16x16x32_bf16 v[104:107], v[174:177], v[198:201], v[104:107]
	v_mfma_f32_16x16x32_bf16 v[96:99], v[182:185], v[198:201], v[96:99]
	v_mfma_f32_16x16x32_bf16 v[88:91], v[174:177], v[206:209], v[88:91]
	v_mfma_f32_16x16x32_bf16 v[80:83], v[182:185], v[206:209], v[80:83]
	v_mfma_f32_16x16x32_bf16 v[72:75], v[174:177], v[214:217], v[72:75]
	v_mfma_f32_16x16x32_bf16 v[64:67], v[182:185], v[214:217], v[64:67]
	s_barrier
	s_setprio 0
	s_add_i32 s34, s64, s36
	v_lshl_add_u64 v[144:145], v[144:145], 0, s[12:13]
	s_mov_b32 m0, s34
	s_nop 0
	global_load_lds_dwordx4 v[144:145], off
	s_add_i32 m0, s34, 0x2000
	s_add_u32 s30, s30, 0x40080
	v_lshl_add_u64 v[144:145], v[218:219], 0, s[12:13]
	s_addc_u32 s31, s31, 0
	s_add_i32 s34, s65, s36
	global_load_lds_dwordx4 v[144:145], off
	v_lshl_add_u64 v[144:145], s[30:31], 0, v[132:133]
	s_mov_b32 m0, s34
	s_nop 0
	global_load_lds_dwordx4 v[144:145], off
	v_lshl_add_u64 v[144:145], s[30:31], 0, v[128:129]
	s_add_i32 m0, s34, 0x2000
	s_nop 0
	global_load_lds_dwordx4 v[144:145], off
	v_lshl_add_u64 v[144:145], v[220:221], 0, s[12:13]
	s_mov_b32 m0, s42
	s_nop 0
	global_load_lds_dwordx4 v[144:145], off
	v_lshl_add_u64 v[144:145], v[222:223], 0, s[12:13]
	s_mov_b32 m0, s43
	s_nop 0
	global_load_lds_dwordx4 v[144:145], off
	ds_read_b128 v[186:189], v151 offset:49152
	ds_read_b128 v[190:193], v151 offset:50176
	ds_read_b128 v[194:197], v151 offset:51200
	ds_read_b128 v[198:201], v151 offset:52224
	ds_read_b128 v[202:205], v151 offset:53248
	ds_read_b128 v[206:209], v151 offset:54272
	ds_read_b128 v[210:213], v151 offset:55296
	ds_read_b128 v[214:217], v151 offset:56320
	s_waitcnt vmcnt(8)
	s_waitcnt lgkmcnt(0)
	s_setprio 1
	s_barrier
	v_mfma_f32_16x16x32_bf16 v[60:63], v[154:157], v[186:189], v[60:63]
	v_mfma_f32_16x16x32_bf16 v[52:55], v[162:165], v[186:189], v[52:55]
	v_mfma_f32_16x16x32_bf16 v[44:47], v[154:157], v[194:197], v[44:47]
	v_mfma_f32_16x16x32_bf16 v[36:39], v[162:165], v[194:197], v[36:39]
	v_mfma_f32_16x16x32_bf16 v[28:31], v[154:157], v[202:205], v[28:31]
	v_mfma_f32_16x16x32_bf16 v[20:23], v[162:165], v[202:205], v[20:23]
	v_mfma_f32_16x16x32_bf16 v[12:15], v[154:157], v[210:213], v[12:15]
	v_mfma_f32_16x16x32_bf16 v[4:7], v[162:165], v[210:213], v[4:7]
	v_mfma_f32_16x16x32_bf16 v[60:63], v[158:161], v[190:193], v[60:63]
	v_mfma_f32_16x16x32_bf16 v[52:55], v[166:169], v[190:193], v[52:55]
	v_mfma_f32_16x16x32_bf16 v[44:47], v[158:161], v[198:201], v[44:47]
	v_mfma_f32_16x16x32_bf16 v[36:39], v[166:169], v[198:201], v[36:39]
	v_mfma_f32_16x16x32_bf16 v[28:31], v[158:161], v[206:209], v[28:31]
	v_mfma_f32_16x16x32_bf16 v[20:23], v[166:169], v[206:209], v[20:23]
	v_mfma_f32_16x16x32_bf16 v[12:15], v[158:161], v[214:217], v[12:15]
	v_mfma_f32_16x16x32_bf16 v[4:7], v[166:169], v[214:217], v[4:7]
	s_setprio 0
	s_setprio 1
	v_mfma_f32_16x16x32_bf16 v[56:59], v[170:173], v[186:189], v[56:59]
	v_mfma_f32_16x16x32_bf16 v[48:51], v[178:181], v[186:189], v[48:51]
	v_mfma_f32_16x16x32_bf16 v[40:43], v[170:173], v[194:197], v[40:43]
	v_mfma_f32_16x16x32_bf16 v[32:35], v[178:181], v[194:197], v[32:35]
	v_mfma_f32_16x16x32_bf16 v[24:27], v[170:173], v[202:205], v[24:27]
	v_mfma_f32_16x16x32_bf16 v[16:19], v[178:181], v[202:205], v[16:19]
	v_mfma_f32_16x16x32_bf16 v[8:11], v[170:173], v[210:213], v[8:11]
	v_mfma_f32_16x16x32_bf16 v[0:3], v[178:181], v[210:213], v[0:3]
	v_mfma_f32_16x16x32_bf16 v[56:59], v[174:177], v[190:193], v[56:59]
	v_mfma_f32_16x16x32_bf16 v[48:51], v[182:185], v[190:193], v[48:51]
	v_mfma_f32_16x16x32_bf16 v[40:43], v[174:177], v[198:201], v[40:43]
	v_mfma_f32_16x16x32_bf16 v[32:35], v[182:185], v[198:201], v[32:35]
	v_mfma_f32_16x16x32_bf16 v[24:27], v[174:177], v[206:209], v[24:27]
	v_mfma_f32_16x16x32_bf16 v[16:19], v[182:185], v[206:209], v[16:19]
	v_mfma_f32_16x16x32_bf16 v[8:11], v[174:177], v[214:217], v[8:11]
	v_mfma_f32_16x16x32_bf16 v[0:3], v[182:185], v[214:217], v[0:3]
	s_barrier
	s_setprio 0
	s_add_i32 s63, s63, 2
	s_add_u32 s28, s28, 0x100
	s_addc_u32 s29, s29, 0
	s_add_u32 s61, s61, 0x100
	s_addc_u32 s62, s62, 0
	s_cmp_gt_u32 s63, 13
	s_cbranch_scc0 .LBB0_555
	s_and_b64 vcc, exec, s[14:15]
	s_cbranch_vccz .LBB0_558
	s_barrier
.LBB0_558:
	v_lshl_add_u32 v144, s26, 8, v146
	v_mov_b32_e32 v145, v230
	v_mov_b32_e32 v153, v231
	v_lshl_or_b32 v156, s24, 7, v148
	v_ashrrev_i32_e32 v157, 31, v156
	v_mul_f32_e32 v162, v108, v104
	v_mul_f32_e32 v163, v109, v105
	v_lshlrev_b64 v[104:105], 1, v[156:157]
	v_mov_b32_e32 v156, v232
	v_mov_b32_e32 v157, v233
	v_mov_b32_e32 v165, v234
	v_mov_b32_e32 v166, v235
	v_mov_b32_e32 v167, v236
	v_mul_f32_e32 v164, v110, v106
	v_mov_b32_e32 v106, v237
	s_and_b64 s[98:99], s[6:7], exec
	s_cselect_b32 s98, s18, s26
	v_lshl_add_u32 v238, s98, 8, v146
	v_ashrrev_i32_e32 v239, 31, v238
	v_lshl_add_u64 v[238:239], v[238:239], 2, s[8:9]
	global_load_dword v230, v[238:239], off sc1
	global_load_dword v231, v[238:239], off offset:64 sc1
	global_load_dword v232, v[238:239], off offset:128 sc1
	global_load_dword v233, v[238:239], off offset:192 sc1
	global_load_dword v234, v[238:239], off offset:512 sc1
	global_load_dword v235, v[238:239], off offset:576 sc1
	global_load_dword v236, v[238:239], off offset:640 sc1
	global_load_dword v237, v[238:239], off offset:704 sc1
	v_mul_f32_e32 v124, v116, v124
	v_mul_f32_e32 v125, v117, v125
	v_mul_f32_e32 v126, v118, v126
	v_mul_f32_e32 v127, v119, v127
	v_mul_f32_e32 v158, v112, v120
	v_mul_f32_e32 v159, v113, v121
	v_mul_f32_e32 v160, v114, v122
	v_mul_f32_e32 v161, v115, v123
	v_mul_f32_e32 v107, v111, v107
	v_mov_b64_e32 v[120:121], s[56:57]
	v_mad_i64_i32 v[122:123], s[28:29], v144, s50, v[120:121]
	v_lshl_add_u64 v[122:123], v[122:123], 0, v[104:105]
	v_mul_f32_e32 v96, v100, v96
	v_mul_f32_e32 v98, v102, v98
	v_mul_f32_e32 v88, v92, v88
	v_mul_f32_e32 v89, v93, v89
	v_mul_f32_e32 v90, v94, v90
	v_mul_f32_e32 v91, v95, v91
	v_mul_f32_e32 v80, v84, v80
	v_mul_f32_e32 v82, v86, v82
	v_mul_f32_e32 v72, v76, v72
	v_mul_f32_e32 v73, v77, v73
	v_mul_f32_e32 v74, v78, v74
	v_mul_f32_e32 v75, v79, v75
	v_mul_f32_e32 v64, v68, v64
	v_mul_f32_e32 v66, v70, v66
	v_mul_f32_e32 v56, v60, v56
	v_mul_f32_e32 v57, v61, v57
	v_mul_f32_e32 v58, v62, v58
	v_mul_f32_e32 v59, v63, v59
	v_mul_f32_e32 v48, v52, v48
	v_mul_f32_e32 v50, v54, v50
	v_mul_f32_e32 v40, v44, v40
	v_mul_f32_e32 v41, v45, v41
	v_mul_f32_e32 v42, v46, v42
	v_mul_f32_e32 v43, v47, v43
	v_mul_f32_e32 v32, v36, v32
	v_mul_f32_e32 v34, v38, v34
	v_mul_f32_e32 v24, v28, v24
	v_mul_f32_e32 v25, v29, v25
	v_mul_f32_e32 v26, v30, v26
	v_mul_f32_e32 v27, v31, v27
	v_mul_f32_e32 v16, v20, v16
	v_mul_f32_e32 v18, v22, v18
	v_mul_f32_e32 v8, v12, v8
	v_mul_f32_e32 v9, v13, v9
	v_mul_f32_e32 v10, v14, v10
	v_mul_f32_e32 v11, v15, v11
	v_mul_f32_e32 v0, v4, v0
	v_mul_f32_e32 v2, v6, v2
	s_andn2_b64 vcc, exec, s[6:7]
	s_mov_b64 s[6:7], -1
	v_fmamk_f32 v145, v145, 0x3a800000, v152
	v_fmamk_f32 v153, v153, 0x3a800000, v152
	v_rsq_f32_e32 v168, v145
	v_rsq_f32_e32 v169, v153
	v_mul_f32_e32 v154, 0xbfb8aa3b, v168
	v_mul_f32_e32 v155, 0xbfb8aa3b, v169
	v_mul_f32_e32 v116, v116, v154
	v_mul_f32_e32 v117, v117, v154
	v_mul_f32_e32 v118, v118, v154
	v_mul_f32_e32 v119, v119, v154
	v_mul_f32_e32 v112, v112, v154
	v_mul_f32_e32 v113, v113, v154
	v_mul_f32_e32 v114, v114, v154
	v_mul_f32_e32 v115, v115, v154
	v_mul_f32_e32 v108, v108, v155
	v_mul_f32_e32 v109, v109, v155
	v_mul_f32_e32 v110, v110, v155
	v_exp_f32_e32 v116, v116
	v_exp_f32_e32 v117, v117
	v_exp_f32_e32 v118, v118
	v_exp_f32_e32 v119, v119
	v_exp_f32_e32 v112, v112
	v_exp_f32_e32 v113, v113
	v_exp_f32_e32 v114, v114
	v_exp_f32_e32 v115, v115
	v_exp_f32_e32 v108, v108
	v_exp_f32_e32 v109, v109
	v_exp_f32_e32 v110, v110
	v_mul_f32_e32 v111, v111, v155
	v_exp_f32_e32 v111, v111
	v_fma_f32 v116, v145, v116, v145
	v_fma_f32 v117, v145, v117, v145
	v_fma_f32 v118, v145, v118, v145
	v_fma_f32 v119, v145, v119, v145
	v_fma_f32 v112, v145, v112, v145
	v_fma_f32 v113, v145, v113, v145
	v_fma_f32 v114, v145, v114, v145
	v_fmac_f32_e32 v145, v145, v115
	v_fma_f32 v108, v153, v108, v153
	v_fma_f32 v109, v153, v109, v153
	v_mul_f32_e32 v154, v100, v155
	v_fma_f32 v110, v153, v110, v153
	v_rcp_f32_e32 v115, v116
	v_rcp_f32_e32 v116, v117
	v_rcp_f32_e32 v117, v118
	v_rcp_f32_e32 v118, v119
	v_rcp_f32_e32 v119, v145
	v_rcp_f32_e32 v108, v108
	v_rcp_f32_e32 v109, v109
	v_exp_f32_e32 v154, v154
	v_rcp_f32_e32 v112, v112
	v_rcp_f32_e32 v113, v113
	v_rcp_f32_e32 v114, v114
	v_rcp_f32_e32 v110, v110
	v_fma_f32 v111, v153, v111, v153
	v_rcp_f32_e32 v145, v111
	v_mul_f32_e32 v111, v124, v115
	v_mul_f32_e32 v115, v125, v116
	v_mul_f32_e32 v116, v126, v117
	v_mul_f32_e32 v117, v127, v118
	v_mul_f32_e32 v118, v161, v119
	v_mul_f32_e32 v119, v162, v108
	v_mul_f32_e32 v124, v163, v109
	v_cvt_pk_bf16_f32 v108, v111, v115
	v_cvt_pk_bf16_f32 v109, v116, v117
	v_mul_f32_e32 v112, v158, v112
	v_mul_f32_e32 v113, v159, v113
	v_mul_f32_e32 v114, v160, v114
	v_mul_f32_e32 v125, v164, v110
	v_cvt_pk_bf16_f32 v110, v112, v113
	v_cvt_pk_bf16_f32 v111, v114, v118
	global_store_dwordx4 v[122:123], v[108:111], off
	v_mul_f32_e32 v107, v107, v145
	s_nop 0
	v_fma_f32 v108, v153, v154, v153
	v_mul_f32_e32 v109, v101, v155
	v_rcp_f32_e32 v108, v108
	v_exp_f32_e32 v109, v109
	v_mul_f32_e32 v100, v96, v108
	v_mul_f32_e32 v96, v101, v97
	v_fma_f32 v97, v153, v109, v153
	v_mul_f32_e32 v101, v102, v155
	v_rcp_f32_e32 v97, v97
	v_exp_f32_e32 v101, v101
	v_mul_f32_e32 v108, v103, v155
	v_exp_f32_e32 v108, v108
	v_mul_f32_e32 v109, v96, v97
	v_fma_f32 v96, v153, v101, v153
	v_rcp_f32_e32 v96, v96
	v_fmac_f32_e32 v153, v153, v108
	v_rcp_f32_e32 v97, v153
	v_or_b32_e32 v102, 16, v144
	v_mul_f32_e32 v101, v98, v96
	v_mul_f32_e32 v96, v103, v99
	v_fmamk_f32 v103, v156, 0x3a800000, v152
	v_mul_f32_e32 v99, v96, v97
	v_cvt_pk_bf16_f32 v96, v119, v124
	v_cvt_pk_bf16_f32 v97, v125, v107
	v_rsq_f32_e32 v107, v103
	v_cvt_pk_bf16_f32 v98, v100, v109
	v_cvt_pk_bf16_f32 v99, v101, v99
	v_mad_i64_i32 v[100:101], s[28:29], v102, s50, v[120:121]
	v_mul_f32_e32 v102, 0xbfb8aa3b, v107
	v_mul_f32_e32 v107, v92, v102
	v_mul_f32_e32 v108, v93, v102
	v_mul_f32_e32 v92, v94, v102
	v_mul_f32_e32 v93, v95, v102
	v_exp_f32_e32 v92, v92
	v_exp_f32_e32 v93, v93
	v_mul_f32_e32 v94, v84, v102
	v_exp_f32_e32 v94, v94
	v_fma_f32 v92, v103, v92, v103
	v_fma_f32 v93, v103, v93, v103
	v_rcp_f32_e32 v92, v92
	v_rcp_f32_e32 v93, v93
	v_exp_f32_e32 v107, v107
	v_exp_f32_e32 v108, v108
	v_mul_f32_e32 v90, v90, v92
	v_mul_f32_e32 v91, v91, v93
	v_fma_f32 v92, v103, v94, v103
	v_mul_f32_e32 v93, v85, v102
	v_rcp_f32_e32 v92, v92
	v_exp_f32_e32 v93, v93
	v_lshl_add_u64 v[100:101], v[100:101], 0, v[104:105]
	global_store_dwordx4 v[100:101], v[96:99], off
	v_mul_f32_e32 v84, v80, v92
	v_mul_f32_e32 v80, v85, v81
	v_fma_f32 v81, v103, v93, v103
	v_mul_f32_e32 v85, v86, v102
	v_rcp_f32_e32 v81, v81
	v_exp_f32_e32 v85, v85
	v_mul_f32_e32 v92, v87, v102
	v_exp_f32_e32 v92, v92
	v_fma_f32 v96, v103, v107, v103
	v_mul_f32_e32 v93, v80, v81
	v_fma_f32 v80, v103, v85, v103
	v_rcp_f32_e32 v96, v96
	v_fma_f32 v97, v103, v108, v103
	v_rcp_f32_e32 v80, v80
	v_fmac_f32_e32 v103, v103, v92
	v_rcp_f32_e32 v97, v97
	v_rcp_f32_e32 v81, v103
	v_mul_f32_e32 v88, v88, v96
	v_mul_f32_e32 v85, v82, v80
	v_mul_f32_e32 v80, v87, v83
	v_fmamk_f32 v87, v157, 0x3a800000, v152
	v_mul_f32_e32 v89, v89, v97
	v_mul_f32_e32 v83, v80, v81
	v_cvt_pk_bf16_f32 v80, v88, v89
	v_rsq_f32_e32 v88, v87
	v_or_b32_e32 v86, 32, v144
	v_cvt_pk_bf16_f32 v81, v90, v91
	v_cvt_pk_bf16_f32 v82, v84, v93
	v_cvt_pk_bf16_f32 v83, v85, v83
	v_mad_i64_i32 v[84:85], s[28:29], v86, s50, v[120:121]
	v_mul_f32_e32 v86, 0xbfb8aa3b, v88
	v_mul_f32_e32 v88, v76, v86
	v_mul_f32_e32 v89, v77, v86
	v_mul_f32_e32 v76, v78, v86
	v_mul_f32_e32 v77, v79, v86
	v_exp_f32_e32 v76, v76
	v_exp_f32_e32 v77, v77
	v_mul_f32_e32 v78, v68, v86
	v_exp_f32_e32 v78, v78
	v_fma_f32 v76, v87, v76, v87
	v_fma_f32 v77, v87, v77, v87
	v_rcp_f32_e32 v76, v76
	v_rcp_f32_e32 v77, v77
	v_exp_f32_e32 v88, v88
	v_exp_f32_e32 v89, v89
	v_mul_f32_e32 v74, v74, v76
	v_mul_f32_e32 v75, v75, v77
	v_fma_f32 v76, v87, v78, v87
	v_mul_f32_e32 v77, v69, v86
	v_rcp_f32_e32 v76, v76
	v_exp_f32_e32 v77, v77
	v_lshl_add_u64 v[84:85], v[84:85], 0, v[104:105]
	global_store_dwordx4 v[84:85], v[80:83], off
	v_mul_f32_e32 v68, v64, v76
	v_mul_f32_e32 v64, v69, v65
	v_fma_f32 v65, v87, v77, v87
	v_mul_f32_e32 v69, v70, v86
	v_rcp_f32_e32 v65, v65
	v_exp_f32_e32 v69, v69
	v_mul_f32_e32 v76, v71, v86
	v_exp_f32_e32 v76, v76
	v_fma_f32 v80, v87, v88, v87
	v_mul_f32_e32 v77, v64, v65
	v_fma_f32 v64, v87, v69, v87
	v_rcp_f32_e32 v80, v80
	v_fma_f32 v81, v87, v89, v87
	v_rcp_f32_e32 v64, v64
	v_fmac_f32_e32 v87, v87, v76
	v_rcp_f32_e32 v81, v81
	v_rcp_f32_e32 v65, v87
	v_mul_f32_e32 v72, v72, v80
	v_mul_f32_e32 v69, v66, v64
	v_mul_f32_e32 v64, v71, v67
	v_fmamk_f32 v71, v165, 0x3a800000, v152
	v_mul_f32_e32 v73, v73, v81
	v_mul_f32_e32 v67, v64, v65
	v_cvt_pk_bf16_f32 v64, v72, v73
	v_rsq_f32_e32 v72, v71
	v_or_b32_e32 v70, 48, v144
	v_cvt_pk_bf16_f32 v65, v74, v75
	v_cvt_pk_bf16_f32 v66, v68, v77
	v_cvt_pk_bf16_f32 v67, v69, v67
	v_mad_i64_i32 v[68:69], s[28:29], v70, s50, v[120:121]
	v_lshl_add_u64 v[68:69], v[68:69], 0, v[104:105]
	global_store_dwordx4 v[68:69], v[64:67], off
	s_nop 1
	v_mul_f32_e32 v64, 0xbfb8aa3b, v72
	v_mul_f32_e32 v65, v60, v64
	v_mul_f32_e32 v66, v61, v64
	v_mul_f32_e32 v60, v62, v64
	v_mul_f32_e32 v61, v63, v64
	v_exp_f32_e32 v60, v60
	v_exp_f32_e32 v61, v61
	v_mul_f32_e32 v62, v52, v64
	v_exp_f32_e32 v62, v62
	v_fma_f32 v60, v71, v60, v71
	v_fma_f32 v61, v71, v61, v71
	v_rcp_f32_e32 v60, v60
	v_rcp_f32_e32 v61, v61
	v_exp_f32_e32 v65, v65
	v_exp_f32_e32 v66, v66
	v_mul_f32_e32 v58, v58, v60
	v_mul_f32_e32 v59, v59, v61
	v_fma_f32 v60, v71, v62, v71
	v_mul_f32_e32 v61, v53, v64
	v_rcp_f32_e32 v60, v60
	v_exp_f32_e32 v61, v61
	v_fma_f32 v65, v71, v65, v71
	v_fma_f32 v66, v71, v66, v71
	v_mul_f32_e32 v52, v48, v60
	v_mul_f32_e32 v48, v53, v49
	v_fma_f32 v49, v71, v61, v71
	v_mul_f32_e32 v53, v54, v64
	v_rcp_f32_e32 v49, v49
	v_exp_f32_e32 v53, v53
	v_mul_f32_e32 v60, v55, v64
	v_exp_f32_e32 v60, v60
	v_mul_f32_e32 v61, v48, v49
	v_fma_f32 v48, v71, v53, v71
	v_rcp_f32_e32 v48, v48
	v_fmamk_f32 v54, v166, 0x3a800000, v152
	v_rcp_f32_e32 v65, v65
	v_rcp_f32_e32 v66, v66
	v_fmac_f32_e32 v71, v71, v60
	v_mul_f32_e32 v53, v50, v48
	v_mul_f32_e32 v48, v55, v51
	v_rsq_f32_e32 v55, v54
	v_rcp_f32_e32 v49, v71
	v_mul_f32_e32 v56, v56, v65
	v_mul_f32_e32 v57, v57, v66
	v_mul_f32_e32 v55, 0xbfb8aa3b, v55
	v_mul_f32_e32 v51, v48, v49
	v_cvt_pk_bf16_f32 v48, v56, v57
	v_mul_f32_e32 v56, v44, v55
	v_mul_f32_e32 v57, v45, v55
	v_mul_f32_e32 v44, v46, v55
	v_mul_f32_e32 v45, v47, v55
	v_exp_f32_e32 v44, v44
	v_exp_f32_e32 v45, v45
	v_mul_f32_e32 v46, v36, v55
	v_exp_f32_e32 v46, v46
	v_fma_f32 v44, v54, v44, v54
	v_fma_f32 v45, v54, v45, v54
	v_rcp_f32_e32 v44, v44
	v_rcp_f32_e32 v45, v45
	v_exp_f32_e32 v56, v56
	v_add_u32_e32 v67, 0x80, v144
	v_mul_f32_e32 v42, v42, v44
	v_mul_f32_e32 v43, v43, v45
	v_fma_f32 v44, v54, v46, v54
	v_mul_f32_e32 v45, v37, v55
	v_rcp_f32_e32 v44, v44
	v_exp_f32_e32 v45, v45
	v_exp_f32_e32 v57, v57
	v_cvt_pk_bf16_f32 v49, v58, v59
	v_mul_f32_e32 v36, v32, v44
	v_mul_f32_e32 v32, v37, v33
	v_fma_f32 v33, v54, v45, v54
	v_mul_f32_e32 v37, v38, v55
	v_rcp_f32_e32 v33, v33
	v_exp_f32_e32 v37, v37
	v_mul_f32_e32 v44, v39, v55
	v_exp_f32_e32 v44, v44
	v_cvt_pk_bf16_f32 v50, v52, v61
	v_cvt_pk_bf16_f32 v51, v53, v51
	v_mad_i64_i32 v[52:53], s[28:29], v67, s50, v[120:121]
	v_lshl_add_u64 v[52:53], v[52:53], 0, v[104:105]
	global_store_dwordx4 v[52:53], v[48:51], off
	v_mul_f32_e32 v45, v32, v33
	v_fma_f32 v32, v54, v37, v54
	v_fma_f32 v48, v54, v56, v54
	v_rcp_f32_e32 v48, v48
	v_fma_f32 v49, v54, v57, v54
	v_rcp_f32_e32 v32, v32
	v_fmac_f32_e32 v54, v54, v44
	v_rcp_f32_e32 v49, v49
	v_rcp_f32_e32 v33, v54
	v_mul_f32_e32 v40, v40, v48
	v_mul_f32_e32 v37, v34, v32
	v_mul_f32_e32 v32, v39, v35
	v_fmamk_f32 v39, v167, 0x3a800000, v152
	v_mul_f32_e32 v41, v41, v49
	v_mul_f32_e32 v35, v32, v33
	v_cvt_pk_bf16_f32 v32, v40, v41
	v_rsq_f32_e32 v40, v39
	v_add_u32_e32 v38, 0x90, v144
	v_cvt_pk_bf16_f32 v33, v42, v43
	v_cvt_pk_bf16_f32 v34, v36, v45
	v_cvt_pk_bf16_f32 v35, v37, v35
	v_mad_i64_i32 v[36:37], s[28:29], v38, s50, v[120:121]
	v_mul_f32_e32 v38, 0xbfb8aa3b, v40
	v_mul_f32_e32 v40, v28, v38
	v_mul_f32_e32 v41, v29, v38
	v_mul_f32_e32 v28, v30, v38
	v_mul_f32_e32 v29, v31, v38
	v_exp_f32_e32 v28, v28
	v_exp_f32_e32 v29, v29
	v_mul_f32_e32 v30, v20, v38
	v_exp_f32_e32 v30, v30
	v_fma_f32 v28, v39, v28, v39
	v_fma_f32 v29, v39, v29, v39
	v_rcp_f32_e32 v28, v28
	v_rcp_f32_e32 v29, v29
	v_exp_f32_e32 v40, v40
	v_exp_f32_e32 v41, v41
	v_mul_f32_e32 v26, v26, v28
	v_mul_f32_e32 v27, v27, v29
	v_fma_f32 v28, v39, v30, v39
	v_mul_f32_e32 v29, v21, v38
	v_rcp_f32_e32 v28, v28
	v_exp_f32_e32 v29, v29
	v_lshl_add_u64 v[36:37], v[36:37], 0, v[104:105]
	global_store_dwordx4 v[36:37], v[32:35], off
	v_mul_f32_e32 v20, v16, v28
	v_mul_f32_e32 v16, v21, v17
	v_fma_f32 v17, v39, v29, v39
	v_mul_f32_e32 v21, v22, v38
	v_rcp_f32_e32 v17, v17
	v_exp_f32_e32 v21, v21
	v_mul_f32_e32 v28, v23, v38
	v_exp_f32_e32 v28, v28
	v_fma_f32 v32, v39, v40, v39
	v_mul_f32_e32 v29, v16, v17
	v_fma_f32 v16, v39, v21, v39
	v_rcp_f32_e32 v32, v32
	v_fma_f32 v33, v39, v41, v39
	v_rcp_f32_e32 v16, v16
	v_fmac_f32_e32 v39, v39, v28
	v_rcp_f32_e32 v33, v33
	v_rcp_f32_e32 v17, v39
	v_mul_f32_e32 v24, v24, v32
	v_mul_f32_e32 v21, v18, v16
	v_mul_f32_e32 v16, v23, v19
	v_fmamk_f32 v23, v106, 0x3a800000, v152
	v_mul_f32_e32 v25, v25, v33
	v_mul_f32_e32 v19, v16, v17
	v_cvt_pk_bf16_f32 v16, v24, v25
	v_rsq_f32_e32 v24, v23
	v_add_u32_e32 v22, 0xa0, v144
	v_cvt_pk_bf16_f32 v17, v26, v27
	v_cvt_pk_bf16_f32 v18, v20, v29
	v_cvt_pk_bf16_f32 v19, v21, v19
	v_mad_i64_i32 v[20:21], s[28:29], v22, s50, v[120:121]
	v_mul_f32_e32 v22, 0xbfb8aa3b, v24
	v_mul_f32_e32 v24, v12, v22
	v_mul_f32_e32 v25, v13, v22
	v_mul_f32_e32 v12, v14, v22
	v_mul_f32_e32 v13, v15, v22
	v_exp_f32_e32 v12, v12
	v_exp_f32_e32 v13, v13
	v_mul_f32_e32 v14, v4, v22
	v_exp_f32_e32 v14, v14
	v_fma_f32 v12, v23, v12, v23
	v_fma_f32 v13, v23, v13, v23
	v_rcp_f32_e32 v12, v12
	v_rcp_f32_e32 v13, v13
	v_exp_f32_e32 v24, v24
	v_exp_f32_e32 v25, v25
	v_mul_f32_e32 v10, v10, v12
	v_mul_f32_e32 v11, v11, v13
	v_fma_f32 v12, v23, v14, v23
	v_mul_f32_e32 v13, v5, v22
	v_rcp_f32_e32 v12, v12
	v_exp_f32_e32 v13, v13
	v_lshl_add_u64 v[20:21], v[20:21], 0, v[104:105]
	global_store_dwordx4 v[20:21], v[16:19], off
	v_mul_f32_e32 v4, v0, v12
	v_mul_f32_e32 v0, v5, v1
	v_fma_f32 v1, v23, v13, v23
	v_mul_f32_e32 v5, v6, v22
	v_rcp_f32_e32 v1, v1
	v_exp_f32_e32 v5, v5
	v_mul_f32_e32 v12, v7, v22
	v_exp_f32_e32 v12, v12
	v_mul_f32_e32 v13, v0, v1
	v_fma_f32 v0, v23, v5, v23
	v_fma_f32 v16, v23, v24, v23
	v_fma_f32 v17, v23, v25, v23
	v_rcp_f32_e32 v0, v0
	v_fmac_f32_e32 v23, v23, v12
	v_rcp_f32_e32 v1, v23
	v_rcp_f32_e32 v16, v16
	v_rcp_f32_e32 v17, v17
	v_mul_f32_e32 v5, v2, v0
	v_mul_f32_e32 v0, v7, v3
	v_mul_f32_e32 v3, v0, v1
	v_add_u32_e32 v6, 0xb0, v144
	v_mul_f32_e32 v8, v8, v16
	v_mul_f32_e32 v9, v9, v17
	v_cvt_pk_bf16_f32 v0, v8, v9
	v_cvt_pk_bf16_f32 v1, v10, v11
	v_cvt_pk_bf16_f32 v2, v4, v13
	v_cvt_pk_bf16_f32 v3, v5, v3
	v_mad_i64_i32 v[4:5], s[28:29], v6, s50, v[120:121]
	v_lshl_add_u64 v[4:5], v[4:5], 0, v[104:105]
	global_store_dwordx4 v[4:5], v[0:3], off
	s_cbranch_vccnz .LBB0_551
	s_mov_b32 s101, 0
	s_andn2_b64 vcc, exec, s[10:11]
	s_cbranch_vccnz .LBB0_550
	s_mov_b32 s101, 1
	s_branch .LBB0_550

.LBB0_623:
	s_lshl_b32 s9, s9, 5
	s_mov_b64 s[14:15], 0x80
	s_and_b32 s37, s9, 0x60
	s_add_i32 m0, s29, 0x18000
	v_lshl_add_u64 v[6:7], v[6:7], 0, s[14:15]
	s_lshl_b32 s36, s7, 6
	s_lshl_b32 s7, s7, 13
	s_lshl_b32 s9, s37, 7
	s_waitcnt vmcnt(2)
	s_barrier
	global_load_lds_dwordx4 v[6:7], off
	v_lshl_add_u64 v[4:5], v[4:5], 0, s[14:15]
	s_add_i32 m0, s29, 0x1a000
	s_add_i32 s38, s29, 0x8000
	s_add_i32 s39, s29, 0xa000
	global_load_lds_dwordx4 v[4:5], off
	v_lshl_add_u64 v[0:1], v[0:1], 0, s[14:15]
	s_mov_b32 m0, s38
	s_add_u32 s16, s22, 0xb0080
	global_load_lds_dwordx4 v[0:1], off
	v_lshl_add_u64 v[0:1], v[2:3], 0, s[14:15]
	s_mov_b32 m0, s39
	s_addc_u32 s17, s23, 0
	global_load_lds_dwordx4 v[0:1], off
	s_add_i32 m0, s29, 0x1c000
	v_lshl_add_u64 v[0:1], s[16:17], 0, v[194:195]
	global_load_lds_dwordx4 v[0:1], off
	v_lshl_add_u64 v[0:1], s[16:17], 0, v[198:199]
	s_add_i32 m0, s29, 0x1e000
	v_bfe_u32 v244, v8, 4, 2
	global_load_lds_dwordx4 v[0:1], off
	v_and_b32_e32 v245, 15, v8
	v_lshlrev_b32_e32 v0, 4, v244
	v_lshlrev_b32_e32 v1, 2, v8
	v_lshl_or_b32 v0, v245, 6, v0
	v_and_b32_e32 v1, 32, v1
	v_bitop3_b32 v2, v0, s7, v1 bitop3:0xde
	v_bitop3_b32 v246, v0, s9, v1 bitop3:0xde
	v_lshrrev_b32_e32 v1, 1, v9
	v_mul_lo_u32 v0, v11, s6
	s_mov_b32 s7, 0xb000
	s_cmpk_lt_u32 s8, 0x100
	v_mad_u64_u32 v[0:1], s[8:9], v1, s7, v[0:1]
	v_or_b32_e32 v0, v0, v10
	s_mov_b64 s[18:19], 0xb0080
	v_add_lshl_u32 v0, v0, v12, 1
	v_mov_b32_e32 v1, v195
	v_lshl_add_u64 v[200:201], v[0:1], 0, s[18:19]
	v_lshrrev_b32_e32 v1, 1, v13
	v_mul_lo_u32 v0, v14, s6
	v_mad_u64_u32 v[0:1], s[6:7], v1, s7, v[0:1]
	s_waitcnt vmcnt(6)
	v_or_b32_e32 v0, v0, v15
	s_cselect_b64 s[16:17], -1, 0
	v_add_lshl_u32 v0, v0, v16, 1
	v_mov_b32_e32 v1, v195
	s_add_i32 s43, 0, 0x10000
	s_add_i32 s46, 0, 0x14000
	s_ashr_i32 s40, s52, 31
	s_mov_b32 s41, s52
	s_ashr_i32 s42, s33, 31
	v_lshl_add_u64 v[202:203], v[0:1], 0, s[18:19]
	v_mov_b64_e32 v[204:205], 0x1ff
	v_add_u32_e32 v247, s43, v246
	v_add_u32_e32 v248, s46, v246
	v_add_u32_e32 v249, 0, v2
	s_barrier
	s_mov_b32 s101, 0
	s_branch .LBB0_626

.LBB0_636:
	s_add_u32 s51, s22, 0x100
	v_mov_b32_e32 v0, 0
	s_addc_u32 s60, s23, 0
	s_mov_b32 s61, -2
	s_waitcnt vmcnt(0)
	s_cmp_lg_u32 s101, 0
	s_cbranch_scc0 .Lph637_a
	v_mov_b32_e32 v1, v0
	v_mov_b32_e32 v2, v0
	v_mov_b32_e32 v3, v0
	v_mov_b32_e32 v4, v0
	v_mov_b32_e32 v5, v0
	v_mov_b32_e32 v6, v0
	v_mov_b32_e32 v7, v0
	v_mov_b32_e32 v16, v0
	v_mov_b32_e32 v17, v0
	v_mov_b32_e32 v18, v0
	v_mov_b32_e32 v19, v0
	v_mov_b32_e32 v20, v0
	v_mov_b32_e32 v21, v0
	v_mov_b32_e32 v22, v0
	v_mov_b32_e32 v23, v0
	v_mov_b32_e32 v32, v0
	v_mov_b32_e32 v33, v0
	v_mov_b32_e32 v34, v0
	v_mov_b32_e32 v35, v0
	v_mov_b32_e32 v36, v0
	v_mov_b32_e32 v37, v0
	v_mov_b32_e32 v38, v0
	v_mov_b32_e32 v39, v0
	v_mov_b32_e32 v48, v0
	v_mov_b32_e32 v49, v0
	v_mov_b32_e32 v50, v0
	v_mov_b32_e32 v51, v0
	v_mov_b32_e32 v52, v0
	v_mov_b32_e32 v53, v0
	v_mov_b32_e32 v54, v0
	v_mov_b32_e32 v55, v0
	v_mov_b32_e32 v8, v0
	v_mov_b32_e32 v9, v0
	v_mov_b32_e32 v10, v0
	v_mov_b32_e32 v11, v0
	v_mov_b32_e32 v12, v0
	v_mov_b32_e32 v13, v0
	v_mov_b32_e32 v14, v0
	v_mov_b32_e32 v15, v0
	v_mov_b32_e32 v24, v0
	v_mov_b32_e32 v25, v0
	v_mov_b32_e32 v26, v0
	v_mov_b32_e32 v27, v0
	v_mov_b32_e32 v28, v0
	v_mov_b32_e32 v29, v0
	v_mov_b32_e32 v30, v0
	v_mov_b32_e32 v31, v0
	v_mov_b32_e32 v40, v0
	v_mov_b32_e32 v41, v0
	v_mov_b32_e32 v42, v0
	v_mov_b32_e32 v43, v0
	v_mov_b32_e32 v44, v0
	v_mov_b32_e32 v45, v0
	v_mov_b32_e32 v46, v0
	v_mov_b32_e32 v47, v0
	v_mov_b32_e32 v56, v0
	v_mov_b32_e32 v57, v0
	v_mov_b32_e32 v58, v0
	v_mov_b32_e32 v59, v0
	v_mov_b32_e32 v60, v0
	v_mov_b32_e32 v61, v0
	v_mov_b32_e32 v62, v0
	v_mov_b32_e32 v63, v0
	v_mov_b32_e32 v64, v0
	v_mov_b32_e32 v65, v0
	v_mov_b32_e32 v66, v0
	v_mov_b32_e32 v67, v0
	v_mov_b32_e32 v68, v0
	v_mov_b32_e32 v69, v0
	v_mov_b32_e32 v70, v0
	v_mov_b32_e32 v71, v0
	v_mov_b32_e32 v80, v0
	v_mov_b32_e32 v81, v0
	v_mov_b32_e32 v82, v0
	v_mov_b32_e32 v83, v0
	v_mov_b32_e32 v84, v0
	v_mov_b32_e32 v85, v0
	v_mov_b32_e32 v86, v0
	v_mov_b32_e32 v87, v0
	v_mov_b32_e32 v96, v0
	v_mov_b32_e32 v97, v0
	v_mov_b32_e32 v98, v0
	v_mov_b32_e32 v99, v0
	v_mov_b32_e32 v100, v0
	v_mov_b32_e32 v101, v0
	v_mov_b32_e32 v102, v0
	v_mov_b32_e32 v103, v0
	v_mov_b32_e32 v112, v0
	v_mov_b32_e32 v113, v0
	v_mov_b32_e32 v114, v0
	v_mov_b32_e32 v115, v0
	v_mov_b32_e32 v116, v0
	v_mov_b32_e32 v117, v0
	v_mov_b32_e32 v118, v0
	v_mov_b32_e32 v119, v0
	v_mov_b32_e32 v72, v0
	v_mov_b32_e32 v73, v0
	v_mov_b32_e32 v74, v0
	v_mov_b32_e32 v75, v0
	v_mov_b32_e32 v76, v0
	v_mov_b32_e32 v77, v0
	v_mov_b32_e32 v78, v0
	v_mov_b32_e32 v79, v0
	v_mov_b32_e32 v88, v0
	v_mov_b32_e32 v89, v0
	v_mov_b32_e32 v90, v0
	v_mov_b32_e32 v91, v0
	v_mov_b32_e32 v92, v0
	v_mov_b32_e32 v93, v0
	v_mov_b32_e32 v94, v0
	v_mov_b32_e32 v95, v0
	v_mov_b32_e32 v104, v0
	v_mov_b32_e32 v105, v0
	v_mov_b32_e32 v106, v0
	v_mov_b32_e32 v107, v0
	v_mov_b32_e32 v108, v0
	v_mov_b32_e32 v109, v0
	v_mov_b32_e32 v110, v0
	v_mov_b32_e32 v111, v0
	v_mov_b32_e32 v136, v0
	v_mov_b32_e32 v137, v0
	v_mov_b32_e32 v138, v0
	v_mov_b32_e32 v139, v0
	v_mov_b32_e32 v144, v0
	v_mov_b32_e32 v145, v0
	v_mov_b32_e32 v146, v0
	v_mov_b32_e32 v147, v0
	s_barrier
	s_mov_b32 s101, 0
	s_branch .LBB0_637
.Lph637_a:
	s_add_u32 s22, s20, 0x100
	s_addc_u32 s23, s21, 0
	s_cmp_eq_u32 s61, 40
	s_cselect_b32 s27, s9, s23
	s_cselect_b32 s26, s8, s22
	s_cselect_b32 s25, s19, s60
	s_cselect_b32 s24, s18, s51
	v_lshl_add_u64 v[206:207], s[20:21], 0, v[200:201]
	s_add_i32 m0, s29, 0xc000
	s_nop 0
	global_load_lds_dwordx4 v[206:207], off
	v_lshl_add_u64 v[206:207], s[20:21], 0, v[202:203]
	s_add_i32 m0, s29, 0xe000
	s_nop 0
	global_load_lds_dwordx4 v[206:207], off
	ds_read_b128 v[120:123], v247
	ds_read_b128 v[124:127], v247 offset:1024
	ds_read_b128 v[128:131], v247 offset:2048
	ds_read_b128 v[132:135], v247 offset:3072
	ds_read_b128 v[140:143], v248
	ds_read_b128 v[148:151], v248 offset:1024
	ds_read_b128 v[152:155], v248 offset:2048
	ds_read_b128 v[156:159], v248 offset:3072
	ds_read_b128 v[160:163], v249
	ds_read_b128 v[164:167], v249 offset:1024
	ds_read_b128 v[168:171], v249 offset:2048
	ds_read_b128 v[172:175], v249 offset:3072
	ds_read_b128 v[176:179], v249 offset:4096
	ds_read_b128 v[180:183], v249 offset:5120
	ds_read_b128 v[184:187], v249 offset:6144
	ds_read_b128 v[188:191], v249 offset:7168
	v_mov_b32_e32 v1, v0
	v_mov_b32_e32 v2, v0
	v_mov_b32_e32 v3, v0
	v_mov_b32_e32 v4, v0
	v_mov_b32_e32 v5, v0
	v_mov_b32_e32 v6, v0
	v_mov_b32_e32 v7, v0
	v_mov_b32_e32 v16, v0
	v_mov_b32_e32 v17, v0
	v_mov_b32_e32 v18, v0
	v_mov_b32_e32 v19, v0
	v_mov_b32_e32 v20, v0
	v_mov_b32_e32 v21, v0
	v_mov_b32_e32 v22, v0
	v_mov_b32_e32 v23, v0
	v_mov_b32_e32 v32, v0
	v_mov_b32_e32 v33, v0
	v_mov_b32_e32 v34, v0
	v_mov_b32_e32 v35, v0
	v_mov_b32_e32 v36, v0
	v_mov_b32_e32 v37, v0
	v_mov_b32_e32 v38, v0
	v_mov_b32_e32 v39, v0
	v_mov_b32_e32 v48, v0
	v_mov_b32_e32 v49, v0
	v_mov_b32_e32 v50, v0
	v_mov_b32_e32 v51, v0
	v_mov_b32_e32 v52, v0
	v_mov_b32_e32 v53, v0
	v_mov_b32_e32 v54, v0
	v_mov_b32_e32 v55, v0
	v_mov_b32_e32 v8, v0
	v_mov_b32_e32 v9, v0
	v_mov_b32_e32 v10, v0
	v_mov_b32_e32 v11, v0
	v_mov_b32_e32 v12, v0
	v_mov_b32_e32 v13, v0
	v_mov_b32_e32 v14, v0
	v_mov_b32_e32 v15, v0
	v_mov_b32_e32 v24, v0
	v_mov_b32_e32 v25, v0
	v_mov_b32_e32 v26, v0
	v_mov_b32_e32 v27, v0
	v_mov_b32_e32 v28, v0
	v_mov_b32_e32 v29, v0
	v_mov_b32_e32 v30, v0
	v_mov_b32_e32 v31, v0
	v_mov_b32_e32 v40, v0
	v_mov_b32_e32 v41, v0
	v_mov_b32_e32 v42, v0
	v_mov_b32_e32 v43, v0
	v_mov_b32_e32 v44, v0
	v_mov_b32_e32 v45, v0
	v_mov_b32_e32 v46, v0
	v_mov_b32_e32 v47, v0
	v_mov_b32_e32 v56, v0
	v_mov_b32_e32 v57, v0
	v_mov_b32_e32 v58, v0
	v_mov_b32_e32 v59, v0
	v_mov_b32_e32 v60, v0
	v_mov_b32_e32 v61, v0
	v_mov_b32_e32 v62, v0
	v_mov_b32_e32 v63, v0
	v_mov_b32_e32 v64, v0
	v_mov_b32_e32 v65, v0
	v_mov_b32_e32 v66, v0
	v_mov_b32_e32 v67, v0
	v_mov_b32_e32 v68, v0
	v_mov_b32_e32 v69, v0
	v_mov_b32_e32 v70, v0
	v_mov_b32_e32 v71, v0
	v_mov_b32_e32 v80, v0
	v_mov_b32_e32 v81, v0
	v_mov_b32_e32 v82, v0
	v_mov_b32_e32 v83, v0
	v_mov_b32_e32 v84, v0
	v_mov_b32_e32 v85, v0
	v_mov_b32_e32 v86, v0
	v_mov_b32_e32 v87, v0
	v_mov_b32_e32 v96, v0
	v_mov_b32_e32 v97, v0
	v_mov_b32_e32 v98, v0
	v_mov_b32_e32 v99, v0
	v_mov_b32_e32 v100, v0
	v_mov_b32_e32 v101, v0
	v_mov_b32_e32 v102, v0
	v_mov_b32_e32 v103, v0
	v_mov_b32_e32 v112, v0
	v_mov_b32_e32 v113, v0
	v_mov_b32_e32 v114, v0
	v_mov_b32_e32 v115, v0
	v_mov_b32_e32 v116, v0
	v_mov_b32_e32 v117, v0
	v_mov_b32_e32 v118, v0
	v_mov_b32_e32 v119, v0
	v_mov_b32_e32 v72, v0
	v_mov_b32_e32 v73, v0
	v_mov_b32_e32 v74, v0
	v_mov_b32_e32 v75, v0
	v_mov_b32_e32 v76, v0
	v_mov_b32_e32 v77, v0
	v_mov_b32_e32 v78, v0
	v_mov_b32_e32 v79, v0
	v_mov_b32_e32 v88, v0
	v_mov_b32_e32 v89, v0
	v_mov_b32_e32 v90, v0
	v_mov_b32_e32 v91, v0
	v_mov_b32_e32 v92, v0
	v_mov_b32_e32 v93, v0
	v_mov_b32_e32 v94, v0
	v_mov_b32_e32 v95, v0
	v_mov_b32_e32 v104, v0
	v_mov_b32_e32 v105, v0
	v_mov_b32_e32 v106, v0
	v_mov_b32_e32 v107, v0
	v_mov_b32_e32 v108, v0
	v_mov_b32_e32 v109, v0
	v_mov_b32_e32 v110, v0
	v_mov_b32_e32 v111, v0
	v_mov_b32_e32 v136, v0
	v_mov_b32_e32 v137, v0
	v_mov_b32_e32 v138, v0
	v_mov_b32_e32 v139, v0
	v_mov_b32_e32 v144, v0
	v_mov_b32_e32 v145, v0
	v_mov_b32_e32 v146, v0
	v_mov_b32_e32 v147, v0
	s_branch .Lph637_w

.Lph637_w:
	s_nop 0
	s_nop 0
	s_waitcnt vmcnt(8)
	s_waitcnt lgkmcnt(0)
	s_setprio 1
	s_barrier
	v_mfma_f32_16x16x32_bf16 v[144:147], v[120:123], v[160:163], v[144:147]
	v_mfma_f32_16x16x32_bf16 v[136:139], v[128:131], v[160:163], v[136:139]
	v_mfma_f32_16x16x32_bf16 v[108:111], v[120:123], v[168:171], v[108:111]
	v_mfma_f32_16x16x32_bf16 v[104:107], v[128:131], v[168:171], v[104:107]
	v_mfma_f32_16x16x32_bf16 v[92:95], v[120:123], v[176:179], v[92:95]
	v_mfma_f32_16x16x32_bf16 v[88:91], v[128:131], v[176:179], v[88:91]
	v_mfma_f32_16x16x32_bf16 v[76:79], v[120:123], v[184:187], v[76:79]
	v_mfma_f32_16x16x32_bf16 v[72:75], v[128:131], v[184:187], v[72:75]
	v_mfma_f32_16x16x32_bf16 v[144:147], v[124:127], v[164:167], v[144:147]
	v_mfma_f32_16x16x32_bf16 v[136:139], v[132:135], v[164:167], v[136:139]
	v_mfma_f32_16x16x32_bf16 v[108:111], v[124:127], v[172:175], v[108:111]
	v_mfma_f32_16x16x32_bf16 v[104:107], v[132:135], v[172:175], v[104:107]
	v_mfma_f32_16x16x32_bf16 v[92:95], v[124:127], v[180:183], v[92:95]
	v_mfma_f32_16x16x32_bf16 v[88:91], v[132:135], v[180:183], v[88:91]
	v_mfma_f32_16x16x32_bf16 v[76:79], v[124:127], v[188:191], v[76:79]
	v_mfma_f32_16x16x32_bf16 v[72:75], v[132:135], v[188:191], v[72:75]
	s_setprio 0
	s_setprio 1
	v_mfma_f32_16x16x32_bf16 v[116:119], v[140:143], v[160:163], v[116:119]
	v_mfma_f32_16x16x32_bf16 v[112:115], v[152:155], v[160:163], v[112:115]
	v_mfma_f32_16x16x32_bf16 v[100:103], v[140:143], v[168:171], v[100:103]
	v_mfma_f32_16x16x32_bf16 v[96:99], v[152:155], v[168:171], v[96:99]
	v_mfma_f32_16x16x32_bf16 v[84:87], v[140:143], v[176:179], v[84:87]
	v_mfma_f32_16x16x32_bf16 v[80:83], v[152:155], v[176:179], v[80:83]
	v_mfma_f32_16x16x32_bf16 v[68:71], v[140:143], v[184:187], v[68:71]
	v_mfma_f32_16x16x32_bf16 v[64:67], v[152:155], v[184:187], v[64:67]
	v_mfma_f32_16x16x32_bf16 v[116:119], v[148:151], v[164:167], v[116:119]
	v_mfma_f32_16x16x32_bf16 v[112:115], v[156:159], v[164:167], v[112:115]
	v_mfma_f32_16x16x32_bf16 v[100:103], v[148:151], v[172:175], v[100:103]
	v_mfma_f32_16x16x32_bf16 v[96:99], v[156:159], v[172:175], v[96:99]
	v_mfma_f32_16x16x32_bf16 v[84:87], v[148:151], v[180:183], v[84:87]
	v_mfma_f32_16x16x32_bf16 v[80:83], v[156:159], v[180:183], v[80:83]
	v_mfma_f32_16x16x32_bf16 v[68:71], v[148:151], v[188:191], v[68:71]
	v_mfma_f32_16x16x32_bf16 v[64:67], v[156:159], v[188:191], v[64:67]
	s_barrier
	s_setprio 0
	s_add_i32 s20, s43, s28
	v_lshl_add_u64 v[206:207], s[24:25], 0, v[194:195]
	s_mov_b32 m0, s20
	s_nop 0
	global_load_lds_dwordx4 v[206:207], off
	s_add_i32 m0, s20, 0x2000
	s_add_u32 s20, s24, 0xb0000
	v_lshl_add_u64 v[208:209], s[24:25], 0, v[198:199]
	s_addc_u32 s21, s25, 0
	s_add_i32 s62, s46, s28
	global_load_lds_dwordx4 v[208:209], off
	v_lshl_add_u64 v[210:211], s[20:21], 0, v[194:195]
	s_mov_b32 m0, s62
	v_lshl_add_u64 v[212:213], s[26:27], 0, v[196:197]
	global_load_lds_dwordx4 v[210:211], off
	v_lshl_add_u64 v[210:211], s[20:21], 0, v[198:199]
	s_add_i32 m0, s62, 0x2000
	s_nop 0
	global_load_lds_dwordx4 v[210:211], off
	v_lshl_add_u64 v[210:211], s[26:27], 0, v[192:193]
	s_mov_b32 m0, s29
	s_nop 0
	global_load_lds_dwordx4 v[210:211], off
	s_mov_b32 m0, s30
	s_nop 0
	global_load_lds_dwordx4 v[212:213], off
	ds_read_b128 v[160:163], v249 offset:16384
	ds_read_b128 v[164:167], v249 offset:17408
	ds_read_b128 v[168:171], v249 offset:18432
	ds_read_b128 v[172:175], v249 offset:19456
	ds_read_b128 v[176:179], v249 offset:20480
	ds_read_b128 v[180:183], v249 offset:21504
	ds_read_b128 v[184:187], v249 offset:22528
	ds_read_b128 v[188:191], v249 offset:23552
	s_nop 0
	s_waitcnt vmcnt(8)
	s_waitcnt lgkmcnt(0)
	s_setprio 1
	s_barrier
	v_mfma_f32_16x16x32_bf16 v[60:63], v[120:123], v[160:163], v[60:63]
	v_mfma_f32_16x16x32_bf16 v[56:59], v[128:131], v[160:163], v[56:59]
	v_mfma_f32_16x16x32_bf16 v[44:47], v[120:123], v[168:171], v[44:47]
	v_mfma_f32_16x16x32_bf16 v[40:43], v[128:131], v[168:171], v[40:43]
	v_mfma_f32_16x16x32_bf16 v[28:31], v[120:123], v[176:179], v[28:31]
	v_mfma_f32_16x16x32_bf16 v[24:27], v[128:131], v[176:179], v[24:27]
	v_mfma_f32_16x16x32_bf16 v[12:15], v[120:123], v[184:187], v[12:15]
	v_mfma_f32_16x16x32_bf16 v[8:11], v[128:131], v[184:187], v[8:11]
	v_mfma_f32_16x16x32_bf16 v[60:63], v[124:127], v[164:167], v[60:63]
	v_mfma_f32_16x16x32_bf16 v[56:59], v[132:135], v[164:167], v[56:59]
	v_mfma_f32_16x16x32_bf16 v[44:47], v[124:127], v[172:175], v[44:47]
	v_mfma_f32_16x16x32_bf16 v[40:43], v[132:135], v[172:175], v[40:43]
	v_mfma_f32_16x16x32_bf16 v[28:31], v[124:127], v[180:183], v[28:31]
	v_mfma_f32_16x16x32_bf16 v[24:27], v[132:135], v[180:183], v[24:27]
	v_mfma_f32_16x16x32_bf16 v[12:15], v[124:127], v[188:191], v[12:15]
	v_mfma_f32_16x16x32_bf16 v[8:11], v[132:135], v[188:191], v[8:11]
	s_setprio 0
	s_setprio 1
	v_mfma_f32_16x16x32_bf16 v[52:55], v[140:143], v[160:163], v[52:55]
	v_mfma_f32_16x16x32_bf16 v[48:51], v[152:155], v[160:163], v[48:51]
	v_mfma_f32_16x16x32_bf16 v[36:39], v[140:143], v[168:171], v[36:39]
	v_mfma_f32_16x16x32_bf16 v[32:35], v[152:155], v[168:171], v[32:35]
	v_mfma_f32_16x16x32_bf16 v[20:23], v[140:143], v[176:179], v[20:23]
	v_mfma_f32_16x16x32_bf16 v[16:19], v[152:155], v[176:179], v[16:19]
	v_mfma_f32_16x16x32_bf16 v[4:7], v[140:143], v[184:187], v[4:7]
	v_mfma_f32_16x16x32_bf16 v[0:3], v[152:155], v[184:187], v[0:3]
	v_mfma_f32_16x16x32_bf16 v[52:55], v[148:151], v[164:167], v[52:55]
	v_mfma_f32_16x16x32_bf16 v[48:51], v[156:159], v[164:167], v[48:51]
	v_mfma_f32_16x16x32_bf16 v[36:39], v[148:151], v[172:175], v[36:39]
	v_mfma_f32_16x16x32_bf16 v[32:35], v[156:159], v[172:175], v[32:35]
	v_mfma_f32_16x16x32_bf16 v[20:23], v[148:151], v[180:183], v[20:23]
	v_mfma_f32_16x16x32_bf16 v[16:19], v[156:159], v[180:183], v[16:19]
	v_mfma_f32_16x16x32_bf16 v[4:7], v[148:151], v[188:191], v[4:7]
	v_mfma_f32_16x16x32_bf16 v[0:3], v[156:159], v[188:191], v[0:3]
	s_barrier
	s_setprio 0
	s_add_i32 s62, 0, 0x18000
	s_add_i32 s63, 0, 0x1c000
	s_add_u32 s20, s26, 0xb0000
	s_addc_u32 s21, s27, 0
	s_mov_b32 m0, s31
	v_lshl_add_u64 v[214:215], s[20:21], 0, v[192:193]
	global_load_lds_dwordx4 v[214:215], off
	v_lshl_add_u64 v[214:215], s[20:21], 0, v[196:197]
	s_mov_b32 m0, s34
	s_nop 0
	global_load_lds_dwordx4 v[214:215], off
	v_add_u32_e32 v132, s62, v246
	v_add_u32_e32 v156, s63, v246
	ds_read_b128 v[120:123], v132
	ds_read_b128 v[124:127], v132 offset:1024
	ds_read_b128 v[128:131], v132 offset:2048
	ds_read_b128 v[132:135], v132 offset:3072
	ds_read_b128 v[140:143], v156
	ds_read_b128 v[148:151], v156 offset:1024
	ds_read_b128 v[152:155], v156 offset:2048
	ds_read_b128 v[156:159], v156 offset:3072
	ds_read_b128 v[160:163], v249 offset:32768
	ds_read_b128 v[164:167], v249 offset:33792
	ds_read_b128 v[168:171], v249 offset:34816
	ds_read_b128 v[172:175], v249 offset:35840
	ds_read_b128 v[176:179], v249 offset:36864
	ds_read_b128 v[180:183], v249 offset:37888
	ds_read_b128 v[184:187], v249 offset:38912
	ds_read_b128 v[188:191], v249 offset:39936
	s_waitcnt vmcnt(8)
	s_waitcnt lgkmcnt(0)
	s_setprio 1
	s_barrier
	v_mfma_f32_16x16x32_bf16 v[144:147], v[120:123], v[160:163], v[144:147]
	v_mfma_f32_16x16x32_bf16 v[136:139], v[128:131], v[160:163], v[136:139]
	v_mfma_f32_16x16x32_bf16 v[108:111], v[120:123], v[168:171], v[108:111]
	v_mfma_f32_16x16x32_bf16 v[104:107], v[128:131], v[168:171], v[104:107]
	v_mfma_f32_16x16x32_bf16 v[92:95], v[120:123], v[176:179], v[92:95]
	v_mfma_f32_16x16x32_bf16 v[88:91], v[128:131], v[176:179], v[88:91]
	v_mfma_f32_16x16x32_bf16 v[76:79], v[120:123], v[184:187], v[76:79]
	v_mfma_f32_16x16x32_bf16 v[72:75], v[128:131], v[184:187], v[72:75]
	v_mfma_f32_16x16x32_bf16 v[144:147], v[124:127], v[164:167], v[144:147]
	v_mfma_f32_16x16x32_bf16 v[136:139], v[132:135], v[164:167], v[136:139]
	v_mfma_f32_16x16x32_bf16 v[108:111], v[124:127], v[172:175], v[108:111]
	v_mfma_f32_16x16x32_bf16 v[104:107], v[132:135], v[172:175], v[104:107]
	v_mfma_f32_16x16x32_bf16 v[92:95], v[124:127], v[180:183], v[92:95]
	v_mfma_f32_16x16x32_bf16 v[88:91], v[132:135], v[180:183], v[88:91]
	v_mfma_f32_16x16x32_bf16 v[76:79], v[124:127], v[188:191], v[76:79]
	v_mfma_f32_16x16x32_bf16 v[72:75], v[132:135], v[188:191], v[72:75]
	s_setprio 0
	s_setprio 1
	v_mfma_f32_16x16x32_bf16 v[116:119], v[140:143], v[160:163], v[116:119]
	v_mfma_f32_16x16x32_bf16 v[112:115], v[152:155], v[160:163], v[112:115]
	v_mfma_f32_16x16x32_bf16 v[100:103], v[140:143], v[168:171], v[100:103]
	v_mfma_f32_16x16x32_bf16 v[96:99], v[152:155], v[168:171], v[96:99]
	v_mfma_f32_16x16x32_bf16 v[84:87], v[140:143], v[176:179], v[84:87]
	v_mfma_f32_16x16x32_bf16 v[80:83], v[152:155], v[176:179], v[80:83]
	v_mfma_f32_16x16x32_bf16 v[68:71], v[140:143], v[184:187], v[68:71]
	v_mfma_f32_16x16x32_bf16 v[64:67], v[152:155], v[184:187], v[64:67]
	v_mfma_f32_16x16x32_bf16 v[116:119], v[148:151], v[164:167], v[116:119]
	v_mfma_f32_16x16x32_bf16 v[112:115], v[156:159], v[164:167], v[112:115]
	v_mfma_f32_16x16x32_bf16 v[100:103], v[148:151], v[172:175], v[100:103]
	v_mfma_f32_16x16x32_bf16 v[96:99], v[156:159], v[172:175], v[96:99]
	v_mfma_f32_16x16x32_bf16 v[84:87], v[148:151], v[180:183], v[84:87]
	v_mfma_f32_16x16x32_bf16 v[80:83], v[156:159], v[180:183], v[80:83]
	v_mfma_f32_16x16x32_bf16 v[68:71], v[148:151], v[188:191], v[68:71]
	v_mfma_f32_16x16x32_bf16 v[64:67], v[156:159], v[188:191], v[64:67]
	s_barrier
	s_setprio 0
	s_add_i32 s20, s62, s28
	v_lshl_add_u64 v[206:207], v[206:207], 0, s[14:15]
	s_mov_b32 m0, s20
	s_nop 0
	global_load_lds_dwordx4 v[206:207], off
	s_add_i32 m0, s20, 0x2000
	s_add_u32 s20, s24, 0xb0080
	v_lshl_add_u64 v[206:207], v[208:209], 0, s[14:15]
	s_addc_u32 s21, s25, 0
	s_add_i32 s24, s63, s28
	global_load_lds_dwordx4 v[206:207], off
	v_lshl_add_u64 v[206:207], s[20:21], 0, v[194:195]
	s_mov_b32 m0, s24
	s_nop 0
	global_load_lds_dwordx4 v[206:207], off
	v_lshl_add_u64 v[206:207], s[20:21], 0, v[198:199]
	s_add_i32 m0, s24, 0x2000
	s_nop 0
	global_load_lds_dwordx4 v[206:207], off
	v_lshl_add_u64 v[206:207], v[210:211], 0, s[14:15]
	s_mov_b32 m0, s38
	s_nop 0
	global_load_lds_dwordx4 v[206:207], off
	v_lshl_add_u64 v[206:207], v[212:213], 0, s[14:15]
	s_mov_b32 m0, s39
	s_nop 0
	global_load_lds_dwordx4 v[206:207], off
	ds_read_b128 v[160:163], v249 offset:49152
	ds_read_b128 v[164:167], v249 offset:50176
	ds_read_b128 v[168:171], v249 offset:51200
	ds_read_b128 v[172:175], v249 offset:52224
	ds_read_b128 v[176:179], v249 offset:53248
	ds_read_b128 v[180:183], v249 offset:54272
	ds_read_b128 v[184:187], v249 offset:55296
	ds_read_b128 v[188:191], v249 offset:56320
	s_waitcnt vmcnt(8)
	s_waitcnt lgkmcnt(0)
	s_setprio 1
	s_barrier
	v_mfma_f32_16x16x32_bf16 v[60:63], v[120:123], v[160:163], v[60:63]
	v_mfma_f32_16x16x32_bf16 v[56:59], v[128:131], v[160:163], v[56:59]
	v_mfma_f32_16x16x32_bf16 v[44:47], v[120:123], v[168:171], v[44:47]
	v_mfma_f32_16x16x32_bf16 v[40:43], v[128:131], v[168:171], v[40:43]
	v_mfma_f32_16x16x32_bf16 v[28:31], v[120:123], v[176:179], v[28:31]
	v_mfma_f32_16x16x32_bf16 v[24:27], v[128:131], v[176:179], v[24:27]
	v_mfma_f32_16x16x32_bf16 v[12:15], v[120:123], v[184:187], v[12:15]
	v_mfma_f32_16x16x32_bf16 v[8:11], v[128:131], v[184:187], v[8:11]
	v_mfma_f32_16x16x32_bf16 v[60:63], v[124:127], v[164:167], v[60:63]
	v_mfma_f32_16x16x32_bf16 v[56:59], v[132:135], v[164:167], v[56:59]
	v_mfma_f32_16x16x32_bf16 v[44:47], v[124:127], v[172:175], v[44:47]
	v_mfma_f32_16x16x32_bf16 v[40:43], v[132:135], v[172:175], v[40:43]
	v_mfma_f32_16x16x32_bf16 v[28:31], v[124:127], v[180:183], v[28:31]
	v_mfma_f32_16x16x32_bf16 v[24:27], v[132:135], v[180:183], v[24:27]
	v_mfma_f32_16x16x32_bf16 v[12:15], v[124:127], v[188:191], v[12:15]
	v_mfma_f32_16x16x32_bf16 v[8:11], v[132:135], v[188:191], v[8:11]
	s_setprio 0
	s_setprio 1
	v_mfma_f32_16x16x32_bf16 v[52:55], v[140:143], v[160:163], v[52:55]
	v_mfma_f32_16x16x32_bf16 v[48:51], v[152:155], v[160:163], v[48:51]
	v_mfma_f32_16x16x32_bf16 v[36:39], v[140:143], v[168:171], v[36:39]
	v_mfma_f32_16x16x32_bf16 v[32:35], v[152:155], v[168:171], v[32:35]
	v_mfma_f32_16x16x32_bf16 v[20:23], v[140:143], v[176:179], v[20:23]
	v_mfma_f32_16x16x32_bf16 v[16:19], v[152:155], v[176:179], v[16:19]
	v_mfma_f32_16x16x32_bf16 v[4:7], v[140:143], v[184:187], v[4:7]
	v_mfma_f32_16x16x32_bf16 v[0:3], v[152:155], v[184:187], v[0:3]
	v_mfma_f32_16x16x32_bf16 v[52:55], v[148:151], v[164:167], v[52:55]
	v_mfma_f32_16x16x32_bf16 v[48:51], v[156:159], v[164:167], v[48:51]
	v_mfma_f32_16x16x32_bf16 v[36:39], v[148:151], v[172:175], v[36:39]
	v_mfma_f32_16x16x32_bf16 v[32:35], v[156:159], v[172:175], v[32:35]
	v_mfma_f32_16x16x32_bf16 v[20:23], v[148:151], v[180:183], v[20:23]
	v_mfma_f32_16x16x32_bf16 v[16:19], v[156:159], v[180:183], v[16:19]
	v_mfma_f32_16x16x32_bf16 v[4:7], v[148:151], v[188:191], v[4:7]
	v_mfma_f32_16x16x32_bf16 v[0:3], v[156:159], v[188:191], v[0:3]
	s_barrier
	s_setprio 0
	s_add_i32 s61, s61, 2
	s_add_u32 s51, s51, 0x100
	s_addc_u32 s60, s60, 0
	s_cmp_gt_u32 s61, 41
	s_mov_b64 s[20:21], s[22:23]
	s_cbranch_scc0 .LBB0_637
	s_and_b64 vcc, exec, s[16:17]
	s_cbranch_vccz .LBB0_640
	s_barrier

.LBB0_656:
	s_or_b64 exec, exec, s[20:21]
	s_and_b64 vcc, exec, s[6:7]
	s_mov_b64 s[6:7], -1
	s_cbranch_vccnz .LBB0_625
	s_mov_b32 s101, 0
	s_andn2_b64 vcc, exec, s[12:13]
	s_cbranch_vccnz .LBB0_624
	s_mov_b32 s101, 1
	s_branch .LBB0_624

.LBB0_717:
	s_mov_b64 s[14:15], 0x80
	s_and_b32 s9, s6, 3
	s_add_i32 m0, s69, 0x18000
	v_lshl_add_u64 v[6:7], v[6:7], 0, s[14:15]
	s_lshl_b32 s74, s7, 6
	s_lshl_b32 s17, s7, 13
	s_lshl_b32 s75, s9, 5
	s_lshl_b32 s18, s9, 12
	s_waitcnt vmcnt(2)
	s_barrier
	global_load_lds_dwordx4 v[6:7], off
	v_lshl_add_u64 v[4:5], v[4:5], 0, s[14:15]
	s_add_i32 m0, s69, 0x1a000
	s_add_i32 s76, s69, 0x8000
	s_add_i32 s77, s69, 0xa000
	global_load_lds_dwordx4 v[4:5], off
	v_lshl_add_u64 v[0:1], v[0:1], 0, s[14:15]
	s_mov_b32 m0, s76
	s_add_u32 s6, s62, 0x40080
	global_load_lds_dwordx4 v[0:1], off
	v_lshl_add_u64 v[0:1], v[2:3], 0, s[14:15]
	s_mov_b32 m0, s77
	s_addc_u32 s7, s63, 0
	global_load_lds_dwordx4 v[0:1], off
	s_add_i32 m0, s69, 0x1c000
	v_lshl_add_u64 v[0:1], s[6:7], 0, v[208:209]
	global_load_lds_dwordx4 v[0:1], off
	v_lshl_add_u64 v[0:1], s[6:7], 0, v[212:213]
	s_add_i32 m0, s69, 0x1e000
	v_bfe_u32 v233, v8, 4, 2
	global_load_lds_dwordx4 v[0:1], off
	v_and_b32_e32 v232, 15, v8
	v_lshlrev_b32_e32 v0, 4, v233
	v_lshlrev_b32_e32 v1, 2, v8
	v_lshl_or_b32 v0, v232, 6, v0
	v_and_b32_e32 v1, 32, v1
	s_cmpk_lt_u32 s16, 0x100
	v_bitop3_b32 v2, v0, s17, v1 bitop3:0xde
	s_cselect_b64 s[16:17], -1, 0
	s_lshl_b32 s78, s9, 2
	s_lshl_b32 s6, s9, 4
	v_bitop3_b32 v234, v0, s18, v1 bitop3:0xde
	s_add_u32 s6, s54, s6
	v_lshlrev_b32_e32 v0, 14, v9
	s_addc_u32 s7, s55, 0
	v_and_b32_e32 v0, 0xffff8000, v0
	s_add_u32 s18, s6, 0x100000
	v_lshl_add_u32 v0, v10, 11, v0
	v_and_b32_e32 v1, 1, v9
	s_addc_u32 s19, s7, 0
	v_lshl_or_b32 v0, v1, 6, v0
	s_add_u32 s20, s6, 0x300000
	s_mul_i32 s80, s9, 24
	v_lshl_add_u32 v214, v11, 1, v0
	v_lshlrev_b32_e32 v0, 14, v12
	s_addc_u32 s21, s7, 0
	s_or_b32 s79, s78, 0x20000
	s_add_i32 s80, s80, 24
	s_or_b32 s81, s78, 16
	v_and_b32_e32 v0, 0xffff8000, v0
	s_waitcnt vmcnt(6)
	s_add_u32 s82, s54, 0xc2000
	v_lshl_add_u32 v0, v13, 11, v0
	v_and_b32_e32 v1, 1, v12
	s_addc_u32 s83, s55, 0
	v_lshl_or_b32 v0, v1, 6, v0
	s_add_i32 s88, 0, 0x10000
	s_add_i32 s89, 0, 0x14000
	s_ashr_i32 s84, s52, 31
	s_mov_b32 s85, s52
	s_ashr_i32 s86, s33, 31
	v_mov_b32_e32 v215, v209
	v_lshl_add_u32 v216, v14, 1, v0
	v_mov_b32_e32 v217, v209
	s_movk_i32 s87, 0x121
	v_add_u32_e32 v235, s88, v234
	v_add_u32_e32 v236, s89, v234
	v_add_u32_e32 v237, 0, v2
	s_brev_b32 s90, 16
	s_mov_b64 s[22:23], 0x400
	s_mov_b64 s[24:25], 0x800
	s_mov_b64 s[26:27], 0xc00
	s_mov_b64 s[28:29], 0x2000
	s_mov_b64 s[30:31], 0x2400
	s_mov_b64 s[34:35], 0x2800
	s_mov_b64 s[36:37], 0x2c00
	v_mov_b32_e32 v238, 0x358637bd
	s_movk_i32 s91, 0xc00
	s_movk_i32 s92, 0x600
	s_barrier
	s_mov_b32 s101, 0
	s_branch .LBB0_720

.LBB0_722:
	s_ashr_i32 s41, s40, 31
	s_lshl_b64 s[42:43], s[40:41], 19
	s_add_u32 s42, s58, s42
	s_addc_u32 s43, s59, s43
	s_and_b64 s[46:47], s[6:7], exec
	s_cselect_b32 s9, s43, s49
	s_cselect_b32 s41, s42, s48
	s_ashr_i32 s39, s38, 31
	s_lshl_b64 s[46:47], s[38:39], 19
	s_add_u32 s46, s4, s46
	s_addc_u32 s47, s5, s47
	s_and_b64 s[60:61], s[6:7], exec
	s_cselect_b32 s39, s47, s63
	s_cselect_b32 s51, s46, s62
	s_add_u32 s48, s48, 0x40080
	s_addc_u32 s49, s49, 0
	s_add_u32 s60, s62, 0x100
	v_mov_b32_e32 v0, 0
	s_addc_u32 s61, s63, 0
	s_mov_b32 s93, -2
	s_waitcnt vmcnt(0)
	s_cmp_lg_u32 s101, 0
	s_cbranch_scc0 .Lph723_a
	v_mov_b32_e32 v1, v0
	v_mov_b32_e32 v2, v0
	v_mov_b32_e32 v3, v0
	v_mov_b32_e32 v4, v0
	v_mov_b32_e32 v5, v0
	v_mov_b32_e32 v6, v0
	v_mov_b32_e32 v7, v0
	v_mov_b32_e32 v12, v0
	v_mov_b32_e32 v13, v0
	v_mov_b32_e32 v14, v0
	v_mov_b32_e32 v15, v0
	v_mov_b32_e32 v20, v0
	v_mov_b32_e32 v21, v0
	v_mov_b32_e32 v22, v0
	v_mov_b32_e32 v23, v0
	v_mov_b32_e32 v28, v0
	v_mov_b32_e32 v29, v0
	v_mov_b32_e32 v30, v0
	v_mov_b32_e32 v31, v0
	v_mov_b32_e32 v36, v0
	v_mov_b32_e32 v37, v0
	v_mov_b32_e32 v38, v0
	v_mov_b32_e32 v39, v0
	v_mov_b32_e32 v44, v0
	v_mov_b32_e32 v45, v0
	v_mov_b32_e32 v46, v0
	v_mov_b32_e32 v47, v0
	v_mov_b32_e32 v52, v0
	v_mov_b32_e32 v53, v0
	v_mov_b32_e32 v54, v0
	v_mov_b32_e32 v55, v0
	v_mov_b32_e32 v8, v0
	v_mov_b32_e32 v9, v0
	v_mov_b32_e32 v10, v0
	v_mov_b32_e32 v11, v0
	v_mov_b32_e32 v16, v0
	v_mov_b32_e32 v17, v0
	v_mov_b32_e32 v18, v0
	v_mov_b32_e32 v19, v0
	v_mov_b32_e32 v24, v0
	v_mov_b32_e32 v25, v0
	v_mov_b32_e32 v26, v0
	v_mov_b32_e32 v27, v0
	v_mov_b32_e32 v32, v0
	v_mov_b32_e32 v33, v0
	v_mov_b32_e32 v34, v0
	v_mov_b32_e32 v35, v0
	v_mov_b32_e32 v40, v0
	v_mov_b32_e32 v41, v0
	v_mov_b32_e32 v42, v0
	v_mov_b32_e32 v43, v0
	v_mov_b32_e32 v48, v0
	v_mov_b32_e32 v49, v0
	v_mov_b32_e32 v50, v0
	v_mov_b32_e32 v51, v0
	v_mov_b32_e32 v56, v0
	v_mov_b32_e32 v57, v0
	v_mov_b32_e32 v58, v0
	v_mov_b32_e32 v59, v0
	v_mov_b32_e32 v60, v0
	v_mov_b32_e32 v61, v0
	v_mov_b32_e32 v62, v0
	v_mov_b32_e32 v63, v0
	v_mov_b32_e32 v64, v0
	v_mov_b32_e32 v65, v0
	v_mov_b32_e32 v66, v0
	v_mov_b32_e32 v67, v0
	v_mov_b32_e32 v68, v0
	v_mov_b32_e32 v69, v0
	v_mov_b32_e32 v70, v0
	v_mov_b32_e32 v71, v0
	v_mov_b32_e32 v72, v0
	v_mov_b32_e32 v73, v0
	v_mov_b32_e32 v74, v0
	v_mov_b32_e32 v75, v0
	v_mov_b32_e32 v76, v0
	v_mov_b32_e32 v77, v0
	v_mov_b32_e32 v78, v0
	v_mov_b32_e32 v79, v0
	v_mov_b32_e32 v84, v0
	v_mov_b32_e32 v85, v0
	v_mov_b32_e32 v86, v0
	v_mov_b32_e32 v87, v0
	v_mov_b32_e32 v88, v0
	v_mov_b32_e32 v89, v0
	v_mov_b32_e32 v90, v0
	v_mov_b32_e32 v91, v0
	v_mov_b32_e32 v96, v0
	v_mov_b32_e32 v97, v0
	v_mov_b32_e32 v98, v0
	v_mov_b32_e32 v99, v0
	v_mov_b32_e32 v104, v0
	v_mov_b32_e32 v105, v0
	v_mov_b32_e32 v106, v0
	v_mov_b32_e32 v107, v0
	v_mov_b32_e32 v80, v0
	v_mov_b32_e32 v81, v0
	v_mov_b32_e32 v82, v0
	v_mov_b32_e32 v83, v0
	v_mov_b32_e32 v92, v0
	v_mov_b32_e32 v93, v0
	v_mov_b32_e32 v94, v0
	v_mov_b32_e32 v95, v0
	v_mov_b32_e32 v100, v0
	v_mov_b32_e32 v101, v0
	v_mov_b32_e32 v102, v0
	v_mov_b32_e32 v103, v0
	v_mov_b32_e32 v108, v0
	v_mov_b32_e32 v109, v0
	v_mov_b32_e32 v110, v0
	v_mov_b32_e32 v111, v0
	v_mov_b32_e32 v112, v0
	v_mov_b32_e32 v113, v0
	v_mov_b32_e32 v114, v0
	v_mov_b32_e32 v115, v0
	v_mov_b32_e32 v116, v0
	v_mov_b32_e32 v117, v0
	v_mov_b32_e32 v118, v0
	v_mov_b32_e32 v119, v0
	v_mov_b32_e32 v120, v0
	v_mov_b32_e32 v121, v0
	v_mov_b32_e32 v122, v0
	v_mov_b32_e32 v123, v0
	v_mov_b32_e32 v124, v0
	v_mov_b32_e32 v125, v0
	v_mov_b32_e32 v126, v0
	v_mov_b32_e32 v127, v0
	s_barrier
	s_mov_b32 s101, 0
	s_branch .LBB0_723
.Lph723_a:
	s_add_u32 s62, s48, 0xfffc0080
	s_addc_u32 s63, s49, -1
	s_cmp_eq_u32 s93, 12
	s_cselect_b32 s65, s9, s63
	s_cselect_b32 s64, s41, s62
	s_cselect_b32 s63, s39, s61
	s_cselect_b32 s62, s51, s60
	v_lshl_add_u64 v[192:193], s[48:49], 0, v[214:215]
	s_add_i32 m0, s69, 0xc000
	s_nop 0
	global_load_lds_dwordx4 v[192:193], off
	v_lshl_add_u64 v[192:193], s[48:49], 0, v[216:217]
	s_add_i32 m0, s69, 0xe000
	s_nop 0
	global_load_lds_dwordx4 v[192:193], off
	ds_read_b128 v[128:131], v235
	ds_read_b128 v[132:135], v235 offset:1024
	ds_read_b128 v[136:139], v235 offset:2048
	ds_read_b128 v[140:143], v235 offset:3072
	ds_read_b128 v[144:147], v236
	ds_read_b128 v[148:151], v236 offset:1024
	ds_read_b128 v[152:155], v236 offset:2048
	ds_read_b128 v[156:159], v236 offset:3072
	ds_read_b128 v[160:163], v237
	ds_read_b128 v[164:167], v237 offset:1024
	ds_read_b128 v[168:171], v237 offset:2048
	ds_read_b128 v[172:175], v237 offset:3072
	ds_read_b128 v[176:179], v237 offset:4096
	ds_read_b128 v[180:183], v237 offset:5120
	ds_read_b128 v[184:187], v237 offset:6144
	ds_read_b128 v[188:191], v237 offset:7168
	v_mov_b32_e32 v1, v0
	v_mov_b32_e32 v2, v0
	v_mov_b32_e32 v3, v0
	v_mov_b32_e32 v4, v0
	v_mov_b32_e32 v5, v0
	v_mov_b32_e32 v6, v0
	v_mov_b32_e32 v7, v0
	v_mov_b32_e32 v12, v0
	v_mov_b32_e32 v13, v0
	v_mov_b32_e32 v14, v0
	v_mov_b32_e32 v15, v0
	v_mov_b32_e32 v20, v0
	v_mov_b32_e32 v21, v0
	v_mov_b32_e32 v22, v0
	v_mov_b32_e32 v23, v0
	v_mov_b32_e32 v28, v0
	v_mov_b32_e32 v29, v0
	v_mov_b32_e32 v30, v0
	v_mov_b32_e32 v31, v0
	v_mov_b32_e32 v36, v0
	v_mov_b32_e32 v37, v0
	v_mov_b32_e32 v38, v0
	v_mov_b32_e32 v39, v0
	v_mov_b32_e32 v44, v0
	v_mov_b32_e32 v45, v0
	v_mov_b32_e32 v46, v0
	v_mov_b32_e32 v47, v0
	v_mov_b32_e32 v52, v0
	v_mov_b32_e32 v53, v0
	v_mov_b32_e32 v54, v0
	v_mov_b32_e32 v55, v0
	v_mov_b32_e32 v8, v0
	v_mov_b32_e32 v9, v0
	v_mov_b32_e32 v10, v0
	v_mov_b32_e32 v11, v0
	v_mov_b32_e32 v16, v0
	v_mov_b32_e32 v17, v0
	v_mov_b32_e32 v18, v0
	v_mov_b32_e32 v19, v0
	v_mov_b32_e32 v24, v0
	v_mov_b32_e32 v25, v0
	v_mov_b32_e32 v26, v0
	v_mov_b32_e32 v27, v0
	v_mov_b32_e32 v32, v0
	v_mov_b32_e32 v33, v0
	v_mov_b32_e32 v34, v0
	v_mov_b32_e32 v35, v0
	v_mov_b32_e32 v40, v0
	v_mov_b32_e32 v41, v0
	v_mov_b32_e32 v42, v0
	v_mov_b32_e32 v43, v0
	v_mov_b32_e32 v48, v0
	v_mov_b32_e32 v49, v0
	v_mov_b32_e32 v50, v0
	v_mov_b32_e32 v51, v0
	v_mov_b32_e32 v56, v0
	v_mov_b32_e32 v57, v0
	v_mov_b32_e32 v58, v0
	v_mov_b32_e32 v59, v0
	v_mov_b32_e32 v60, v0
	v_mov_b32_e32 v61, v0
	v_mov_b32_e32 v62, v0
	v_mov_b32_e32 v63, v0
	v_mov_b32_e32 v64, v0
	v_mov_b32_e32 v65, v0
	v_mov_b32_e32 v66, v0
	v_mov_b32_e32 v67, v0
	v_mov_b32_e32 v68, v0
	v_mov_b32_e32 v69, v0
	v_mov_b32_e32 v70, v0
	v_mov_b32_e32 v71, v0
	v_mov_b32_e32 v72, v0
	v_mov_b32_e32 v73, v0
	v_mov_b32_e32 v74, v0
	v_mov_b32_e32 v75, v0
	v_mov_b32_e32 v76, v0
	v_mov_b32_e32 v77, v0
	v_mov_b32_e32 v78, v0
	v_mov_b32_e32 v79, v0
	v_mov_b32_e32 v84, v0
	v_mov_b32_e32 v85, v0
	v_mov_b32_e32 v86, v0
	v_mov_b32_e32 v87, v0
	v_mov_b32_e32 v88, v0
	v_mov_b32_e32 v89, v0
	v_mov_b32_e32 v90, v0
	v_mov_b32_e32 v91, v0
	v_mov_b32_e32 v96, v0
	v_mov_b32_e32 v97, v0
	v_mov_b32_e32 v98, v0
	v_mov_b32_e32 v99, v0
	v_mov_b32_e32 v104, v0
	v_mov_b32_e32 v105, v0
	v_mov_b32_e32 v106, v0
	v_mov_b32_e32 v107, v0
	v_mov_b32_e32 v80, v0
	v_mov_b32_e32 v81, v0
	v_mov_b32_e32 v82, v0
	v_mov_b32_e32 v83, v0
	v_mov_b32_e32 v92, v0
	v_mov_b32_e32 v93, v0
	v_mov_b32_e32 v94, v0
	v_mov_b32_e32 v95, v0
	v_mov_b32_e32 v100, v0
	v_mov_b32_e32 v101, v0
	v_mov_b32_e32 v102, v0
	v_mov_b32_e32 v103, v0
	v_mov_b32_e32 v108, v0
	v_mov_b32_e32 v109, v0
	v_mov_b32_e32 v110, v0
	v_mov_b32_e32 v111, v0
	v_mov_b32_e32 v112, v0
	v_mov_b32_e32 v113, v0
	v_mov_b32_e32 v114, v0
	v_mov_b32_e32 v115, v0
	v_mov_b32_e32 v116, v0
	v_mov_b32_e32 v117, v0
	v_mov_b32_e32 v118, v0
	v_mov_b32_e32 v119, v0
	v_mov_b32_e32 v120, v0
	v_mov_b32_e32 v121, v0
	v_mov_b32_e32 v122, v0
	v_mov_b32_e32 v123, v0
	v_mov_b32_e32 v124, v0
	v_mov_b32_e32 v125, v0
	v_mov_b32_e32 v126, v0
	v_mov_b32_e32 v127, v0
	s_branch .Lph723_w

.Lph723_w:
	s_nop 0
	s_nop 0
	s_waitcnt vmcnt(8)
	s_waitcnt lgkmcnt(0)
	s_setprio 1
	s_barrier
	v_mfma_f32_16x16x32_bf16 v[124:127], v[128:131], v[160:163], v[124:127]
	v_mfma_f32_16x16x32_bf16 v[120:123], v[136:139], v[160:163], v[120:123]
	v_mfma_f32_16x16x32_bf16 v[116:119], v[128:131], v[168:171], v[116:119]
	v_mfma_f32_16x16x32_bf16 v[112:115], v[136:139], v[168:171], v[112:115]
	v_mfma_f32_16x16x32_bf16 v[108:111], v[128:131], v[176:179], v[108:111]
	v_mfma_f32_16x16x32_bf16 v[100:103], v[136:139], v[176:179], v[100:103]
	v_mfma_f32_16x16x32_bf16 v[92:95], v[128:131], v[184:187], v[92:95]
	v_mfma_f32_16x16x32_bf16 v[80:83], v[136:139], v[184:187], v[80:83]
	v_mfma_f32_16x16x32_bf16 v[124:127], v[132:135], v[164:167], v[124:127]
	v_mfma_f32_16x16x32_bf16 v[120:123], v[140:143], v[164:167], v[120:123]
	v_mfma_f32_16x16x32_bf16 v[116:119], v[132:135], v[172:175], v[116:119]
	v_mfma_f32_16x16x32_bf16 v[112:115], v[140:143], v[172:175], v[112:115]
	v_mfma_f32_16x16x32_bf16 v[108:111], v[132:135], v[180:183], v[108:111]
	v_mfma_f32_16x16x32_bf16 v[100:103], v[140:143], v[180:183], v[100:103]
	v_mfma_f32_16x16x32_bf16 v[92:95], v[132:135], v[188:191], v[92:95]
	v_mfma_f32_16x16x32_bf16 v[80:83], v[140:143], v[188:191], v[80:83]
	s_setprio 0
	s_setprio 1
	v_mfma_f32_16x16x32_bf16 v[104:107], v[144:147], v[160:163], v[104:107]
	v_mfma_f32_16x16x32_bf16 v[96:99], v[152:155], v[160:163], v[96:99]
	v_mfma_f32_16x16x32_bf16 v[88:91], v[144:147], v[168:171], v[88:91]
	v_mfma_f32_16x16x32_bf16 v[84:87], v[152:155], v[168:171], v[84:87]
	v_mfma_f32_16x16x32_bf16 v[76:79], v[144:147], v[176:179], v[76:79]
	v_mfma_f32_16x16x32_bf16 v[72:75], v[152:155], v[176:179], v[72:75]
	v_mfma_f32_16x16x32_bf16 v[68:71], v[144:147], v[184:187], v[68:71]
	v_mfma_f32_16x16x32_bf16 v[64:67], v[152:155], v[184:187], v[64:67]
	v_mfma_f32_16x16x32_bf16 v[104:107], v[148:151], v[164:167], v[104:107]
	v_mfma_f32_16x16x32_bf16 v[96:99], v[156:159], v[164:167], v[96:99]
	v_mfma_f32_16x16x32_bf16 v[88:91], v[148:151], v[172:175], v[88:91]
	v_mfma_f32_16x16x32_bf16 v[84:87], v[156:159], v[172:175], v[84:87]
	v_mfma_f32_16x16x32_bf16 v[76:79], v[148:151], v[180:183], v[76:79]
	v_mfma_f32_16x16x32_bf16 v[72:75], v[156:159], v[180:183], v[72:75]
	v_mfma_f32_16x16x32_bf16 v[68:71], v[148:151], v[188:191], v[68:71]
	v_mfma_f32_16x16x32_bf16 v[64:67], v[156:159], v[188:191], v[64:67]
	s_barrier
	s_setprio 0
	s_add_i32 s94, s88, s68
	v_lshl_add_u64 v[192:193], s[62:63], 0, v[208:209]
	s_mov_b32 m0, s94
	s_nop 0
	global_load_lds_dwordx4 v[192:193], off
	s_add_i32 m0, s94, 0x2000
	s_add_u32 s94, s62, 0x40000
	v_lshl_add_u64 v[194:195], s[62:63], 0, v[212:213]
	s_addc_u32 s95, s63, 0
	s_add_i32 s96, s89, s68
	global_load_lds_dwordx4 v[194:195], off
	v_lshl_add_u64 v[196:197], s[94:95], 0, v[208:209]
	s_mov_b32 m0, s96
	v_lshl_add_u64 v[198:199], s[64:65], 0, v[210:211]
	global_load_lds_dwordx4 v[196:197], off
	v_lshl_add_u64 v[196:197], s[94:95], 0, v[212:213]
	s_add_i32 m0, s96, 0x2000
	s_nop 0
	global_load_lds_dwordx4 v[196:197], off
	v_lshl_add_u64 v[196:197], s[64:65], 0, v[206:207]
	s_mov_b32 m0, s69
	s_nop 0
	global_load_lds_dwordx4 v[196:197], off
	s_mov_b32 m0, s70
	s_nop 0
	global_load_lds_dwordx4 v[198:199], off
	ds_read_b128 v[160:163], v237 offset:16384
	ds_read_b128 v[164:167], v237 offset:17408
	ds_read_b128 v[168:171], v237 offset:18432
	ds_read_b128 v[172:175], v237 offset:19456
	ds_read_b128 v[176:179], v237 offset:20480
	ds_read_b128 v[180:183], v237 offset:21504
	ds_read_b128 v[184:187], v237 offset:22528
	ds_read_b128 v[188:191], v237 offset:23552
	s_nop 0
	s_waitcnt vmcnt(8)
	s_waitcnt lgkmcnt(0)
	s_setprio 1
	s_barrier
	v_mfma_f32_16x16x32_bf16 v[60:63], v[128:131], v[160:163], v[60:63]
	v_mfma_f32_16x16x32_bf16 v[56:59], v[136:139], v[160:163], v[56:59]
	v_mfma_f32_16x16x32_bf16 v[48:51], v[128:131], v[168:171], v[48:51]
	v_mfma_f32_16x16x32_bf16 v[40:43], v[136:139], v[168:171], v[40:43]
	v_mfma_f32_16x16x32_bf16 v[32:35], v[128:131], v[176:179], v[32:35]
	v_mfma_f32_16x16x32_bf16 v[24:27], v[136:139], v[176:179], v[24:27]
	v_mfma_f32_16x16x32_bf16 v[16:19], v[128:131], v[184:187], v[16:19]
	v_mfma_f32_16x16x32_bf16 v[8:11], v[136:139], v[184:187], v[8:11]
	v_mfma_f32_16x16x32_bf16 v[60:63], v[132:135], v[164:167], v[60:63]
	v_mfma_f32_16x16x32_bf16 v[56:59], v[140:143], v[164:167], v[56:59]
	v_mfma_f32_16x16x32_bf16 v[48:51], v[132:135], v[172:175], v[48:51]
	v_mfma_f32_16x16x32_bf16 v[40:43], v[140:143], v[172:175], v[40:43]
	v_mfma_f32_16x16x32_bf16 v[32:35], v[132:135], v[180:183], v[32:35]
	v_mfma_f32_16x16x32_bf16 v[24:27], v[140:143], v[180:183], v[24:27]
	v_mfma_f32_16x16x32_bf16 v[16:19], v[132:135], v[188:191], v[16:19]
	v_mfma_f32_16x16x32_bf16 v[8:11], v[140:143], v[188:191], v[8:11]
	s_setprio 0
	s_setprio 1
	v_mfma_f32_16x16x32_bf16 v[52:55], v[144:147], v[160:163], v[52:55]
	v_mfma_f32_16x16x32_bf16 v[44:47], v[152:155], v[160:163], v[44:47]
	v_mfma_f32_16x16x32_bf16 v[36:39], v[144:147], v[168:171], v[36:39]
	v_mfma_f32_16x16x32_bf16 v[28:31], v[152:155], v[168:171], v[28:31]
	v_mfma_f32_16x16x32_bf16 v[20:23], v[144:147], v[176:179], v[20:23]
	v_mfma_f32_16x16x32_bf16 v[12:15], v[152:155], v[176:179], v[12:15]
	v_mfma_f32_16x16x32_bf16 v[4:7], v[144:147], v[184:187], v[4:7]
	v_mfma_f32_16x16x32_bf16 v[0:3], v[152:155], v[184:187], v[0:3]
	v_mfma_f32_16x16x32_bf16 v[52:55], v[148:151], v[164:167], v[52:55]
	v_mfma_f32_16x16x32_bf16 v[44:47], v[156:159], v[164:167], v[44:47]
	v_mfma_f32_16x16x32_bf16 v[36:39], v[148:151], v[172:175], v[36:39]
	v_mfma_f32_16x16x32_bf16 v[28:31], v[156:159], v[172:175], v[28:31]
	v_mfma_f32_16x16x32_bf16 v[20:23], v[148:151], v[180:183], v[20:23]
	v_mfma_f32_16x16x32_bf16 v[12:15], v[156:159], v[180:183], v[12:15]
	v_mfma_f32_16x16x32_bf16 v[4:7], v[148:151], v[188:191], v[4:7]
	v_mfma_f32_16x16x32_bf16 v[0:3], v[156:159], v[188:191], v[0:3]
	s_barrier
	s_setprio 0
	s_add_i32 s94, 0, 0x18000
	s_add_i32 s95, 0, 0x1c000
	s_add_u32 s64, s64, 0x40000
	s_addc_u32 s65, s65, 0
	s_mov_b32 m0, s71
	v_lshl_add_u64 v[200:201], s[64:65], 0, v[206:207]
	global_load_lds_dwordx4 v[200:201], off
	v_lshl_add_u64 v[200:201], s[64:65], 0, v[210:211]
	s_mov_b32 m0, s72
	s_nop 0
	global_load_lds_dwordx4 v[200:201], off
	v_add_u32_e32 v140, s94, v234
	v_add_u32_e32 v156, s95, v234
	ds_read_b128 v[128:131], v140
	ds_read_b128 v[132:135], v140 offset:1024
	ds_read_b128 v[136:139], v140 offset:2048
	ds_read_b128 v[140:143], v140 offset:3072
	ds_read_b128 v[144:147], v156
	ds_read_b128 v[148:151], v156 offset:1024
	ds_read_b128 v[152:155], v156 offset:2048
	ds_read_b128 v[156:159], v156 offset:3072
	ds_read_b128 v[160:163], v237 offset:32768
	ds_read_b128 v[164:167], v237 offset:33792
	ds_read_b128 v[168:171], v237 offset:34816
	ds_read_b128 v[172:175], v237 offset:35840
	ds_read_b128 v[176:179], v237 offset:36864
	ds_read_b128 v[180:183], v237 offset:37888
	ds_read_b128 v[184:187], v237 offset:38912
	ds_read_b128 v[188:191], v237 offset:39936
	s_waitcnt vmcnt(8)
	s_waitcnt lgkmcnt(0)
	s_setprio 1
	s_barrier
	v_mfma_f32_16x16x32_bf16 v[124:127], v[128:131], v[160:163], v[124:127]
	v_mfma_f32_16x16x32_bf16 v[120:123], v[136:139], v[160:163], v[120:123]
	v_mfma_f32_16x16x32_bf16 v[116:119], v[128:131], v[168:171], v[116:119]
	v_mfma_f32_16x16x32_bf16 v[112:115], v[136:139], v[168:171], v[112:115]
	v_mfma_f32_16x16x32_bf16 v[108:111], v[128:131], v[176:179], v[108:111]
	v_mfma_f32_16x16x32_bf16 v[100:103], v[136:139], v[176:179], v[100:103]
	v_mfma_f32_16x16x32_bf16 v[92:95], v[128:131], v[184:187], v[92:95]
	v_mfma_f32_16x16x32_bf16 v[80:83], v[136:139], v[184:187], v[80:83]
	v_mfma_f32_16x16x32_bf16 v[124:127], v[132:135], v[164:167], v[124:127]
	v_mfma_f32_16x16x32_bf16 v[120:123], v[140:143], v[164:167], v[120:123]
	v_mfma_f32_16x16x32_bf16 v[116:119], v[132:135], v[172:175], v[116:119]
	v_mfma_f32_16x16x32_bf16 v[112:115], v[140:143], v[172:175], v[112:115]
	v_mfma_f32_16x16x32_bf16 v[108:111], v[132:135], v[180:183], v[108:111]
	v_mfma_f32_16x16x32_bf16 v[100:103], v[140:143], v[180:183], v[100:103]
	v_mfma_f32_16x16x32_bf16 v[92:95], v[132:135], v[188:191], v[92:95]
	v_mfma_f32_16x16x32_bf16 v[80:83], v[140:143], v[188:191], v[80:83]
	s_setprio 0
	s_setprio 1
	v_mfma_f32_16x16x32_bf16 v[104:107], v[144:147], v[160:163], v[104:107]
	v_mfma_f32_16x16x32_bf16 v[96:99], v[152:155], v[160:163], v[96:99]
	v_mfma_f32_16x16x32_bf16 v[88:91], v[144:147], v[168:171], v[88:91]
	v_mfma_f32_16x16x32_bf16 v[84:87], v[152:155], v[168:171], v[84:87]
	v_mfma_f32_16x16x32_bf16 v[76:79], v[144:147], v[176:179], v[76:79]
	v_mfma_f32_16x16x32_bf16 v[72:75], v[152:155], v[176:179], v[72:75]
	v_mfma_f32_16x16x32_bf16 v[68:71], v[144:147], v[184:187], v[68:71]
	v_mfma_f32_16x16x32_bf16 v[64:67], v[152:155], v[184:187], v[64:67]
	v_mfma_f32_16x16x32_bf16 v[104:107], v[148:151], v[164:167], v[104:107]
	v_mfma_f32_16x16x32_bf16 v[96:99], v[156:159], v[164:167], v[96:99]
	v_mfma_f32_16x16x32_bf16 v[88:91], v[148:151], v[172:175], v[88:91]
	v_mfma_f32_16x16x32_bf16 v[84:87], v[156:159], v[172:175], v[84:87]
	v_mfma_f32_16x16x32_bf16 v[76:79], v[148:151], v[180:183], v[76:79]
	v_mfma_f32_16x16x32_bf16 v[72:75], v[156:159], v[180:183], v[72:75]
	v_mfma_f32_16x16x32_bf16 v[68:71], v[148:151], v[188:191], v[68:71]
	v_mfma_f32_16x16x32_bf16 v[64:67], v[156:159], v[188:191], v[64:67]
	s_barrier
	s_setprio 0
	s_add_i32 s64, s94, s68
	v_lshl_add_u64 v[192:193], v[192:193], 0, s[14:15]
	s_mov_b32 m0, s64
	s_nop 0
	global_load_lds_dwordx4 v[192:193], off
	s_add_i32 m0, s64, 0x2000
	s_add_u32 s62, s62, 0x40080
	v_lshl_add_u64 v[192:193], v[194:195], 0, s[14:15]
	s_addc_u32 s63, s63, 0
	s_add_i32 s64, s95, s68
	global_load_lds_dwordx4 v[192:193], off
	v_lshl_add_u64 v[192:193], s[62:63], 0, v[208:209]
	s_mov_b32 m0, s64
	s_nop 0
	global_load_lds_dwordx4 v[192:193], off
	v_lshl_add_u64 v[192:193], s[62:63], 0, v[212:213]
	s_add_i32 m0, s64, 0x2000
	s_nop 0
	global_load_lds_dwordx4 v[192:193], off
	v_lshl_add_u64 v[192:193], v[196:197], 0, s[14:15]
	s_mov_b32 m0, s76
	s_nop 0
	global_load_lds_dwordx4 v[192:193], off
	v_lshl_add_u64 v[192:193], v[198:199], 0, s[14:15]
	s_mov_b32 m0, s77
	s_nop 0
	global_load_lds_dwordx4 v[192:193], off
	ds_read_b128 v[160:163], v237 offset:49152
	ds_read_b128 v[164:167], v237 offset:50176
	ds_read_b128 v[168:171], v237 offset:51200
	ds_read_b128 v[172:175], v237 offset:52224
	ds_read_b128 v[176:179], v237 offset:53248
	ds_read_b128 v[180:183], v237 offset:54272
	ds_read_b128 v[184:187], v237 offset:55296
	ds_read_b128 v[188:191], v237 offset:56320
	s_waitcnt vmcnt(8)
	s_waitcnt lgkmcnt(0)
	s_setprio 1
	s_barrier
	v_mfma_f32_16x16x32_bf16 v[60:63], v[128:131], v[160:163], v[60:63]
	v_mfma_f32_16x16x32_bf16 v[56:59], v[136:139], v[160:163], v[56:59]
	v_mfma_f32_16x16x32_bf16 v[48:51], v[128:131], v[168:171], v[48:51]
	v_mfma_f32_16x16x32_bf16 v[40:43], v[136:139], v[168:171], v[40:43]
	v_mfma_f32_16x16x32_bf16 v[32:35], v[128:131], v[176:179], v[32:35]
	v_mfma_f32_16x16x32_bf16 v[24:27], v[136:139], v[176:179], v[24:27]
	v_mfma_f32_16x16x32_bf16 v[16:19], v[128:131], v[184:187], v[16:19]
	v_mfma_f32_16x16x32_bf16 v[8:11], v[136:139], v[184:187], v[8:11]
	v_mfma_f32_16x16x32_bf16 v[60:63], v[132:135], v[164:167], v[60:63]
	v_mfma_f32_16x16x32_bf16 v[56:59], v[140:143], v[164:167], v[56:59]
	v_mfma_f32_16x16x32_bf16 v[48:51], v[132:135], v[172:175], v[48:51]
	v_mfma_f32_16x16x32_bf16 v[40:43], v[140:143], v[172:175], v[40:43]
	v_mfma_f32_16x16x32_bf16 v[32:35], v[132:135], v[180:183], v[32:35]
	v_mfma_f32_16x16x32_bf16 v[24:27], v[140:143], v[180:183], v[24:27]
	v_mfma_f32_16x16x32_bf16 v[16:19], v[132:135], v[188:191], v[16:19]
	v_mfma_f32_16x16x32_bf16 v[8:11], v[140:143], v[188:191], v[8:11]
	s_setprio 0
	s_setprio 1
	v_mfma_f32_16x16x32_bf16 v[52:55], v[144:147], v[160:163], v[52:55]
	v_mfma_f32_16x16x32_bf16 v[44:47], v[152:155], v[160:163], v[44:47]
	v_mfma_f32_16x16x32_bf16 v[36:39], v[144:147], v[168:171], v[36:39]
	v_mfma_f32_16x16x32_bf16 v[28:31], v[152:155], v[168:171], v[28:31]
	v_mfma_f32_16x16x32_bf16 v[20:23], v[144:147], v[176:179], v[20:23]
	v_mfma_f32_16x16x32_bf16 v[12:15], v[152:155], v[176:179], v[12:15]
	v_mfma_f32_16x16x32_bf16 v[4:7], v[144:147], v[184:187], v[4:7]
	v_mfma_f32_16x16x32_bf16 v[0:3], v[152:155], v[184:187], v[0:3]
	v_mfma_f32_16x16x32_bf16 v[52:55], v[148:151], v[164:167], v[52:55]
	v_mfma_f32_16x16x32_bf16 v[44:47], v[156:159], v[164:167], v[44:47]
	v_mfma_f32_16x16x32_bf16 v[36:39], v[148:151], v[172:175], v[36:39]
	v_mfma_f32_16x16x32_bf16 v[28:31], v[156:159], v[172:175], v[28:31]
	v_mfma_f32_16x16x32_bf16 v[20:23], v[148:151], v[180:183], v[20:23]
	v_mfma_f32_16x16x32_bf16 v[12:15], v[156:159], v[180:183], v[12:15]
	v_mfma_f32_16x16x32_bf16 v[4:7], v[148:151], v[188:191], v[4:7]
	v_mfma_f32_16x16x32_bf16 v[0:3], v[156:159], v[188:191], v[0:3]
	s_barrier
	s_setprio 0
	s_add_i32 s93, s93, 2
	s_add_u32 s48, s48, 0x100
	s_addc_u32 s49, s49, 0
	s_add_u32 s60, s60, 0x100
	s_addc_u32 s61, s61, 0
	s_cmp_gt_u32 s93, 13
	s_cbranch_scc0 .LBB0_723
	s_and_b64 vcc, exec, s[16:17]
	s_cbranch_vccz .LBB0_726
	s_barrier

.LBB0_843:
	s_mov_b32 s101, 0
	s_andn2_b64 vcc, exec, s[12:13]
	s_cbranch_vccnz .LBB0_718
	s_mov_b32 s101, 1
	s_branch .LBB0_718

.LBB0_1099:
	s_lshl_b32 s42, s6, 6
	s_lshl_b32 s15, s6, 13
	s_lshl_b32 s6, s7, 5
	s_mov_b64 s[12:13], 0x80
	s_and_b32 s43, s6, 0x60
	s_add_i32 m0, s27, 0x18000
	v_lshl_add_u64 v[6:7], v[6:7], 0, s[12:13]
	s_lshl_b32 s16, s43, 7
	s_waitcnt vmcnt(2)
	s_barrier
	global_load_lds_dwordx4 v[6:7], off
	v_lshl_add_u64 v[4:5], v[4:5], 0, s[12:13]
	s_add_i32 m0, s27, 0x1a000
	s_add_i32 s46, s27, 0x8000
	s_add_i32 s47, s27, 0xa000
	global_load_lds_dwordx4 v[4:5], off
	v_lshl_add_u64 v[0:1], v[0:1], 0, s[12:13]
	s_mov_b32 m0, s46
	s_add_u32 s6, s30, 0x40080
	global_load_lds_dwordx4 v[0:1], off
	v_lshl_add_u64 v[0:1], v[2:3], 0, s[12:13]
	s_mov_b32 m0, s47
	s_addc_u32 s7, s31, 0
	global_load_lds_dwordx4 v[0:1], off
	s_add_i32 m0, s27, 0x1c000
	v_lshl_add_u64 v[0:1], s[6:7], 0, v[194:195]
	global_load_lds_dwordx4 v[0:1], off
	v_lshl_add_u64 v[0:1], s[6:7], 0, v[198:199]
	s_add_i32 m0, s27, 0x1e000
	v_bfe_u32 v243, v8, 4, 2
	global_load_lds_dwordx4 v[0:1], off
	v_and_b32_e32 v244, 15, v8
	v_lshlrev_b32_e32 v0, 4, v243
	v_lshlrev_b32_e32 v1, 2, v8
	v_lshl_or_b32 v0, v244, 6, v0
	v_and_b32_e32 v1, 32, v1
	v_bitop3_b32 v2, v0, s15, v1 bitop3:0xde
	v_bitop3_b32 v245, v0, s16, v1 bitop3:0xde
	v_lshlrev_b32_e32 v0, 14, v9
	v_and_b32_e32 v0, 0xffff8000, v0
	v_lshl_add_u32 v0, v10, 11, v0
	v_and_b32_e32 v1, 1, v9
	v_lshl_or_b32 v0, v1, 6, v0
	v_lshl_add_u32 v200, v11, 1, v0
	v_lshlrev_b32_e32 v0, 14, v12
	v_and_b32_e32 v0, 0xffff8000, v0
	s_waitcnt vmcnt(6)
	s_cmpk_lt_u32 s14, 0x100
	v_lshl_add_u32 v0, v13, 11, v0
	v_and_b32_e32 v1, 1, v12
	s_cselect_b64 s[14:15], -1, 0
	v_lshl_or_b32 v0, v1, 6, v0
	s_add_i32 s51, 0, 0x10000
	s_add_i32 s60, 0, 0x14000
	s_ashr_i32 s48, s52, 31
	s_mov_b32 s49, s52
	s_ashr_i32 s50, s33, 31
	v_mov_b32_e32 v201, v195
	v_lshl_add_u32 v202, v14, 1, v0
	v_mov_b32_e32 v203, v195
	v_mov_b64_e32 v[204:205], 0x1ff
	v_add_u32_e32 v246, s51, v245
	v_add_u32_e32 v247, s60, v245
	v_add_u32_e32 v248, 0, v2
	s_barrier
	s_mov_b32 s101, 0
	s_branch .LBB0_1102

.LBB0_1108:
	s_ashr_i32 s19, s18, 31
	s_lshl_b64 s[20:21], s[18:19], 19
	s_add_u32 s20, s2, s20
	s_addc_u32 s21, s4, s21
	s_and_b64 s[22:23], s[6:7], exec
	s_cselect_b32 s19, s21, s29
	s_cselect_b32 s25, s20, s28
	s_ashr_i32 s17, s16, 31
	s_lshl_b64 s[22:23], s[16:17], 19
	s_add_u32 s22, s5, s22
	s_addc_u32 s23, s36, s23
	s_and_b64 s[34:35], s[6:7], exec
	s_cselect_b32 s17, s23, s31
	s_cselect_b32 s61, s22, s30
	s_add_u32 s28, s28, 0x40080
	s_addc_u32 s29, s29, 0
	s_add_u32 s62, s30, 0x100
	v_mov_b32_e32 v0, 0
	s_addc_u32 s63, s31, 0
	s_mov_b32 s64, -2
	s_cmp_lg_u32 s101, 0
	s_cbranch_scc0 .Lph1109_a
	v_mov_b32_e32 v1, v0
	v_mov_b32_e32 v2, v0
	v_mov_b32_e32 v3, v0
	v_mov_b32_e32 v4, v0
	v_mov_b32_e32 v5, v0
	v_mov_b32_e32 v6, v0
	v_mov_b32_e32 v7, v0
	v_mov_b32_e32 v16, v0
	v_mov_b32_e32 v17, v0
	v_mov_b32_e32 v18, v0
	v_mov_b32_e32 v19, v0
	v_mov_b32_e32 v20, v0
	v_mov_b32_e32 v21, v0
	v_mov_b32_e32 v22, v0
	v_mov_b32_e32 v23, v0
	v_mov_b32_e32 v32, v0
	v_mov_b32_e32 v33, v0
	v_mov_b32_e32 v34, v0
	v_mov_b32_e32 v35, v0
	v_mov_b32_e32 v36, v0
	v_mov_b32_e32 v37, v0
	v_mov_b32_e32 v38, v0
	v_mov_b32_e32 v39, v0
	v_mov_b32_e32 v48, v0
	v_mov_b32_e32 v49, v0
	v_mov_b32_e32 v50, v0
	v_mov_b32_e32 v51, v0
	v_mov_b32_e32 v52, v0
	v_mov_b32_e32 v53, v0
	v_mov_b32_e32 v54, v0
	v_mov_b32_e32 v55, v0
	v_mov_b32_e32 v8, v0
	v_mov_b32_e32 v9, v0
	v_mov_b32_e32 v10, v0
	v_mov_b32_e32 v11, v0
	v_mov_b32_e32 v12, v0
	v_mov_b32_e32 v13, v0
	v_mov_b32_e32 v14, v0
	v_mov_b32_e32 v15, v0
	v_mov_b32_e32 v24, v0
	v_mov_b32_e32 v25, v0
	v_mov_b32_e32 v26, v0
	v_mov_b32_e32 v27, v0
	v_mov_b32_e32 v28, v0
	v_mov_b32_e32 v29, v0
	v_mov_b32_e32 v30, v0
	v_mov_b32_e32 v31, v0
	v_mov_b32_e32 v40, v0
	v_mov_b32_e32 v41, v0
	v_mov_b32_e32 v42, v0
	v_mov_b32_e32 v43, v0
	v_mov_b32_e32 v44, v0
	v_mov_b32_e32 v45, v0
	v_mov_b32_e32 v46, v0
	v_mov_b32_e32 v47, v0
	v_mov_b32_e32 v56, v0
	v_mov_b32_e32 v57, v0
	v_mov_b32_e32 v58, v0
	v_mov_b32_e32 v59, v0
	v_mov_b32_e32 v60, v0
	v_mov_b32_e32 v61, v0
	v_mov_b32_e32 v62, v0
	v_mov_b32_e32 v63, v0
	v_mov_b32_e32 v64, v0
	v_mov_b32_e32 v65, v0
	v_mov_b32_e32 v66, v0
	v_mov_b32_e32 v67, v0
	v_mov_b32_e32 v68, v0
	v_mov_b32_e32 v69, v0
	v_mov_b32_e32 v70, v0
	v_mov_b32_e32 v71, v0
	v_mov_b32_e32 v80, v0
	v_mov_b32_e32 v81, v0
	v_mov_b32_e32 v82, v0
	v_mov_b32_e32 v83, v0
	v_mov_b32_e32 v84, v0
	v_mov_b32_e32 v85, v0
	v_mov_b32_e32 v86, v0
	v_mov_b32_e32 v87, v0
	v_mov_b32_e32 v96, v0
	v_mov_b32_e32 v97, v0
	v_mov_b32_e32 v98, v0
	v_mov_b32_e32 v99, v0
	v_mov_b32_e32 v100, v0
	v_mov_b32_e32 v101, v0
	v_mov_b32_e32 v102, v0
	v_mov_b32_e32 v103, v0
	v_mov_b32_e32 v112, v0
	v_mov_b32_e32 v113, v0
	v_mov_b32_e32 v114, v0
	v_mov_b32_e32 v115, v0
	v_mov_b32_e32 v116, v0
	v_mov_b32_e32 v117, v0
	v_mov_b32_e32 v118, v0
	v_mov_b32_e32 v119, v0
	v_mov_b32_e32 v72, v0
	v_mov_b32_e32 v73, v0
	v_mov_b32_e32 v74, v0
	v_mov_b32_e32 v75, v0
	v_mov_b32_e32 v76, v0
	v_mov_b32_e32 v77, v0
	v_mov_b32_e32 v78, v0
	v_mov_b32_e32 v79, v0
	v_mov_b32_e32 v88, v0
	v_mov_b32_e32 v89, v0
	v_mov_b32_e32 v90, v0
	v_mov_b32_e32 v91, v0
	v_mov_b32_e32 v92, v0
	v_mov_b32_e32 v93, v0
	v_mov_b32_e32 v94, v0
	v_mov_b32_e32 v95, v0
	v_mov_b32_e32 v104, v0
	v_mov_b32_e32 v105, v0
	v_mov_b32_e32 v106, v0
	v_mov_b32_e32 v107, v0
	v_mov_b32_e32 v108, v0
	v_mov_b32_e32 v109, v0
	v_mov_b32_e32 v110, v0
	v_mov_b32_e32 v111, v0
	v_mov_b32_e32 v136, v0
	v_mov_b32_e32 v137, v0
	v_mov_b32_e32 v138, v0
	v_mov_b32_e32 v139, v0
	v_mov_b32_e32 v144, v0
	v_mov_b32_e32 v145, v0
	v_mov_b32_e32 v146, v0
	v_mov_b32_e32 v147, v0
	s_barrier
	s_mov_b32 s101, 0
	s_branch .LBB0_1109
.Lph1109_a:
	s_add_u32 s30, s28, 0xfffc0080
	s_addc_u32 s31, s29, -1
	s_cmp_eq_u32 s64, 12
	s_cselect_b32 s35, s19, s31
	s_cselect_b32 s34, s25, s30
	s_cselect_b32 s31, s17, s63
	s_cselect_b32 s30, s61, s62
	v_lshl_add_u64 v[206:207], s[28:29], 0, v[200:201]
	s_add_i32 m0, s27, 0xc000
	s_nop 0
	global_load_lds_dwordx4 v[206:207], off
	v_lshl_add_u64 v[206:207], s[28:29], 0, v[202:203]
	s_add_i32 m0, s27, 0xe000
	s_nop 0
	global_load_lds_dwordx4 v[206:207], off
	ds_read_b128 v[120:123], v246
	ds_read_b128 v[124:127], v246 offset:1024
	ds_read_b128 v[128:131], v246 offset:2048
	ds_read_b128 v[132:135], v246 offset:3072
	ds_read_b128 v[140:143], v247
	ds_read_b128 v[148:151], v247 offset:1024
	ds_read_b128 v[152:155], v247 offset:2048
	ds_read_b128 v[156:159], v247 offset:3072
	ds_read_b128 v[160:163], v248
	ds_read_b128 v[164:167], v248 offset:1024
	ds_read_b128 v[168:171], v248 offset:2048
	ds_read_b128 v[172:175], v248 offset:3072
	ds_read_b128 v[176:179], v248 offset:4096
	ds_read_b128 v[180:183], v248 offset:5120
	ds_read_b128 v[184:187], v248 offset:6144
	ds_read_b128 v[188:191], v248 offset:7168
	v_mov_b32_e32 v1, v0
	v_mov_b32_e32 v2, v0
	v_mov_b32_e32 v3, v0
	v_mov_b32_e32 v4, v0
	v_mov_b32_e32 v5, v0
	v_mov_b32_e32 v6, v0
	v_mov_b32_e32 v7, v0
	v_mov_b32_e32 v16, v0
	v_mov_b32_e32 v17, v0
	v_mov_b32_e32 v18, v0
	v_mov_b32_e32 v19, v0
	v_mov_b32_e32 v20, v0
	v_mov_b32_e32 v21, v0
	v_mov_b32_e32 v22, v0
	v_mov_b32_e32 v23, v0
	v_mov_b32_e32 v32, v0
	v_mov_b32_e32 v33, v0
	v_mov_b32_e32 v34, v0
	v_mov_b32_e32 v35, v0
	v_mov_b32_e32 v36, v0
	v_mov_b32_e32 v37, v0
	v_mov_b32_e32 v38, v0
	v_mov_b32_e32 v39, v0
	v_mov_b32_e32 v48, v0
	v_mov_b32_e32 v49, v0
	v_mov_b32_e32 v50, v0
	v_mov_b32_e32 v51, v0
	v_mov_b32_e32 v52, v0
	v_mov_b32_e32 v53, v0
	v_mov_b32_e32 v54, v0
	v_mov_b32_e32 v55, v0
	v_mov_b32_e32 v8, v0
	v_mov_b32_e32 v9, v0
	v_mov_b32_e32 v10, v0
	v_mov_b32_e32 v11, v0
	v_mov_b32_e32 v12, v0
	v_mov_b32_e32 v13, v0
	v_mov_b32_e32 v14, v0
	v_mov_b32_e32 v15, v0
	v_mov_b32_e32 v24, v0
	v_mov_b32_e32 v25, v0
	v_mov_b32_e32 v26, v0
	v_mov_b32_e32 v27, v0
	v_mov_b32_e32 v28, v0
	v_mov_b32_e32 v29, v0
	v_mov_b32_e32 v30, v0
	v_mov_b32_e32 v31, v0
	v_mov_b32_e32 v40, v0
	v_mov_b32_e32 v41, v0
	v_mov_b32_e32 v42, v0
	v_mov_b32_e32 v43, v0
	v_mov_b32_e32 v44, v0
	v_mov_b32_e32 v45, v0
	v_mov_b32_e32 v46, v0
	v_mov_b32_e32 v47, v0
	v_mov_b32_e32 v56, v0
	v_mov_b32_e32 v57, v0
	v_mov_b32_e32 v58, v0
	v_mov_b32_e32 v59, v0
	v_mov_b32_e32 v60, v0
	v_mov_b32_e32 v61, v0
	v_mov_b32_e32 v62, v0
	v_mov_b32_e32 v63, v0
	v_mov_b32_e32 v64, v0
	v_mov_b32_e32 v65, v0
	v_mov_b32_e32 v66, v0
	v_mov_b32_e32 v67, v0
	v_mov_b32_e32 v68, v0
	v_mov_b32_e32 v69, v0
	v_mov_b32_e32 v70, v0
	v_mov_b32_e32 v71, v0
	v_mov_b32_e32 v80, v0
	v_mov_b32_e32 v81, v0
	v_mov_b32_e32 v82, v0
	v_mov_b32_e32 v83, v0
	v_mov_b32_e32 v84, v0
	v_mov_b32_e32 v85, v0
	v_mov_b32_e32 v86, v0
	v_mov_b32_e32 v87, v0
	v_mov_b32_e32 v96, v0
	v_mov_b32_e32 v97, v0
	v_mov_b32_e32 v98, v0
	v_mov_b32_e32 v99, v0
	v_mov_b32_e32 v100, v0
	v_mov_b32_e32 v101, v0
	v_mov_b32_e32 v102, v0
	v_mov_b32_e32 v103, v0
	v_mov_b32_e32 v112, v0
	v_mov_b32_e32 v113, v0
	v_mov_b32_e32 v114, v0
	v_mov_b32_e32 v115, v0
	v_mov_b32_e32 v116, v0
	v_mov_b32_e32 v117, v0
	v_mov_b32_e32 v118, v0
	v_mov_b32_e32 v119, v0
	v_mov_b32_e32 v72, v0
	v_mov_b32_e32 v73, v0
	v_mov_b32_e32 v74, v0
	v_mov_b32_e32 v75, v0
	v_mov_b32_e32 v76, v0
	v_mov_b32_e32 v77, v0
	v_mov_b32_e32 v78, v0
	v_mov_b32_e32 v79, v0
	v_mov_b32_e32 v88, v0
	v_mov_b32_e32 v89, v0
	v_mov_b32_e32 v90, v0
	v_mov_b32_e32 v91, v0
	v_mov_b32_e32 v92, v0
	v_mov_b32_e32 v93, v0
	v_mov_b32_e32 v94, v0
	v_mov_b32_e32 v95, v0
	v_mov_b32_e32 v104, v0
	v_mov_b32_e32 v105, v0
	v_mov_b32_e32 v106, v0
	v_mov_b32_e32 v107, v0
	v_mov_b32_e32 v108, v0
	v_mov_b32_e32 v109, v0
	v_mov_b32_e32 v110, v0
	v_mov_b32_e32 v111, v0
	v_mov_b32_e32 v136, v0
	v_mov_b32_e32 v137, v0
	v_mov_b32_e32 v138, v0
	v_mov_b32_e32 v139, v0
	v_mov_b32_e32 v144, v0
	v_mov_b32_e32 v145, v0
	v_mov_b32_e32 v146, v0
	v_mov_b32_e32 v147, v0
	s_branch .Lph1109_w

.Lph1109_w:
	s_nop 0
	s_nop 0
	s_nop 0
	s_waitcnt vmcnt(8)
	s_waitcnt lgkmcnt(0)
	s_setprio 1
	s_barrier
	v_mfma_f32_16x16x32_bf16 v[144:147], v[120:123], v[160:163], v[144:147]
	v_mfma_f32_16x16x32_bf16 v[136:139], v[128:131], v[160:163], v[136:139]
	v_mfma_f32_16x16x32_bf16 v[108:111], v[120:123], v[168:171], v[108:111]
	v_mfma_f32_16x16x32_bf16 v[104:107], v[128:131], v[168:171], v[104:107]
	v_mfma_f32_16x16x32_bf16 v[92:95], v[120:123], v[176:179], v[92:95]
	v_mfma_f32_16x16x32_bf16 v[88:91], v[128:131], v[176:179], v[88:91]
	v_mfma_f32_16x16x32_bf16 v[76:79], v[120:123], v[184:187], v[76:79]
	v_mfma_f32_16x16x32_bf16 v[72:75], v[128:131], v[184:187], v[72:75]
	v_mfma_f32_16x16x32_bf16 v[144:147], v[124:127], v[164:167], v[144:147]
	v_mfma_f32_16x16x32_bf16 v[136:139], v[132:135], v[164:167], v[136:139]
	v_mfma_f32_16x16x32_bf16 v[108:111], v[124:127], v[172:175], v[108:111]
	v_mfma_f32_16x16x32_bf16 v[104:107], v[132:135], v[172:175], v[104:107]
	v_mfma_f32_16x16x32_bf16 v[92:95], v[124:127], v[180:183], v[92:95]
	v_mfma_f32_16x16x32_bf16 v[88:91], v[132:135], v[180:183], v[88:91]
	v_mfma_f32_16x16x32_bf16 v[76:79], v[124:127], v[188:191], v[76:79]
	v_mfma_f32_16x16x32_bf16 v[72:75], v[132:135], v[188:191], v[72:75]
	s_setprio 0
	s_setprio 1
	v_mfma_f32_16x16x32_bf16 v[116:119], v[140:143], v[160:163], v[116:119]
	v_mfma_f32_16x16x32_bf16 v[112:115], v[152:155], v[160:163], v[112:115]
	v_mfma_f32_16x16x32_bf16 v[100:103], v[140:143], v[168:171], v[100:103]
	v_mfma_f32_16x16x32_bf16 v[96:99], v[152:155], v[168:171], v[96:99]
	v_mfma_f32_16x16x32_bf16 v[84:87], v[140:143], v[176:179], v[84:87]
	v_mfma_f32_16x16x32_bf16 v[80:83], v[152:155], v[176:179], v[80:83]
	v_mfma_f32_16x16x32_bf16 v[68:71], v[140:143], v[184:187], v[68:71]
	v_mfma_f32_16x16x32_bf16 v[64:67], v[152:155], v[184:187], v[64:67]
	v_mfma_f32_16x16x32_bf16 v[116:119], v[148:151], v[164:167], v[116:119]
	v_mfma_f32_16x16x32_bf16 v[112:115], v[156:159], v[164:167], v[112:115]
	v_mfma_f32_16x16x32_bf16 v[100:103], v[148:151], v[172:175], v[100:103]
	v_mfma_f32_16x16x32_bf16 v[96:99], v[156:159], v[172:175], v[96:99]
	v_mfma_f32_16x16x32_bf16 v[84:87], v[148:151], v[180:183], v[84:87]
	v_mfma_f32_16x16x32_bf16 v[80:83], v[156:159], v[180:183], v[80:83]
	v_mfma_f32_16x16x32_bf16 v[68:71], v[148:151], v[188:191], v[68:71]
	v_mfma_f32_16x16x32_bf16 v[64:67], v[156:159], v[188:191], v[64:67]
	s_barrier
	s_setprio 0
	s_add_i32 s65, s51, s37
	v_lshl_add_u64 v[206:207], s[30:31], 0, v[194:195]
	s_mov_b32 m0, s65
	s_nop 0
	global_load_lds_dwordx4 v[206:207], off
	s_add_i32 m0, s65, 0x2000
	s_add_u32 s66, s30, 0x40000
	v_lshl_add_u64 v[208:209], s[30:31], 0, v[198:199]
	s_addc_u32 s67, s31, 0
	s_add_i32 s65, s60, s37
	global_load_lds_dwordx4 v[208:209], off
	v_lshl_add_u64 v[210:211], s[66:67], 0, v[194:195]
	s_mov_b32 m0, s65
	v_lshl_add_u64 v[212:213], s[34:35], 0, v[196:197]
	global_load_lds_dwordx4 v[210:211], off
	v_lshl_add_u64 v[210:211], s[66:67], 0, v[198:199]
	s_add_i32 m0, s65, 0x2000
	s_nop 0
	global_load_lds_dwordx4 v[210:211], off
	v_lshl_add_u64 v[210:211], s[34:35], 0, v[192:193]
	s_mov_b32 m0, s27
	s_nop 0
	global_load_lds_dwordx4 v[210:211], off
	s_mov_b32 m0, s38
	s_nop 0
	global_load_lds_dwordx4 v[212:213], off
	ds_read_b128 v[160:163], v248 offset:16384
	ds_read_b128 v[164:167], v248 offset:17408
	ds_read_b128 v[168:171], v248 offset:18432
	ds_read_b128 v[172:175], v248 offset:19456
	ds_read_b128 v[176:179], v248 offset:20480
	ds_read_b128 v[180:183], v248 offset:21504
	ds_read_b128 v[184:187], v248 offset:22528
	ds_read_b128 v[188:191], v248 offset:23552
	s_nop 0
	s_waitcnt vmcnt(8)
	s_waitcnt lgkmcnt(0)
	s_setprio 1
	s_barrier
	v_mfma_f32_16x16x32_bf16 v[60:63], v[120:123], v[160:163], v[60:63]
	v_mfma_f32_16x16x32_bf16 v[56:59], v[128:131], v[160:163], v[56:59]
	v_mfma_f32_16x16x32_bf16 v[44:47], v[120:123], v[168:171], v[44:47]
	v_mfma_f32_16x16x32_bf16 v[40:43], v[128:131], v[168:171], v[40:43]
	v_mfma_f32_16x16x32_bf16 v[28:31], v[120:123], v[176:179], v[28:31]
	v_mfma_f32_16x16x32_bf16 v[24:27], v[128:131], v[176:179], v[24:27]
	v_mfma_f32_16x16x32_bf16 v[12:15], v[120:123], v[184:187], v[12:15]
	v_mfma_f32_16x16x32_bf16 v[8:11], v[128:131], v[184:187], v[8:11]
	v_mfma_f32_16x16x32_bf16 v[60:63], v[124:127], v[164:167], v[60:63]
	v_mfma_f32_16x16x32_bf16 v[56:59], v[132:135], v[164:167], v[56:59]
	v_mfma_f32_16x16x32_bf16 v[44:47], v[124:127], v[172:175], v[44:47]
	v_mfma_f32_16x16x32_bf16 v[40:43], v[132:135], v[172:175], v[40:43]
	v_mfma_f32_16x16x32_bf16 v[28:31], v[124:127], v[180:183], v[28:31]
	v_mfma_f32_16x16x32_bf16 v[24:27], v[132:135], v[180:183], v[24:27]
	v_mfma_f32_16x16x32_bf16 v[12:15], v[124:127], v[188:191], v[12:15]
	v_mfma_f32_16x16x32_bf16 v[8:11], v[132:135], v[188:191], v[8:11]
	s_setprio 0
	s_setprio 1
	v_mfma_f32_16x16x32_bf16 v[52:55], v[140:143], v[160:163], v[52:55]
	v_mfma_f32_16x16x32_bf16 v[48:51], v[152:155], v[160:163], v[48:51]
	v_mfma_f32_16x16x32_bf16 v[36:39], v[140:143], v[168:171], v[36:39]
	v_mfma_f32_16x16x32_bf16 v[32:35], v[152:155], v[168:171], v[32:35]
	v_mfma_f32_16x16x32_bf16 v[20:23], v[140:143], v[176:179], v[20:23]
	v_mfma_f32_16x16x32_bf16 v[16:19], v[152:155], v[176:179], v[16:19]
	v_mfma_f32_16x16x32_bf16 v[4:7], v[140:143], v[184:187], v[4:7]
	v_mfma_f32_16x16x32_bf16 v[0:3], v[152:155], v[184:187], v[0:3]
	v_mfma_f32_16x16x32_bf16 v[52:55], v[148:151], v[164:167], v[52:55]
	v_mfma_f32_16x16x32_bf16 v[48:51], v[156:159], v[164:167], v[48:51]
	v_mfma_f32_16x16x32_bf16 v[36:39], v[148:151], v[172:175], v[36:39]
	v_mfma_f32_16x16x32_bf16 v[32:35], v[156:159], v[172:175], v[32:35]
	v_mfma_f32_16x16x32_bf16 v[20:23], v[148:151], v[180:183], v[20:23]
	v_mfma_f32_16x16x32_bf16 v[16:19], v[156:159], v[180:183], v[16:19]
	v_mfma_f32_16x16x32_bf16 v[4:7], v[148:151], v[188:191], v[4:7]
	v_mfma_f32_16x16x32_bf16 v[0:3], v[156:159], v[188:191], v[0:3]
	s_barrier
	s_setprio 0
	s_add_i32 s65, 0, 0x18000
	s_add_i32 s66, 0, 0x1c000
	s_add_u32 s34, s34, 0x40000
	s_addc_u32 s35, s35, 0
	s_mov_b32 m0, s39
	v_lshl_add_u64 v[214:215], s[34:35], 0, v[192:193]
	global_load_lds_dwordx4 v[214:215], off
	v_lshl_add_u64 v[214:215], s[34:35], 0, v[196:197]
	s_mov_b32 m0, s40
	s_nop 0
	global_load_lds_dwordx4 v[214:215], off
	v_add_u32_e32 v132, s65, v245
	v_add_u32_e32 v156, s66, v245
	ds_read_b128 v[120:123], v132
	ds_read_b128 v[124:127], v132 offset:1024
	ds_read_b128 v[128:131], v132 offset:2048
	ds_read_b128 v[132:135], v132 offset:3072
	ds_read_b128 v[140:143], v156
	ds_read_b128 v[148:151], v156 offset:1024
	ds_read_b128 v[152:155], v156 offset:2048
	ds_read_b128 v[156:159], v156 offset:3072
	ds_read_b128 v[160:163], v248 offset:32768
	ds_read_b128 v[164:167], v248 offset:33792
	ds_read_b128 v[168:171], v248 offset:34816
	ds_read_b128 v[172:175], v248 offset:35840
	ds_read_b128 v[176:179], v248 offset:36864
	ds_read_b128 v[180:183], v248 offset:37888
	ds_read_b128 v[184:187], v248 offset:38912
	ds_read_b128 v[188:191], v248 offset:39936
	s_waitcnt vmcnt(8)
	s_waitcnt lgkmcnt(0)
	s_setprio 1
	s_barrier
	v_mfma_f32_16x16x32_bf16 v[144:147], v[120:123], v[160:163], v[144:147]
	v_mfma_f32_16x16x32_bf16 v[136:139], v[128:131], v[160:163], v[136:139]
	v_mfma_f32_16x16x32_bf16 v[108:111], v[120:123], v[168:171], v[108:111]
	v_mfma_f32_16x16x32_bf16 v[104:107], v[128:131], v[168:171], v[104:107]
	v_mfma_f32_16x16x32_bf16 v[92:95], v[120:123], v[176:179], v[92:95]
	v_mfma_f32_16x16x32_bf16 v[88:91], v[128:131], v[176:179], v[88:91]
	v_mfma_f32_16x16x32_bf16 v[76:79], v[120:123], v[184:187], v[76:79]
	v_mfma_f32_16x16x32_bf16 v[72:75], v[128:131], v[184:187], v[72:75]
	v_mfma_f32_16x16x32_bf16 v[144:147], v[124:127], v[164:167], v[144:147]
	v_mfma_f32_16x16x32_bf16 v[136:139], v[132:135], v[164:167], v[136:139]
	v_mfma_f32_16x16x32_bf16 v[108:111], v[124:127], v[172:175], v[108:111]
	v_mfma_f32_16x16x32_bf16 v[104:107], v[132:135], v[172:175], v[104:107]
	v_mfma_f32_16x16x32_bf16 v[92:95], v[124:127], v[180:183], v[92:95]
	v_mfma_f32_16x16x32_bf16 v[88:91], v[132:135], v[180:183], v[88:91]
	v_mfma_f32_16x16x32_bf16 v[76:79], v[124:127], v[188:191], v[76:79]
	v_mfma_f32_16x16x32_bf16 v[72:75], v[132:135], v[188:191], v[72:75]
	s_setprio 0
	s_setprio 1
	v_mfma_f32_16x16x32_bf16 v[116:119], v[140:143], v[160:163], v[116:119]
	v_mfma_f32_16x16x32_bf16 v[112:115], v[152:155], v[160:163], v[112:115]
	v_mfma_f32_16x16x32_bf16 v[100:103], v[140:143], v[168:171], v[100:103]
	v_mfma_f32_16x16x32_bf16 v[96:99], v[152:155], v[168:171], v[96:99]
	v_mfma_f32_16x16x32_bf16 v[84:87], v[140:143], v[176:179], v[84:87]
	v_mfma_f32_16x16x32_bf16 v[80:83], v[152:155], v[176:179], v[80:83]
	v_mfma_f32_16x16x32_bf16 v[68:71], v[140:143], v[184:187], v[68:71]
	v_mfma_f32_16x16x32_bf16 v[64:67], v[152:155], v[184:187], v[64:67]
	v_mfma_f32_16x16x32_bf16 v[116:119], v[148:151], v[164:167], v[116:119]
	v_mfma_f32_16x16x32_bf16 v[112:115], v[156:159], v[164:167], v[112:115]
	v_mfma_f32_16x16x32_bf16 v[100:103], v[148:151], v[172:175], v[100:103]
	v_mfma_f32_16x16x32_bf16 v[96:99], v[156:159], v[172:175], v[96:99]
	v_mfma_f32_16x16x32_bf16 v[84:87], v[148:151], v[180:183], v[84:87]
	v_mfma_f32_16x16x32_bf16 v[80:83], v[156:159], v[180:183], v[80:83]
	v_mfma_f32_16x16x32_bf16 v[68:71], v[148:151], v[188:191], v[68:71]
	v_mfma_f32_16x16x32_bf16 v[64:67], v[156:159], v[188:191], v[64:67]
	s_barrier
	s_setprio 0
	s_add_i32 s34, s65, s37
	v_lshl_add_u64 v[206:207], v[206:207], 0, s[12:13]
	s_mov_b32 m0, s34
	s_nop 0
	global_load_lds_dwordx4 v[206:207], off
	s_add_i32 m0, s34, 0x2000
	s_add_u32 s30, s30, 0x40080
	v_lshl_add_u64 v[206:207], v[208:209], 0, s[12:13]
	s_addc_u32 s31, s31, 0
	s_add_i32 s34, s66, s37
	global_load_lds_dwordx4 v[206:207], off
	v_lshl_add_u64 v[206:207], s[30:31], 0, v[194:195]
	s_mov_b32 m0, s34
	s_nop 0
	global_load_lds_dwordx4 v[206:207], off
	v_lshl_add_u64 v[206:207], s[30:31], 0, v[198:199]
	s_add_i32 m0, s34, 0x2000
	s_nop 0
	global_load_lds_dwordx4 v[206:207], off
	v_lshl_add_u64 v[206:207], v[210:211], 0, s[12:13]
	s_mov_b32 m0, s46
	s_nop 0
	global_load_lds_dwordx4 v[206:207], off
	v_lshl_add_u64 v[206:207], v[212:213], 0, s[12:13]
	s_mov_b32 m0, s47
	s_nop 0
	global_load_lds_dwordx4 v[206:207], off
	ds_read_b128 v[160:163], v248 offset:49152
	ds_read_b128 v[164:167], v248 offset:50176
	ds_read_b128 v[168:171], v248 offset:51200
	ds_read_b128 v[172:175], v248 offset:52224
	ds_read_b128 v[176:179], v248 offset:53248
	ds_read_b128 v[180:183], v248 offset:54272
	ds_read_b128 v[184:187], v248 offset:55296
	ds_read_b128 v[188:191], v248 offset:56320
	s_waitcnt vmcnt(8)
	s_waitcnt lgkmcnt(0)
	s_setprio 1
	s_barrier
	v_mfma_f32_16x16x32_bf16 v[60:63], v[120:123], v[160:163], v[60:63]
	v_mfma_f32_16x16x32_bf16 v[56:59], v[128:131], v[160:163], v[56:59]
	v_mfma_f32_16x16x32_bf16 v[44:47], v[120:123], v[168:171], v[44:47]
	v_mfma_f32_16x16x32_bf16 v[40:43], v[128:131], v[168:171], v[40:43]
	v_mfma_f32_16x16x32_bf16 v[28:31], v[120:123], v[176:179], v[28:31]
	v_mfma_f32_16x16x32_bf16 v[24:27], v[128:131], v[176:179], v[24:27]
	v_mfma_f32_16x16x32_bf16 v[12:15], v[120:123], v[184:187], v[12:15]
	v_mfma_f32_16x16x32_bf16 v[8:11], v[128:131], v[184:187], v[8:11]
	v_mfma_f32_16x16x32_bf16 v[60:63], v[124:127], v[164:167], v[60:63]
	v_mfma_f32_16x16x32_bf16 v[56:59], v[132:135], v[164:167], v[56:59]
	v_mfma_f32_16x16x32_bf16 v[44:47], v[124:127], v[172:175], v[44:47]
	v_mfma_f32_16x16x32_bf16 v[40:43], v[132:135], v[172:175], v[40:43]
	v_mfma_f32_16x16x32_bf16 v[28:31], v[124:127], v[180:183], v[28:31]
	v_mfma_f32_16x16x32_bf16 v[24:27], v[132:135], v[180:183], v[24:27]
	v_mfma_f32_16x16x32_bf16 v[12:15], v[124:127], v[188:191], v[12:15]
	v_mfma_f32_16x16x32_bf16 v[8:11], v[132:135], v[188:191], v[8:11]
	s_setprio 0
	s_setprio 1
	v_mfma_f32_16x16x32_bf16 v[52:55], v[140:143], v[160:163], v[52:55]
	v_mfma_f32_16x16x32_bf16 v[48:51], v[152:155], v[160:163], v[48:51]
	v_mfma_f32_16x16x32_bf16 v[36:39], v[140:143], v[168:171], v[36:39]
	v_mfma_f32_16x16x32_bf16 v[32:35], v[152:155], v[168:171], v[32:35]
	v_mfma_f32_16x16x32_bf16 v[20:23], v[140:143], v[176:179], v[20:23]
	v_mfma_f32_16x16x32_bf16 v[16:19], v[152:155], v[176:179], v[16:19]
	v_mfma_f32_16x16x32_bf16 v[4:7], v[140:143], v[184:187], v[4:7]
	v_mfma_f32_16x16x32_bf16 v[0:3], v[152:155], v[184:187], v[0:3]
	v_mfma_f32_16x16x32_bf16 v[52:55], v[148:151], v[164:167], v[52:55]
	v_mfma_f32_16x16x32_bf16 v[48:51], v[156:159], v[164:167], v[48:51]
	v_mfma_f32_16x16x32_bf16 v[36:39], v[148:151], v[172:175], v[36:39]
	v_mfma_f32_16x16x32_bf16 v[32:35], v[156:159], v[172:175], v[32:35]
	v_mfma_f32_16x16x32_bf16 v[20:23], v[148:151], v[180:183], v[20:23]
	v_mfma_f32_16x16x32_bf16 v[16:19], v[156:159], v[180:183], v[16:19]
	v_mfma_f32_16x16x32_bf16 v[4:7], v[148:151], v[188:191], v[4:7]
	v_mfma_f32_16x16x32_bf16 v[0:3], v[156:159], v[188:191], v[0:3]
	s_barrier
	s_setprio 0
	s_add_i32 s64, s64, 2
	s_add_u32 s28, s28, 0x100
	s_addc_u32 s29, s29, 0
	s_add_u32 s62, s62, 0x100
	s_addc_u32 s63, s63, 0
	s_cmp_gt_u32 s64, 13
	s_cbranch_scc0 .LBB0_1109
	s_and_b64 vcc, exec, s[14:15]
	s_cbranch_vccz .LBB0_1112
	s_barrier

.LBB0_1128:
	s_or_b64 exec, exec, s[24:25]
	s_andn2_b64 vcc, exec, s[6:7]
	s_mov_b64 s[6:7], -1
	s_cbranch_vccnz .LBB0_1101
	s_mov_b32 s101, 0
	s_andn2_b64 vcc, exec, s[10:11]
	s_cbranch_vccnz .LBB0_1100
	s_mov_b32 s101, 1
	s_branch .LBB0_1100

.LBB0_1187:
	s_lshl_b32 s12, s12, 5
	s_and_b32 s17, s12, 0x60
	s_mov_b64 s[12:13], 0x80
	s_add_i32 m0, s25, 0x18000
	v_lshl_add_u64 v[6:7], v[6:7], 0, s[12:13]
	s_lshl_b32 s16, s7, 13
	s_lshl_b32 s18, s17, 7
	s_waitcnt vmcnt(2)
	s_barrier
	global_load_lds_dwordx4 v[6:7], off
	v_lshl_add_u64 v[4:5], v[4:5], 0, s[12:13]
	s_add_i32 m0, s25, 0x1a000
	s_add_i32 s41, s25, 0x8000
	s_add_i32 s42, s25, 0xa000
	global_load_lds_dwordx4 v[4:5], off
	v_lshl_add_u64 v[0:1], v[0:1], 0, s[12:13]
	s_mov_b32 m0, s41
	s_add_u32 s14, s30, 0x40080
	global_load_lds_dwordx4 v[0:1], off
	v_lshl_add_u64 v[0:1], v[2:3], 0, s[12:13]
	s_mov_b32 m0, s42
	s_addc_u32 s15, s31, 0
	global_load_lds_dwordx4 v[0:1], off
	s_add_i32 m0, s25, 0x1c000
	v_lshl_add_u64 v[0:1], s[14:15], 0, v[132:133]
	global_load_lds_dwordx4 v[0:1], off
	v_lshl_add_u64 v[0:1], s[14:15], 0, v[128:129]
	s_add_i32 m0, s25, 0x1e000
	s_cmpk_lt_u32 s6, 0x100
	global_load_lds_dwordx4 v[0:1], off
	v_lshrrev_b32_e32 v1, 1, v9
	v_and_b32_e32 v1, 24, v1
	v_and_b32_e32 v0, 15, v9
	v_lshlrev_b32_e32 v2, 1, v1
	v_lshl_or_b32 v146, s7, 6, v0
	v_lshl_or_b32 v0, v0, 6, v2
	v_lshlrev_b32_e32 v2, 2, v9
	v_and_b32_e32 v2, 32, v2
	v_bitop3_b32 v3, v0, s16, v2 bitop3:0xde
	v_bitop3_b32 v147, v0, s18, v2 bitop3:0xde
	v_lshlrev_b32_e32 v0, 14, v13
	v_and_b32_e32 v0, 0xffff8000, v0
	v_or_b32_e32 v148, s17, v1
	v_lshl_add_u32 v0, v12, 11, v0
	v_and_b32_e32 v1, 1, v13
	v_lshl_or_b32 v0, v1, 6, v0
	v_lshl_add_u32 v136, v14, 1, v0
	v_lshlrev_b32_e32 v0, 14, v8
	v_and_b32_e32 v0, 0xffff8000, v0
	s_waitcnt vmcnt(6)
	v_lshl_add_u32 v0, v10, 11, v0
	v_and_b32_e32 v1, 1, v8
	s_cselect_b64 s[14:15], -1, 0
	v_lshl_or_b32 v0, v1, 6, v0
	s_add_i32 s47, 0, 0x10000
	s_add_i32 s48, 0, 0x14000
	s_ashr_i32 s43, s52, 31
	s_mov_b32 s46, s52
	v_mov_b32_e32 v137, v133
	v_lshl_add_u32 v138, v11, 1, v0
	v_mov_b32_e32 v139, v133
	v_mov_b64_e32 v[140:141], 0xb00
	v_mov_b64_e32 v[142:143], 0xaff
	v_add_u32_e32 v149, s47, v147
	v_add_u32_e32 v150, s48, v147
	v_add_u32_e32 v151, 0, v3
	v_mov_b32_e32 v152, 0x358637bd
	s_movk_i32 s49, 0x1600
	s_barrier
	v_lshl_add_u32 v238, s26, 8, v146
	v_ashrrev_i32_e32 v239, 31, v238
	v_lshl_add_u64 v[238:239], v[238:239], 2, s[8:9]
	global_load_dword v230, v[238:239], off sc1
	global_load_dword v231, v[238:239], off offset:64 sc1
	global_load_dword v232, v[238:239], off offset:128 sc1
	global_load_dword v233, v[238:239], off offset:192 sc1
	global_load_dword v234, v[238:239], off offset:512 sc1
	global_load_dword v235, v[238:239], off offset:576 sc1
	global_load_dword v236, v[238:239], off offset:640 sc1
	global_load_dword v237, v[238:239], off offset:704 sc1
	s_mov_b32 s101, 0
	s_branch .LBB0_1190

.LBB0_1192:
	s_ashr_i32 s19, s18, 31
	s_lshl_b64 s[20:21], s[18:19], 19
	s_add_u32 s20, s58, s20
	s_addc_u32 s21, s59, s21
	s_and_b64 s[22:23], s[6:7], exec
	s_cselect_b32 s19, s21, s29
	s_cselect_b32 s50, s20, s28
	s_ashr_i32 s17, s16, 31
	s_lshl_b64 s[22:23], s[16:17], 19
	s_add_u32 s22, s2, s22
	s_addc_u32 s23, s4, s23
	s_and_b64 s[34:35], s[6:7], exec
	s_cselect_b32 s17, s23, s31
	s_cselect_b32 s51, s22, s30
	s_add_u32 s28, s28, 0x40080
	s_addc_u32 s29, s29, 0
	s_add_u32 s60, s30, 0x100
	v_mov_b32_e32 v0, 0
	s_addc_u32 s61, s31, 0
	s_mov_b32 s62, -2
	s_cmp_lg_u32 s101, 0
	s_cbranch_scc0 .Lph1193_a
	v_mov_b32_e32 v1, v0
	v_mov_b32_e32 v2, v0
	v_mov_b32_e32 v3, v0
	v_mov_b32_e32 v8, v0
	v_mov_b32_e32 v9, v0
	v_mov_b32_e32 v10, v0
	v_mov_b32_e32 v11, v0
	v_mov_b32_e32 v16, v0
	v_mov_b32_e32 v17, v0
	v_mov_b32_e32 v18, v0
	v_mov_b32_e32 v19, v0
	v_mov_b32_e32 v24, v0
	v_mov_b32_e32 v25, v0
	v_mov_b32_e32 v26, v0
	v_mov_b32_e32 v27, v0
	v_mov_b32_e32 v32, v0
	v_mov_b32_e32 v33, v0
	v_mov_b32_e32 v34, v0
	v_mov_b32_e32 v35, v0
	v_mov_b32_e32 v40, v0
	v_mov_b32_e32 v41, v0
	v_mov_b32_e32 v42, v0
	v_mov_b32_e32 v43, v0
	v_mov_b32_e32 v48, v0
	v_mov_b32_e32 v49, v0
	v_mov_b32_e32 v50, v0
	v_mov_b32_e32 v51, v0
	v_mov_b32_e32 v56, v0
	v_mov_b32_e32 v57, v0
	v_mov_b32_e32 v58, v0
	v_mov_b32_e32 v59, v0
	v_mov_b32_e32 v4, v0
	v_mov_b32_e32 v5, v0
	v_mov_b32_e32 v6, v0
	v_mov_b32_e32 v7, v0
	v_mov_b32_e32 v12, v0
	v_mov_b32_e32 v13, v0
	v_mov_b32_e32 v14, v0
	v_mov_b32_e32 v15, v0
	v_mov_b32_e32 v20, v0
	v_mov_b32_e32 v21, v0
	v_mov_b32_e32 v22, v0
	v_mov_b32_e32 v23, v0
	v_mov_b32_e32 v28, v0
	v_mov_b32_e32 v29, v0
	v_mov_b32_e32 v30, v0
	v_mov_b32_e32 v31, v0
	v_mov_b32_e32 v36, v0
	v_mov_b32_e32 v37, v0
	v_mov_b32_e32 v38, v0
	v_mov_b32_e32 v39, v0
	v_mov_b32_e32 v44, v0
	v_mov_b32_e32 v45, v0
	v_mov_b32_e32 v46, v0
	v_mov_b32_e32 v47, v0
	v_mov_b32_e32 v52, v0
	v_mov_b32_e32 v53, v0
	v_mov_b32_e32 v54, v0
	v_mov_b32_e32 v55, v0
	v_mov_b32_e32 v60, v0
	v_mov_b32_e32 v61, v0
	v_mov_b32_e32 v62, v0
	v_mov_b32_e32 v63, v0
	v_mov_b32_e32 v64, v0
	v_mov_b32_e32 v65, v0
	v_mov_b32_e32 v66, v0
	v_mov_b32_e32 v67, v0
	v_mov_b32_e32 v72, v0
	v_mov_b32_e32 v73, v0
	v_mov_b32_e32 v74, v0
	v_mov_b32_e32 v75, v0
	v_mov_b32_e32 v80, v0
	v_mov_b32_e32 v81, v0
	v_mov_b32_e32 v82, v0
	v_mov_b32_e32 v83, v0
	v_mov_b32_e32 v88, v0
	v_mov_b32_e32 v89, v0
	v_mov_b32_e32 v90, v0
	v_mov_b32_e32 v91, v0
	v_mov_b32_e32 v96, v0
	v_mov_b32_e32 v97, v0
	v_mov_b32_e32 v98, v0
	v_mov_b32_e32 v99, v0
	v_mov_b32_e32 v104, v0
	v_mov_b32_e32 v105, v0
	v_mov_b32_e32 v106, v0
	v_mov_b32_e32 v107, v0
	v_mov_b32_e32 v120, v0
	v_mov_b32_e32 v121, v0
	v_mov_b32_e32 v122, v0
	v_mov_b32_e32 v123, v0
	v_mov_b32_e32 v124, v0
	v_mov_b32_e32 v125, v0
	v_mov_b32_e32 v126, v0
	v_mov_b32_e32 v127, v0
	v_mov_b32_e32 v68, v0
	v_mov_b32_e32 v69, v0
	v_mov_b32_e32 v70, v0
	v_mov_b32_e32 v71, v0
	v_mov_b32_e32 v76, v0
	v_mov_b32_e32 v77, v0
	v_mov_b32_e32 v78, v0
	v_mov_b32_e32 v79, v0
	v_mov_b32_e32 v84, v0
	v_mov_b32_e32 v85, v0
	v_mov_b32_e32 v86, v0
	v_mov_b32_e32 v87, v0
	v_mov_b32_e32 v92, v0
	v_mov_b32_e32 v93, v0
	v_mov_b32_e32 v94, v0
	v_mov_b32_e32 v95, v0
	v_mov_b32_e32 v100, v0
	v_mov_b32_e32 v101, v0
	v_mov_b32_e32 v102, v0
	v_mov_b32_e32 v103, v0
	v_mov_b32_e32 v108, v0
	v_mov_b32_e32 v109, v0
	v_mov_b32_e32 v110, v0
	v_mov_b32_e32 v111, v0
	v_mov_b32_e32 v112, v0
	v_mov_b32_e32 v113, v0
	v_mov_b32_e32 v114, v0
	v_mov_b32_e32 v115, v0
	v_mov_b32_e32 v116, v0
	v_mov_b32_e32 v117, v0
	v_mov_b32_e32 v118, v0
	v_mov_b32_e32 v119, v0
	s_barrier
	s_mov_b32 s101, 0
	s_branch .LBB0_1193
.Lph1193_a:
	s_add_u32 s30, s28, 0xfffc0080
	s_addc_u32 s31, s29, -1
	s_cmp_eq_u32 s62, 12
	s_cselect_b32 s35, s19, s31
	s_cselect_b32 s34, s50, s30
	s_cselect_b32 s31, s17, s61
	s_cselect_b32 s30, s51, s60
	v_lshl_add_u64 v[144:145], s[28:29], 0, v[136:137]
	s_add_i32 m0, s25, 0xc000
	s_nop 0
	global_load_lds_dwordx4 v[144:145], off
	v_lshl_add_u64 v[144:145], s[28:29], 0, v[138:139]
	s_add_i32 m0, s25, 0xe000
	s_nop 0
	global_load_lds_dwordx4 v[144:145], off
	ds_read_b128 v[154:157], v149
	ds_read_b128 v[158:161], v149 offset:1024
	ds_read_b128 v[162:165], v149 offset:2048
	ds_read_b128 v[166:169], v149 offset:3072
	ds_read_b128 v[170:173], v150
	ds_read_b128 v[174:177], v150 offset:1024
	ds_read_b128 v[178:181], v150 offset:2048
	ds_read_b128 v[182:185], v150 offset:3072
	ds_read_b128 v[186:189], v151
	ds_read_b128 v[190:193], v151 offset:1024
	ds_read_b128 v[194:197], v151 offset:2048
	ds_read_b128 v[198:201], v151 offset:3072
	ds_read_b128 v[202:205], v151 offset:4096
	ds_read_b128 v[206:209], v151 offset:5120
	ds_read_b128 v[210:213], v151 offset:6144
	ds_read_b128 v[214:217], v151 offset:7168
	v_mov_b32_e32 v1, v0
	v_mov_b32_e32 v2, v0
	v_mov_b32_e32 v3, v0
	v_mov_b32_e32 v8, v0
	v_mov_b32_e32 v9, v0
	v_mov_b32_e32 v10, v0
	v_mov_b32_e32 v11, v0
	v_mov_b32_e32 v16, v0
	v_mov_b32_e32 v17, v0
	v_mov_b32_e32 v18, v0
	v_mov_b32_e32 v19, v0
	v_mov_b32_e32 v24, v0
	v_mov_b32_e32 v25, v0
	v_mov_b32_e32 v26, v0
	v_mov_b32_e32 v27, v0
	v_mov_b32_e32 v32, v0
	v_mov_b32_e32 v33, v0
	v_mov_b32_e32 v34, v0
	v_mov_b32_e32 v35, v0
	v_mov_b32_e32 v40, v0
	v_mov_b32_e32 v41, v0
	v_mov_b32_e32 v42, v0
	v_mov_b32_e32 v43, v0
	v_mov_b32_e32 v48, v0
	v_mov_b32_e32 v49, v0
	v_mov_b32_e32 v50, v0
	v_mov_b32_e32 v51, v0
	v_mov_b32_e32 v56, v0
	v_mov_b32_e32 v57, v0
	v_mov_b32_e32 v58, v0
	v_mov_b32_e32 v59, v0
	v_mov_b32_e32 v4, v0
	v_mov_b32_e32 v5, v0
	v_mov_b32_e32 v6, v0
	v_mov_b32_e32 v7, v0
	v_mov_b32_e32 v12, v0
	v_mov_b32_e32 v13, v0
	v_mov_b32_e32 v14, v0
	v_mov_b32_e32 v15, v0
	v_mov_b32_e32 v20, v0
	v_mov_b32_e32 v21, v0
	v_mov_b32_e32 v22, v0
	v_mov_b32_e32 v23, v0
	v_mov_b32_e32 v28, v0
	v_mov_b32_e32 v29, v0
	v_mov_b32_e32 v30, v0
	v_mov_b32_e32 v31, v0
	v_mov_b32_e32 v36, v0
	v_mov_b32_e32 v37, v0
	v_mov_b32_e32 v38, v0
	v_mov_b32_e32 v39, v0
	v_mov_b32_e32 v44, v0
	v_mov_b32_e32 v45, v0
	v_mov_b32_e32 v46, v0
	v_mov_b32_e32 v47, v0
	v_mov_b32_e32 v52, v0
	v_mov_b32_e32 v53, v0
	v_mov_b32_e32 v54, v0
	v_mov_b32_e32 v55, v0
	v_mov_b32_e32 v60, v0
	v_mov_b32_e32 v61, v0
	v_mov_b32_e32 v62, v0
	v_mov_b32_e32 v63, v0
	v_mov_b32_e32 v64, v0
	v_mov_b32_e32 v65, v0
	v_mov_b32_e32 v66, v0
	v_mov_b32_e32 v67, v0
	v_mov_b32_e32 v72, v0
	v_mov_b32_e32 v73, v0
	v_mov_b32_e32 v74, v0
	v_mov_b32_e32 v75, v0
	v_mov_b32_e32 v80, v0
	v_mov_b32_e32 v81, v0
	v_mov_b32_e32 v82, v0
	v_mov_b32_e32 v83, v0
	v_mov_b32_e32 v88, v0
	v_mov_b32_e32 v89, v0
	v_mov_b32_e32 v90, v0
	v_mov_b32_e32 v91, v0
	v_mov_b32_e32 v96, v0
	v_mov_b32_e32 v97, v0
	v_mov_b32_e32 v98, v0
	v_mov_b32_e32 v99, v0
	v_mov_b32_e32 v104, v0
	v_mov_b32_e32 v105, v0
	v_mov_b32_e32 v106, v0
	v_mov_b32_e32 v107, v0
	v_mov_b32_e32 v120, v0
	v_mov_b32_e32 v121, v0
	v_mov_b32_e32 v122, v0
	v_mov_b32_e32 v123, v0
	v_mov_b32_e32 v124, v0
	v_mov_b32_e32 v125, v0
	v_mov_b32_e32 v126, v0
	v_mov_b32_e32 v127, v0
	v_mov_b32_e32 v68, v0
	v_mov_b32_e32 v69, v0
	v_mov_b32_e32 v70, v0
	v_mov_b32_e32 v71, v0
	v_mov_b32_e32 v76, v0
	v_mov_b32_e32 v77, v0
	v_mov_b32_e32 v78, v0
	v_mov_b32_e32 v79, v0
	v_mov_b32_e32 v84, v0
	v_mov_b32_e32 v85, v0
	v_mov_b32_e32 v86, v0
	v_mov_b32_e32 v87, v0
	v_mov_b32_e32 v92, v0
	v_mov_b32_e32 v93, v0
	v_mov_b32_e32 v94, v0
	v_mov_b32_e32 v95, v0
	v_mov_b32_e32 v100, v0
	v_mov_b32_e32 v101, v0
	v_mov_b32_e32 v102, v0
	v_mov_b32_e32 v103, v0
	v_mov_b32_e32 v108, v0
	v_mov_b32_e32 v109, v0
	v_mov_b32_e32 v110, v0
	v_mov_b32_e32 v111, v0
	v_mov_b32_e32 v112, v0
	v_mov_b32_e32 v113, v0
	v_mov_b32_e32 v114, v0
	v_mov_b32_e32 v115, v0
	v_mov_b32_e32 v116, v0
	v_mov_b32_e32 v117, v0
	v_mov_b32_e32 v118, v0
	v_mov_b32_e32 v119, v0
	s_branch .Lph1193_w

.Lph1193_w:
	s_nop 0
	s_waitcnt vmcnt(8)
	s_waitcnt lgkmcnt(0)
	s_setprio 1
	s_barrier
	v_mfma_f32_16x16x32_bf16 v[116:119], v[154:157], v[186:189], v[116:119]
	v_mfma_f32_16x16x32_bf16 v[112:115], v[162:165], v[186:189], v[112:115]
	v_mfma_f32_16x16x32_bf16 v[108:111], v[154:157], v[194:197], v[108:111]
	v_mfma_f32_16x16x32_bf16 v[100:103], v[162:165], v[194:197], v[100:103]
	v_mfma_f32_16x16x32_bf16 v[92:95], v[154:157], v[202:205], v[92:95]
	v_mfma_f32_16x16x32_bf16 v[84:87], v[162:165], v[202:205], v[84:87]
	v_mfma_f32_16x16x32_bf16 v[76:79], v[154:157], v[210:213], v[76:79]
	v_mfma_f32_16x16x32_bf16 v[68:71], v[162:165], v[210:213], v[68:71]
	v_mfma_f32_16x16x32_bf16 v[116:119], v[158:161], v[190:193], v[116:119]
	v_mfma_f32_16x16x32_bf16 v[112:115], v[166:169], v[190:193], v[112:115]
	v_mfma_f32_16x16x32_bf16 v[108:111], v[158:161], v[198:201], v[108:111]
	v_mfma_f32_16x16x32_bf16 v[100:103], v[166:169], v[198:201], v[100:103]
	v_mfma_f32_16x16x32_bf16 v[92:95], v[158:161], v[206:209], v[92:95]
	v_mfma_f32_16x16x32_bf16 v[84:87], v[166:169], v[206:209], v[84:87]
	v_mfma_f32_16x16x32_bf16 v[76:79], v[158:161], v[214:217], v[76:79]
	v_mfma_f32_16x16x32_bf16 v[68:71], v[166:169], v[214:217], v[68:71]
	s_setprio 0
	s_setprio 1
	v_mfma_f32_16x16x32_bf16 v[124:127], v[170:173], v[186:189], v[124:127]
	v_mfma_f32_16x16x32_bf16 v[120:123], v[178:181], v[186:189], v[120:123]
	v_mfma_f32_16x16x32_bf16 v[104:107], v[170:173], v[194:197], v[104:107]
	v_mfma_f32_16x16x32_bf16 v[96:99], v[178:181], v[194:197], v[96:99]
	v_mfma_f32_16x16x32_bf16 v[88:91], v[170:173], v[202:205], v[88:91]
	v_mfma_f32_16x16x32_bf16 v[80:83], v[178:181], v[202:205], v[80:83]
	v_mfma_f32_16x16x32_bf16 v[72:75], v[170:173], v[210:213], v[72:75]
	v_mfma_f32_16x16x32_bf16 v[64:67], v[178:181], v[210:213], v[64:67]
	v_mfma_f32_16x16x32_bf16 v[124:127], v[174:177], v[190:193], v[124:127]
	v_mfma_f32_16x16x32_bf16 v[120:123], v[182:185], v[190:193], v[120:123]
	v_mfma_f32_16x16x32_bf16 v[104:107], v[174:177], v[198:201], v[104:107]
	v_mfma_f32_16x16x32_bf16 v[96:99], v[182:185], v[198:201], v[96:99]
	v_mfma_f32_16x16x32_bf16 v[88:91], v[174:177], v[206:209], v[88:91]
	v_mfma_f32_16x16x32_bf16 v[80:83], v[182:185], v[206:209], v[80:83]
	v_mfma_f32_16x16x32_bf16 v[72:75], v[174:177], v[214:217], v[72:75]
	v_mfma_f32_16x16x32_bf16 v[64:67], v[182:185], v[214:217], v[64:67]
	s_barrier
	s_setprio 0
	s_add_i32 s63, s47, s5
	v_lshl_add_u64 v[144:145], s[30:31], 0, v[132:133]
	s_mov_b32 m0, s63
	s_nop 0
	global_load_lds_dwordx4 v[144:145], off
	s_add_i32 m0, s63, 0x2000
	s_add_u32 s64, s30, 0x40000
	v_lshl_add_u64 v[218:219], s[30:31], 0, v[128:129]
	s_addc_u32 s65, s31, 0
	s_add_i32 s63, s48, s5
	global_load_lds_dwordx4 v[218:219], off
	v_lshl_add_u64 v[220:221], s[64:65], 0, v[132:133]
	s_mov_b32 m0, s63
	v_lshl_add_u64 v[222:223], s[34:35], 0, v[130:131]
	global_load_lds_dwordx4 v[220:221], off
	v_lshl_add_u64 v[220:221], s[64:65], 0, v[128:129]
	s_add_i32 m0, s63, 0x2000
	s_nop 0
	global_load_lds_dwordx4 v[220:221], off
	v_lshl_add_u64 v[220:221], s[34:35], 0, v[134:135]
	s_mov_b32 m0, s25
	s_nop 0
	global_load_lds_dwordx4 v[220:221], off
	s_mov_b32 m0, s27
	s_nop 0
	global_load_lds_dwordx4 v[222:223], off
	ds_read_b128 v[186:189], v151 offset:16384
	ds_read_b128 v[190:193], v151 offset:17408
	ds_read_b128 v[194:197], v151 offset:18432
	ds_read_b128 v[198:201], v151 offset:19456
	ds_read_b128 v[202:205], v151 offset:20480
	ds_read_b128 v[206:209], v151 offset:21504
	ds_read_b128 v[210:213], v151 offset:22528
	ds_read_b128 v[214:217], v151 offset:23552
	s_nop 0
	s_waitcnt vmcnt(8)
	s_waitcnt lgkmcnt(0)
	s_setprio 1
	s_barrier
	v_mfma_f32_16x16x32_bf16 v[60:63], v[154:157], v[186:189], v[60:63]
	v_mfma_f32_16x16x32_bf16 v[52:55], v[162:165], v[186:189], v[52:55]
	v_mfma_f32_16x16x32_bf16 v[44:47], v[154:157], v[194:197], v[44:47]
	v_mfma_f32_16x16x32_bf16 v[36:39], v[162:165], v[194:197], v[36:39]
	v_mfma_f32_16x16x32_bf16 v[28:31], v[154:157], v[202:205], v[28:31]
	v_mfma_f32_16x16x32_bf16 v[20:23], v[162:165], v[202:205], v[20:23]
	v_mfma_f32_16x16x32_bf16 v[12:15], v[154:157], v[210:213], v[12:15]
	v_mfma_f32_16x16x32_bf16 v[4:7], v[162:165], v[210:213], v[4:7]
	v_mfma_f32_16x16x32_bf16 v[60:63], v[158:161], v[190:193], v[60:63]
	v_mfma_f32_16x16x32_bf16 v[52:55], v[166:169], v[190:193], v[52:55]
	v_mfma_f32_16x16x32_bf16 v[44:47], v[158:161], v[198:201], v[44:47]
	v_mfma_f32_16x16x32_bf16 v[36:39], v[166:169], v[198:201], v[36:39]
	v_mfma_f32_16x16x32_bf16 v[28:31], v[158:161], v[206:209], v[28:31]
	v_mfma_f32_16x16x32_bf16 v[20:23], v[166:169], v[206:209], v[20:23]
	v_mfma_f32_16x16x32_bf16 v[12:15], v[158:161], v[214:217], v[12:15]
	v_mfma_f32_16x16x32_bf16 v[4:7], v[166:169], v[214:217], v[4:7]
	s_setprio 0
	s_setprio 1
	v_mfma_f32_16x16x32_bf16 v[56:59], v[170:173], v[186:189], v[56:59]
	v_mfma_f32_16x16x32_bf16 v[48:51], v[178:181], v[186:189], v[48:51]
	v_mfma_f32_16x16x32_bf16 v[40:43], v[170:173], v[194:197], v[40:43]
	v_mfma_f32_16x16x32_bf16 v[32:35], v[178:181], v[194:197], v[32:35]
	v_mfma_f32_16x16x32_bf16 v[24:27], v[170:173], v[202:205], v[24:27]
	v_mfma_f32_16x16x32_bf16 v[16:19], v[178:181], v[202:205], v[16:19]
	v_mfma_f32_16x16x32_bf16 v[8:11], v[170:173], v[210:213], v[8:11]
	v_mfma_f32_16x16x32_bf16 v[0:3], v[178:181], v[210:213], v[0:3]
	v_mfma_f32_16x16x32_bf16 v[56:59], v[174:177], v[190:193], v[56:59]
	v_mfma_f32_16x16x32_bf16 v[48:51], v[182:185], v[190:193], v[48:51]
	v_mfma_f32_16x16x32_bf16 v[40:43], v[174:177], v[198:201], v[40:43]
	v_mfma_f32_16x16x32_bf16 v[32:35], v[182:185], v[198:201], v[32:35]
	v_mfma_f32_16x16x32_bf16 v[24:27], v[174:177], v[206:209], v[24:27]
	v_mfma_f32_16x16x32_bf16 v[16:19], v[182:185], v[206:209], v[16:19]
	v_mfma_f32_16x16x32_bf16 v[8:11], v[174:177], v[214:217], v[8:11]
	v_mfma_f32_16x16x32_bf16 v[0:3], v[182:185], v[214:217], v[0:3]
	s_barrier
	s_setprio 0
	s_add_i32 s63, 0, 0x18000
	s_add_i32 s64, 0, 0x1c000
	s_add_u32 s34, s34, 0x40000
	s_addc_u32 s35, s35, 0
	s_mov_b32 m0, s38
	v_lshl_add_u64 v[224:225], s[34:35], 0, v[134:135]
	global_load_lds_dwordx4 v[224:225], off
	v_lshl_add_u64 v[224:225], s[34:35], 0, v[130:131]
	s_mov_b32 m0, s39
	s_nop 0
	global_load_lds_dwordx4 v[224:225], off
	v_add_u32_e32 v153, s63, v147
	ds_read_b128 v[154:157], v153
	ds_read_b128 v[158:161], v153 offset:1024
	ds_read_b128 v[162:165], v153 offset:2048
	ds_read_b128 v[166:169], v153 offset:3072
	v_add_u32_e32 v153, s64, v147
	ds_read_b128 v[170:173], v153
	ds_read_b128 v[174:177], v153 offset:1024
	ds_read_b128 v[178:181], v153 offset:2048
	ds_read_b128 v[182:185], v153 offset:3072
	ds_read_b128 v[186:189], v151 offset:32768
	ds_read_b128 v[190:193], v151 offset:33792
	ds_read_b128 v[194:197], v151 offset:34816
	ds_read_b128 v[198:201], v151 offset:35840
	ds_read_b128 v[202:205], v151 offset:36864
	ds_read_b128 v[206:209], v151 offset:37888
	ds_read_b128 v[210:213], v151 offset:38912
	ds_read_b128 v[214:217], v151 offset:39936
	s_waitcnt vmcnt(8)
	s_waitcnt lgkmcnt(0)
	s_setprio 1
	s_barrier
	v_mfma_f32_16x16x32_bf16 v[116:119], v[154:157], v[186:189], v[116:119]
	v_mfma_f32_16x16x32_bf16 v[112:115], v[162:165], v[186:189], v[112:115]
	v_mfma_f32_16x16x32_bf16 v[108:111], v[154:157], v[194:197], v[108:111]
	v_mfma_f32_16x16x32_bf16 v[100:103], v[162:165], v[194:197], v[100:103]
	v_mfma_f32_16x16x32_bf16 v[92:95], v[154:157], v[202:205], v[92:95]
	v_mfma_f32_16x16x32_bf16 v[84:87], v[162:165], v[202:205], v[84:87]
	v_mfma_f32_16x16x32_bf16 v[76:79], v[154:157], v[210:213], v[76:79]
	v_mfma_f32_16x16x32_bf16 v[68:71], v[162:165], v[210:213], v[68:71]
	v_mfma_f32_16x16x32_bf16 v[116:119], v[158:161], v[190:193], v[116:119]
	v_mfma_f32_16x16x32_bf16 v[112:115], v[166:169], v[190:193], v[112:115]
	v_mfma_f32_16x16x32_bf16 v[108:111], v[158:161], v[198:201], v[108:111]
	v_mfma_f32_16x16x32_bf16 v[100:103], v[166:169], v[198:201], v[100:103]
	v_mfma_f32_16x16x32_bf16 v[92:95], v[158:161], v[206:209], v[92:95]
	v_mfma_f32_16x16x32_bf16 v[84:87], v[166:169], v[206:209], v[84:87]
	v_mfma_f32_16x16x32_bf16 v[76:79], v[158:161], v[214:217], v[76:79]
	v_mfma_f32_16x16x32_bf16 v[68:71], v[166:169], v[214:217], v[68:71]
	s_setprio 0
	s_setprio 1
	v_mfma_f32_16x16x32_bf16 v[124:127], v[170:173], v[186:189], v[124:127]
	v_mfma_f32_16x16x32_bf16 v[120:123], v[178:181], v[186:189], v[120:123]
	v_mfma_f32_16x16x32_bf16 v[104:107], v[170:173], v[194:197], v[104:107]
	v_mfma_f32_16x16x32_bf16 v[96:99], v[178:181], v[194:197], v[96:99]
	v_mfma_f32_16x16x32_bf16 v[88:91], v[170:173], v[202:205], v[88:91]
	v_mfma_f32_16x16x32_bf16 v[80:83], v[178:181], v[202:205], v[80:83]
	v_mfma_f32_16x16x32_bf16 v[72:75], v[170:173], v[210:213], v[72:75]
	v_mfma_f32_16x16x32_bf16 v[64:67], v[178:181], v[210:213], v[64:67]
	v_mfma_f32_16x16x32_bf16 v[124:127], v[174:177], v[190:193], v[124:127]
	v_mfma_f32_16x16x32_bf16 v[120:123], v[182:185], v[190:193], v[120:123]
	v_mfma_f32_16x16x32_bf16 v[104:107], v[174:177], v[198:201], v[104:107]
	v_mfma_f32_16x16x32_bf16 v[96:99], v[182:185], v[198:201], v[96:99]
	v_mfma_f32_16x16x32_bf16 v[88:91], v[174:177], v[206:209], v[88:91]
	v_mfma_f32_16x16x32_bf16 v[80:83], v[182:185], v[206:209], v[80:83]
	v_mfma_f32_16x16x32_bf16 v[72:75], v[174:177], v[214:217], v[72:75]
	v_mfma_f32_16x16x32_bf16 v[64:67], v[182:185], v[214:217], v[64:67]
	s_barrier
	s_setprio 0
	s_add_i32 s34, s63, s5
	v_lshl_add_u64 v[144:145], v[144:145], 0, s[12:13]
	s_mov_b32 m0, s34
	s_nop 0
	global_load_lds_dwordx4 v[144:145], off
	s_add_i32 m0, s34, 0x2000
	s_add_u32 s30, s30, 0x40080
	v_lshl_add_u64 v[144:145], v[218:219], 0, s[12:13]
	s_addc_u32 s31, s31, 0
	s_add_i32 s34, s64, s5
	global_load_lds_dwordx4 v[144:145], off
	v_lshl_add_u64 v[144:145], s[30:31], 0, v[132:133]
	s_mov_b32 m0, s34
	s_nop 0
	global_load_lds_dwordx4 v[144:145], off
	v_lshl_add_u64 v[144:145], s[30:31], 0, v[128:129]
	s_add_i32 m0, s34, 0x2000
	s_nop 0
	global_load_lds_dwordx4 v[144:145], off
	v_lshl_add_u64 v[144:145], v[220:221], 0, s[12:13]
	s_mov_b32 m0, s41
	s_nop 0
	global_load_lds_dwordx4 v[144:145], off
	v_lshl_add_u64 v[144:145], v[222:223], 0, s[12:13]
	s_mov_b32 m0, s42
	s_nop 0
	global_load_lds_dwordx4 v[144:145], off
	ds_read_b128 v[186:189], v151 offset:49152
	ds_read_b128 v[190:193], v151 offset:50176
	ds_read_b128 v[194:197], v151 offset:51200
	ds_read_b128 v[198:201], v151 offset:52224
	ds_read_b128 v[202:205], v151 offset:53248
	ds_read_b128 v[206:209], v151 offset:54272
	ds_read_b128 v[210:213], v151 offset:55296
	ds_read_b128 v[214:217], v151 offset:56320
	s_waitcnt vmcnt(8)
	s_waitcnt lgkmcnt(0)
	s_setprio 1
	s_barrier
	v_mfma_f32_16x16x32_bf16 v[60:63], v[154:157], v[186:189], v[60:63]
	v_mfma_f32_16x16x32_bf16 v[52:55], v[162:165], v[186:189], v[52:55]
	v_mfma_f32_16x16x32_bf16 v[44:47], v[154:157], v[194:197], v[44:47]
	v_mfma_f32_16x16x32_bf16 v[36:39], v[162:165], v[194:197], v[36:39]
	v_mfma_f32_16x16x32_bf16 v[28:31], v[154:157], v[202:205], v[28:31]
	v_mfma_f32_16x16x32_bf16 v[20:23], v[162:165], v[202:205], v[20:23]
	v_mfma_f32_16x16x32_bf16 v[12:15], v[154:157], v[210:213], v[12:15]
	v_mfma_f32_16x16x32_bf16 v[4:7], v[162:165], v[210:213], v[4:7]
	v_mfma_f32_16x16x32_bf16 v[60:63], v[158:161], v[190:193], v[60:63]
	v_mfma_f32_16x16x32_bf16 v[52:55], v[166:169], v[190:193], v[52:55]
	v_mfma_f32_16x16x32_bf16 v[44:47], v[158:161], v[198:201], v[44:47]
	v_mfma_f32_16x16x32_bf16 v[36:39], v[166:169], v[198:201], v[36:39]
	v_mfma_f32_16x16x32_bf16 v[28:31], v[158:161], v[206:209], v[28:31]
	v_mfma_f32_16x16x32_bf16 v[20:23], v[166:169], v[206:209], v[20:23]
	v_mfma_f32_16x16x32_bf16 v[12:15], v[158:161], v[214:217], v[12:15]
	v_mfma_f32_16x16x32_bf16 v[4:7], v[166:169], v[214:217], v[4:7]
	s_setprio 0
	s_setprio 1
	v_mfma_f32_16x16x32_bf16 v[56:59], v[170:173], v[186:189], v[56:59]
	v_mfma_f32_16x16x32_bf16 v[48:51], v[178:181], v[186:189], v[48:51]
	v_mfma_f32_16x16x32_bf16 v[40:43], v[170:173], v[194:197], v[40:43]
	v_mfma_f32_16x16x32_bf16 v[32:35], v[178:181], v[194:197], v[32:35]
	v_mfma_f32_16x16x32_bf16 v[24:27], v[170:173], v[202:205], v[24:27]
	v_mfma_f32_16x16x32_bf16 v[16:19], v[178:181], v[202:205], v[16:19]
	v_mfma_f32_16x16x32_bf16 v[8:11], v[170:173], v[210:213], v[8:11]
	v_mfma_f32_16x16x32_bf16 v[0:3], v[178:181], v[210:213], v[0:3]
	v_mfma_f32_16x16x32_bf16 v[56:59], v[174:177], v[190:193], v[56:59]
	v_mfma_f32_16x16x32_bf16 v[48:51], v[182:185], v[190:193], v[48:51]
	v_mfma_f32_16x16x32_bf16 v[40:43], v[174:177], v[198:201], v[40:43]
	v_mfma_f32_16x16x32_bf16 v[32:35], v[182:185], v[198:201], v[32:35]
	v_mfma_f32_16x16x32_bf16 v[24:27], v[174:177], v[206:209], v[24:27]
	v_mfma_f32_16x16x32_bf16 v[16:19], v[182:185], v[206:209], v[16:19]
	v_mfma_f32_16x16x32_bf16 v[8:11], v[174:177], v[214:217], v[8:11]
	v_mfma_f32_16x16x32_bf16 v[0:3], v[182:185], v[214:217], v[0:3]
	s_barrier
	s_setprio 0
	s_add_i32 s62, s62, 2
	s_add_u32 s28, s28, 0x100
	s_addc_u32 s29, s29, 0
	s_add_u32 s60, s60, 0x100
	s_addc_u32 s61, s61, 0
	s_cmp_gt_u32 s62, 13
	s_cbranch_scc0 .LBB0_1193
	s_and_b64 vcc, exec, s[14:15]
	s_cbranch_vccz .LBB0_1196
	s_barrier
.LBB0_1196:
	v_lshl_add_u32 v144, s26, 8, v146
	v_mov_b32_e32 v145, v230
	v_mov_b32_e32 v153, v231
	v_lshl_or_b32 v156, s24, 7, v148
	v_ashrrev_i32_e32 v157, 31, v156
	v_mul_f32_e32 v162, v108, v104
	v_mul_f32_e32 v163, v109, v105
	v_lshlrev_b64 v[104:105], 1, v[156:157]
	v_mov_b32_e32 v156, v232
	v_mov_b32_e32 v157, v233
	v_mov_b32_e32 v165, v234
	v_mov_b32_e32 v166, v235
	v_mov_b32_e32 v167, v236
	v_mul_f32_e32 v164, v110, v106
	v_mov_b32_e32 v106, v237
	s_and_b64 s[98:99], s[6:7], exec
	s_cselect_b32 s98, s18, s26
	v_lshl_add_u32 v238, s98, 8, v146
	v_ashrrev_i32_e32 v239, 31, v238
	v_lshl_add_u64 v[238:239], v[238:239], 2, s[8:9]
	global_load_dword v230, v[238:239], off sc1
	global_load_dword v231, v[238:239], off offset:64 sc1
	global_load_dword v232, v[238:239], off offset:128 sc1
	global_load_dword v233, v[238:239], off offset:192 sc1
	global_load_dword v234, v[238:239], off offset:512 sc1
	global_load_dword v235, v[238:239], off offset:576 sc1
	global_load_dword v236, v[238:239], off offset:640 sc1
	global_load_dword v237, v[238:239], off offset:704 sc1
	v_mul_f32_e32 v124, v116, v124
	v_mul_f32_e32 v125, v117, v125
	v_mul_f32_e32 v126, v118, v126
	v_mul_f32_e32 v127, v119, v127
	v_mul_f32_e32 v158, v112, v120
	v_mul_f32_e32 v159, v113, v121
	v_mul_f32_e32 v160, v114, v122
	v_mul_f32_e32 v161, v115, v123
	v_mul_f32_e32 v107, v111, v107
	v_mov_b64_e32 v[120:121], s[56:57]
	v_mad_i64_i32 v[122:123], s[28:29], v144, s49, v[120:121]
	v_lshl_add_u64 v[122:123], v[122:123], 0, v[104:105]
	v_mul_f32_e32 v96, v100, v96
	v_mul_f32_e32 v98, v102, v98
	v_mul_f32_e32 v88, v92, v88
	v_mul_f32_e32 v89, v93, v89
	v_mul_f32_e32 v90, v94, v90
	v_mul_f32_e32 v91, v95, v91
	v_mul_f32_e32 v80, v84, v80
	v_mul_f32_e32 v82, v86, v82
	v_mul_f32_e32 v72, v76, v72
	v_mul_f32_e32 v73, v77, v73
	v_mul_f32_e32 v74, v78, v74
	v_mul_f32_e32 v75, v79, v75
	v_mul_f32_e32 v64, v68, v64
	v_mul_f32_e32 v66, v70, v66
	v_mul_f32_e32 v56, v60, v56
	v_mul_f32_e32 v57, v61, v57
	v_mul_f32_e32 v58, v62, v58
	v_mul_f32_e32 v59, v63, v59
	v_mul_f32_e32 v48, v52, v48
	v_mul_f32_e32 v50, v54, v50
	v_mul_f32_e32 v40, v44, v40
	v_mul_f32_e32 v41, v45, v41
	v_mul_f32_e32 v42, v46, v42
	v_mul_f32_e32 v43, v47, v43
	v_mul_f32_e32 v32, v36, v32
	v_mul_f32_e32 v34, v38, v34
	v_mul_f32_e32 v24, v28, v24
	v_mul_f32_e32 v25, v29, v25
	v_mul_f32_e32 v26, v30, v26
	v_mul_f32_e32 v27, v31, v27
	v_mul_f32_e32 v16, v20, v16
	v_mul_f32_e32 v18, v22, v18
	v_mul_f32_e32 v8, v12, v8
	v_mul_f32_e32 v9, v13, v9
	v_mul_f32_e32 v10, v14, v10
	v_mul_f32_e32 v11, v15, v11
	v_mul_f32_e32 v0, v4, v0
	v_mul_f32_e32 v2, v6, v2
	s_andn2_b64 vcc, exec, s[6:7]
	s_mov_b64 s[6:7], -1
	v_fmamk_f32 v145, v145, 0x3a800000, v152
	v_fmamk_f32 v153, v153, 0x3a800000, v152
	v_rsq_f32_e32 v168, v145
	v_rsq_f32_e32 v169, v153
	v_mul_f32_e32 v154, 0xbfb8aa3b, v168
	v_mul_f32_e32 v155, 0xbfb8aa3b, v169
	v_mul_f32_e32 v116, v116, v154
	v_mul_f32_e32 v117, v117, v154
	v_mul_f32_e32 v118, v118, v154
	v_mul_f32_e32 v119, v119, v154
	v_mul_f32_e32 v112, v112, v154
	v_mul_f32_e32 v113, v113, v154
	v_mul_f32_e32 v114, v114, v154
	v_mul_f32_e32 v115, v115, v154
	v_mul_f32_e32 v108, v108, v155
	v_mul_f32_e32 v109, v109, v155
	v_mul_f32_e32 v110, v110, v155
	v_exp_f32_e32 v116, v116
	v_exp_f32_e32 v117, v117
	v_exp_f32_e32 v118, v118
	v_exp_f32_e32 v119, v119
	v_exp_f32_e32 v112, v112
	v_exp_f32_e32 v113, v113
	v_exp_f32_e32 v114, v114
	v_exp_f32_e32 v115, v115
	v_exp_f32_e32 v108, v108
	v_exp_f32_e32 v109, v109
	v_exp_f32_e32 v110, v110
	v_mul_f32_e32 v111, v111, v155
	v_exp_f32_e32 v111, v111
	v_fma_f32 v116, v145, v116, v145
	v_fma_f32 v117, v145, v117, v145
	v_fma_f32 v118, v145, v118, v145
	v_fma_f32 v119, v145, v119, v145
	v_fma_f32 v112, v145, v112, v145
	v_fma_f32 v113, v145, v113, v145
	v_fma_f32 v114, v145, v114, v145
	v_fmac_f32_e32 v145, v145, v115
	v_fma_f32 v108, v153, v108, v153
	v_fma_f32 v109, v153, v109, v153
	v_mul_f32_e32 v154, v100, v155
	v_fma_f32 v110, v153, v110, v153
	v_rcp_f32_e32 v115, v116
	v_rcp_f32_e32 v116, v117
	v_rcp_f32_e32 v117, v118
	v_rcp_f32_e32 v118, v119
	v_rcp_f32_e32 v119, v145
	v_rcp_f32_e32 v108, v108
	v_rcp_f32_e32 v109, v109
	v_exp_f32_e32 v154, v154
	v_rcp_f32_e32 v112, v112
	v_rcp_f32_e32 v113, v113
	v_rcp_f32_e32 v114, v114
	v_rcp_f32_e32 v110, v110
	v_fma_f32 v111, v153, v111, v153
	v_rcp_f32_e32 v145, v111
	v_mul_f32_e32 v111, v124, v115
	v_mul_f32_e32 v115, v125, v116
	v_mul_f32_e32 v116, v126, v117
	v_mul_f32_e32 v117, v127, v118
	v_mul_f32_e32 v118, v161, v119
	v_mul_f32_e32 v119, v162, v108
	v_mul_f32_e32 v124, v163, v109
	v_cvt_pk_bf16_f32 v108, v111, v115
	v_cvt_pk_bf16_f32 v109, v116, v117
	v_mul_f32_e32 v112, v158, v112
	v_mul_f32_e32 v113, v159, v113
	v_mul_f32_e32 v114, v160, v114
	v_mul_f32_e32 v125, v164, v110
	v_cvt_pk_bf16_f32 v110, v112, v113
	v_cvt_pk_bf16_f32 v111, v114, v118
	global_store_dwordx4 v[122:123], v[108:111], off
	v_mul_f32_e32 v107, v107, v145
	s_nop 0
	v_fma_f32 v108, v153, v154, v153
	v_mul_f32_e32 v109, v101, v155
	v_rcp_f32_e32 v108, v108
	v_exp_f32_e32 v109, v109
	v_mul_f32_e32 v100, v96, v108
	v_mul_f32_e32 v96, v101, v97
	v_fma_f32 v97, v153, v109, v153
	v_mul_f32_e32 v101, v102, v155
	v_rcp_f32_e32 v97, v97
	v_exp_f32_e32 v101, v101
	v_mul_f32_e32 v108, v103, v155
	v_exp_f32_e32 v108, v108
	v_mul_f32_e32 v109, v96, v97
	v_fma_f32 v96, v153, v101, v153
	v_rcp_f32_e32 v96, v96
	v_fmac_f32_e32 v153, v153, v108
	v_rcp_f32_e32 v97, v153
	v_or_b32_e32 v102, 16, v144
	v_mul_f32_e32 v101, v98, v96
	v_mul_f32_e32 v96, v103, v99
	v_fmamk_f32 v103, v156, 0x3a800000, v152
	v_mul_f32_e32 v99, v96, v97
	v_cvt_pk_bf16_f32 v96, v119, v124
	v_cvt_pk_bf16_f32 v97, v125, v107
	v_rsq_f32_e32 v107, v103
	v_cvt_pk_bf16_f32 v98, v100, v109
	v_cvt_pk_bf16_f32 v99, v101, v99
	v_mad_i64_i32 v[100:101], s[28:29], v102, s49, v[120:121]
	v_mul_f32_e32 v102, 0xbfb8aa3b, v107
	v_mul_f32_e32 v107, v92, v102
	v_mul_f32_e32 v108, v93, v102
	v_mul_f32_e32 v92, v94, v102
	v_mul_f32_e32 v93, v95, v102
	v_exp_f32_e32 v92, v92
	v_exp_f32_e32 v93, v93
	v_mul_f32_e32 v94, v84, v102
	v_exp_f32_e32 v94, v94
	v_fma_f32 v92, v103, v92, v103
	v_fma_f32 v93, v103, v93, v103
	v_rcp_f32_e32 v92, v92
	v_rcp_f32_e32 v93, v93
	v_exp_f32_e32 v107, v107
	v_exp_f32_e32 v108, v108
	v_mul_f32_e32 v90, v90, v92
	v_mul_f32_e32 v91, v91, v93
	v_fma_f32 v92, v103, v94, v103
	v_mul_f32_e32 v93, v85, v102
	v_rcp_f32_e32 v92, v92
	v_exp_f32_e32 v93, v93
	v_lshl_add_u64 v[100:101], v[100:101], 0, v[104:105]
	global_store_dwordx4 v[100:101], v[96:99], off
	v_mul_f32_e32 v84, v80, v92
	v_mul_f32_e32 v80, v85, v81
	v_fma_f32 v81, v103, v93, v103
	v_mul_f32_e32 v85, v86, v102
	v_rcp_f32_e32 v81, v81
	v_exp_f32_e32 v85, v85
	v_mul_f32_e32 v92, v87, v102
	v_exp_f32_e32 v92, v92
	v_fma_f32 v96, v103, v107, v103
	v_mul_f32_e32 v93, v80, v81
	v_fma_f32 v80, v103, v85, v103
	v_rcp_f32_e32 v96, v96
	v_fma_f32 v97, v103, v108, v103
	v_rcp_f32_e32 v80, v80
	v_fmac_f32_e32 v103, v103, v92
	v_rcp_f32_e32 v97, v97
	v_rcp_f32_e32 v81, v103
	v_mul_f32_e32 v88, v88, v96
	v_mul_f32_e32 v85, v82, v80
	v_mul_f32_e32 v80, v87, v83
	v_fmamk_f32 v87, v157, 0x3a800000, v152
	v_mul_f32_e32 v89, v89, v97
	v_mul_f32_e32 v83, v80, v81
	v_cvt_pk_bf16_f32 v80, v88, v89
	v_rsq_f32_e32 v88, v87
	v_or_b32_e32 v86, 32, v144
	v_cvt_pk_bf16_f32 v81, v90, v91
	v_cvt_pk_bf16_f32 v82, v84, v93
	v_cvt_pk_bf16_f32 v83, v85, v83
	v_mad_i64_i32 v[84:85], s[28:29], v86, s49, v[120:121]
	v_mul_f32_e32 v86, 0xbfb8aa3b, v88
	v_mul_f32_e32 v88, v76, v86
	v_mul_f32_e32 v89, v77, v86
	v_mul_f32_e32 v76, v78, v86
	v_mul_f32_e32 v77, v79, v86
	v_exp_f32_e32 v76, v76
	v_exp_f32_e32 v77, v77
	v_mul_f32_e32 v78, v68, v86
	v_exp_f32_e32 v78, v78
	v_fma_f32 v76, v87, v76, v87
	v_fma_f32 v77, v87, v77, v87
	v_rcp_f32_e32 v76, v76
	v_rcp_f32_e32 v77, v77
	v_exp_f32_e32 v88, v88
	v_exp_f32_e32 v89, v89
	v_mul_f32_e32 v74, v74, v76
	v_mul_f32_e32 v75, v75, v77
	v_fma_f32 v76, v87, v78, v87
	v_mul_f32_e32 v77, v69, v86
	v_rcp_f32_e32 v76, v76
	v_exp_f32_e32 v77, v77
	v_lshl_add_u64 v[84:85], v[84:85], 0, v[104:105]
	global_store_dwordx4 v[84:85], v[80:83], off
	v_mul_f32_e32 v68, v64, v76
	v_mul_f32_e32 v64, v69, v65
	v_fma_f32 v65, v87, v77, v87
	v_mul_f32_e32 v69, v70, v86
	v_rcp_f32_e32 v65, v65
	v_exp_f32_e32 v69, v69
	v_mul_f32_e32 v76, v71, v86
	v_exp_f32_e32 v76, v76
	v_fma_f32 v80, v87, v88, v87
	v_mul_f32_e32 v77, v64, v65
	v_fma_f32 v64, v87, v69, v87
	v_rcp_f32_e32 v80, v80
	v_fma_f32 v81, v87, v89, v87
	v_rcp_f32_e32 v64, v64
	v_fmac_f32_e32 v87, v87, v76
	v_rcp_f32_e32 v81, v81
	v_rcp_f32_e32 v65, v87
	v_mul_f32_e32 v72, v72, v80
	v_mul_f32_e32 v69, v66, v64
	v_mul_f32_e32 v64, v71, v67
	v_fmamk_f32 v71, v165, 0x3a800000, v152
	v_mul_f32_e32 v73, v73, v81
	v_mul_f32_e32 v67, v64, v65
	v_cvt_pk_bf16_f32 v64, v72, v73
	v_rsq_f32_e32 v72, v71
	v_or_b32_e32 v70, 48, v144
	v_cvt_pk_bf16_f32 v65, v74, v75
	v_cvt_pk_bf16_f32 v66, v68, v77
	v_cvt_pk_bf16_f32 v67, v69, v67
	v_mad_i64_i32 v[68:69], s[28:29], v70, s49, v[120:121]
	v_lshl_add_u64 v[68:69], v[68:69], 0, v[104:105]
	global_store_dwordx4 v[68:69], v[64:67], off
	s_nop 1
	v_mul_f32_e32 v64, 0xbfb8aa3b, v72
	v_mul_f32_e32 v65, v60, v64
	v_mul_f32_e32 v66, v61, v64
	v_mul_f32_e32 v60, v62, v64
	v_mul_f32_e32 v61, v63, v64
	v_exp_f32_e32 v60, v60
	v_exp_f32_e32 v61, v61
	v_mul_f32_e32 v62, v52, v64
	v_exp_f32_e32 v62, v62
	v_fma_f32 v60, v71, v60, v71
	v_fma_f32 v61, v71, v61, v71
	v_rcp_f32_e32 v60, v60
	v_rcp_f32_e32 v61, v61
	v_exp_f32_e32 v65, v65
	v_exp_f32_e32 v66, v66
	v_mul_f32_e32 v58, v58, v60
	v_mul_f32_e32 v59, v59, v61
	v_fma_f32 v60, v71, v62, v71
	v_mul_f32_e32 v61, v53, v64
	v_rcp_f32_e32 v60, v60
	v_exp_f32_e32 v61, v61
	v_fma_f32 v65, v71, v65, v71
	v_fma_f32 v66, v71, v66, v71
	v_mul_f32_e32 v52, v48, v60
	v_mul_f32_e32 v48, v53, v49
	v_fma_f32 v49, v71, v61, v71
	v_mul_f32_e32 v53, v54, v64
	v_rcp_f32_e32 v49, v49
	v_exp_f32_e32 v53, v53
	v_mul_f32_e32 v60, v55, v64
	v_exp_f32_e32 v60, v60
	v_mul_f32_e32 v61, v48, v49
	v_fma_f32 v48, v71, v53, v71
	v_rcp_f32_e32 v48, v48
	v_fmamk_f32 v54, v166, 0x3a800000, v152
	v_rcp_f32_e32 v65, v65
	v_rcp_f32_e32 v66, v66
	v_fmac_f32_e32 v71, v71, v60
	v_mul_f32_e32 v53, v50, v48
	v_mul_f32_e32 v48, v55, v51
	v_rsq_f32_e32 v55, v54
	v_rcp_f32_e32 v49, v71
	v_mul_f32_e32 v56, v56, v65
	v_mul_f32_e32 v57, v57, v66
	v_mul_f32_e32 v55, 0xbfb8aa3b, v55
	v_mul_f32_e32 v51, v48, v49
	v_cvt_pk_bf16_f32 v48, v56, v57
	v_mul_f32_e32 v56, v44, v55
	v_mul_f32_e32 v57, v45, v55
	v_mul_f32_e32 v44, v46, v55
	v_mul_f32_e32 v45, v47, v55
	v_exp_f32_e32 v44, v44
	v_exp_f32_e32 v45, v45
	v_mul_f32_e32 v46, v36, v55
	v_exp_f32_e32 v46, v46
	v_fma_f32 v44, v54, v44, v54
	v_fma_f32 v45, v54, v45, v54
	v_rcp_f32_e32 v44, v44
	v_rcp_f32_e32 v45, v45
	v_exp_f32_e32 v56, v56
	v_add_u32_e32 v67, 0x80, v144
	v_mul_f32_e32 v42, v42, v44
	v_mul_f32_e32 v43, v43, v45
	v_fma_f32 v44, v54, v46, v54
	v_mul_f32_e32 v45, v37, v55
	v_rcp_f32_e32 v44, v44
	v_exp_f32_e32 v45, v45
	v_exp_f32_e32 v57, v57
	v_cvt_pk_bf16_f32 v49, v58, v59
	v_mul_f32_e32 v36, v32, v44
	v_mul_f32_e32 v32, v37, v33
	v_fma_f32 v33, v54, v45, v54
	v_mul_f32_e32 v37, v38, v55
	v_rcp_f32_e32 v33, v33
	v_exp_f32_e32 v37, v37
	v_mul_f32_e32 v44, v39, v55
	v_exp_f32_e32 v44, v44
	v_cvt_pk_bf16_f32 v50, v52, v61
	v_cvt_pk_bf16_f32 v51, v53, v51
	v_mad_i64_i32 v[52:53], s[28:29], v67, s49, v[120:121]
	v_lshl_add_u64 v[52:53], v[52:53], 0, v[104:105]
	global_store_dwordx4 v[52:53], v[48:51], off
	v_mul_f32_e32 v45, v32, v33
	v_fma_f32 v32, v54, v37, v54
	v_fma_f32 v48, v54, v56, v54
	v_rcp_f32_e32 v48, v48
	v_fma_f32 v49, v54, v57, v54
	v_rcp_f32_e32 v32, v32
	v_fmac_f32_e32 v54, v54, v44
	v_rcp_f32_e32 v49, v49
	v_rcp_f32_e32 v33, v54
	v_mul_f32_e32 v40, v40, v48
	v_mul_f32_e32 v37, v34, v32
	v_mul_f32_e32 v32, v39, v35
	v_fmamk_f32 v39, v167, 0x3a800000, v152
	v_mul_f32_e32 v41, v41, v49
	v_mul_f32_e32 v35, v32, v33
	v_cvt_pk_bf16_f32 v32, v40, v41
	v_rsq_f32_e32 v40, v39
	v_add_u32_e32 v38, 0x90, v144
	v_cvt_pk_bf16_f32 v33, v42, v43
	v_cvt_pk_bf16_f32 v34, v36, v45
	v_cvt_pk_bf16_f32 v35, v37, v35
	v_mad_i64_i32 v[36:37], s[28:29], v38, s49, v[120:121]
	v_mul_f32_e32 v38, 0xbfb8aa3b, v40
	v_mul_f32_e32 v40, v28, v38
	v_mul_f32_e32 v41, v29, v38
	v_mul_f32_e32 v28, v30, v38
	v_mul_f32_e32 v29, v31, v38
	v_exp_f32_e32 v28, v28
	v_exp_f32_e32 v29, v29
	v_mul_f32_e32 v30, v20, v38
	v_exp_f32_e32 v30, v30
	v_fma_f32 v28, v39, v28, v39
	v_fma_f32 v29, v39, v29, v39
	v_rcp_f32_e32 v28, v28
	v_rcp_f32_e32 v29, v29
	v_exp_f32_e32 v40, v40
	v_exp_f32_e32 v41, v41
	v_mul_f32_e32 v26, v26, v28
	v_mul_f32_e32 v27, v27, v29
	v_fma_f32 v28, v39, v30, v39
	v_mul_f32_e32 v29, v21, v38
	v_rcp_f32_e32 v28, v28
	v_exp_f32_e32 v29, v29
	v_lshl_add_u64 v[36:37], v[36:37], 0, v[104:105]
	global_store_dwordx4 v[36:37], v[32:35], off
	v_mul_f32_e32 v20, v16, v28
	v_mul_f32_e32 v16, v21, v17
	v_fma_f32 v17, v39, v29, v39
	v_mul_f32_e32 v21, v22, v38
	v_rcp_f32_e32 v17, v17
	v_exp_f32_e32 v21, v21
	v_mul_f32_e32 v28, v23, v38
	v_exp_f32_e32 v28, v28
	v_fma_f32 v32, v39, v40, v39
	v_mul_f32_e32 v29, v16, v17
	v_fma_f32 v16, v39, v21, v39
	v_rcp_f32_e32 v32, v32
	v_fma_f32 v33, v39, v41, v39
	v_rcp_f32_e32 v16, v16
	v_fmac_f32_e32 v39, v39, v28
	v_rcp_f32_e32 v33, v33
	v_rcp_f32_e32 v17, v39
	v_mul_f32_e32 v24, v24, v32
	v_mul_f32_e32 v21, v18, v16
	v_mul_f32_e32 v16, v23, v19
	v_fmamk_f32 v23, v106, 0x3a800000, v152
	v_mul_f32_e32 v25, v25, v33
	v_mul_f32_e32 v19, v16, v17
	v_cvt_pk_bf16_f32 v16, v24, v25
	v_rsq_f32_e32 v24, v23
	v_add_u32_e32 v22, 0xa0, v144
	v_cvt_pk_bf16_f32 v17, v26, v27
	v_cvt_pk_bf16_f32 v18, v20, v29
	v_cvt_pk_bf16_f32 v19, v21, v19
	v_mad_i64_i32 v[20:21], s[28:29], v22, s49, v[120:121]
	v_mul_f32_e32 v22, 0xbfb8aa3b, v24
	v_mul_f32_e32 v24, v12, v22
	v_mul_f32_e32 v25, v13, v22
	v_mul_f32_e32 v12, v14, v22
	v_mul_f32_e32 v13, v15, v22
	v_exp_f32_e32 v12, v12
	v_exp_f32_e32 v13, v13
	v_mul_f32_e32 v14, v4, v22
	v_exp_f32_e32 v14, v14
	v_fma_f32 v12, v23, v12, v23
	v_fma_f32 v13, v23, v13, v23
	v_rcp_f32_e32 v12, v12
	v_rcp_f32_e32 v13, v13
	v_exp_f32_e32 v24, v24
	v_exp_f32_e32 v25, v25
	v_mul_f32_e32 v10, v10, v12
	v_mul_f32_e32 v11, v11, v13
	v_fma_f32 v12, v23, v14, v23
	v_mul_f32_e32 v13, v5, v22
	v_rcp_f32_e32 v12, v12
	v_exp_f32_e32 v13, v13
	v_lshl_add_u64 v[20:21], v[20:21], 0, v[104:105]
	global_store_dwordx4 v[20:21], v[16:19], off
	v_mul_f32_e32 v4, v0, v12
	v_mul_f32_e32 v0, v5, v1
	v_fma_f32 v1, v23, v13, v23
	v_mul_f32_e32 v5, v6, v22
	v_rcp_f32_e32 v1, v1
	v_exp_f32_e32 v5, v5
	v_mul_f32_e32 v12, v7, v22
	v_exp_f32_e32 v12, v12
	v_mul_f32_e32 v13, v0, v1
	v_fma_f32 v0, v23, v5, v23
	v_fma_f32 v16, v23, v24, v23
	v_fma_f32 v17, v23, v25, v23
	v_rcp_f32_e32 v0, v0
	v_fmac_f32_e32 v23, v23, v12
	v_rcp_f32_e32 v1, v23
	v_rcp_f32_e32 v16, v16
	v_rcp_f32_e32 v17, v17
	v_mul_f32_e32 v5, v2, v0
	v_mul_f32_e32 v0, v7, v3
	v_mul_f32_e32 v3, v0, v1
	v_add_u32_e32 v6, 0xb0, v144
	v_mul_f32_e32 v8, v8, v16
	v_mul_f32_e32 v9, v9, v17
	v_cvt_pk_bf16_f32 v0, v8, v9
	v_cvt_pk_bf16_f32 v1, v10, v11
	v_cvt_pk_bf16_f32 v2, v4, v13
	v_cvt_pk_bf16_f32 v3, v5, v3
	v_mad_i64_i32 v[4:5], s[28:29], v6, s49, v[120:121]
	v_lshl_add_u64 v[4:5], v[4:5], 0, v[104:105]
	global_store_dwordx4 v[4:5], v[0:3], off
	s_cbranch_vccnz .LBB0_1189
	s_mov_b32 s101, 0
	s_andn2_b64 vcc, exec, s[10:11]
	s_cbranch_vccnz .LBB0_1188
	s_mov_b32 s101, 1
	s_branch .LBB0_1188

.LBB0_1259:
	s_lshl_b32 s0, s10, 5
	s_mov_b64 s[10:11], 0x80
	s_and_b32 s34, s0, 0x60
	s_add_i32 m0, s26, 0x18000
	v_lshl_add_u64 v[6:7], v[6:7], 0, s[10:11]
	s_lshl_b32 s31, s5, 6
	s_lshl_b32 s5, s5, 13
	s_lshl_b32 s13, s34, 7
	s_waitcnt vmcnt(2)
	s_barrier
	global_load_lds_dwordx4 v[6:7], off
	v_lshl_add_u64 v[4:5], v[4:5], 0, s[10:11]
	s_add_i32 m0, s26, 0x1a000
	s_add_i32 s35, s26, 0x8000
	s_add_i32 s36, s26, 0xa000
	global_load_lds_dwordx4 v[4:5], off
	v_lshl_add_u64 v[0:1], v[0:1], 0, s[10:11]
	s_mov_b32 m0, s35
	s_add_u32 s0, s18, 0xb0080
	global_load_lds_dwordx4 v[0:1], off
	v_lshl_add_u64 v[0:1], v[2:3], 0, s[10:11]
	s_mov_b32 m0, s36
	s_addc_u32 s1, s19, 0
	global_load_lds_dwordx4 v[0:1], off
	s_add_i32 m0, s26, 0x1c000
	v_lshl_add_u64 v[0:1], s[0:1], 0, v[166:167]
	global_load_lds_dwordx4 v[0:1], off
	v_lshl_add_u64 v[0:1], s[0:1], 0, v[170:171]
	s_add_i32 m0, s26, 0x1e000
	v_bfe_u32 v195, v242, 4, 2
	global_load_lds_dwordx4 v[0:1], off
	v_and_b32_e32 v194, 15, v242
	v_lshlrev_b32_e32 v0, 4, v195
	v_lshlrev_b32_e32 v1, 2, v242
	v_lshl_or_b32 v0, v194, 6, v0
	v_and_b32_e32 v1, 32, v1
	v_bitop3_b32 v2, v0, s5, v1 bitop3:0xde
	v_bitop3_b32 v196, v0, s13, v1 bitop3:0xde
	v_lshrrev_b32_e32 v1, 1, v8
	v_mul_lo_u32 v0, v10, s4
	s_mov_b32 s5, 0xb000
	v_mad_u64_u32 v[0:1], s[14:15], v1, s5, v[0:1]
	v_or_b32_e32 v0, v0, v9
	s_mov_b64 s[0:1], 0xb0080
	v_add_lshl_u32 v0, v0, v11, 1
	v_mov_b32_e32 v1, v167
	v_lshl_add_u64 v[172:173], v[0:1], 0, s[0:1]
	v_lshrrev_b32_e32 v1, 1, v12
	v_mul_lo_u32 v0, v13, s4
	v_mad_u64_u32 v[0:1], s[4:5], v1, s5, v[0:1]
	s_waitcnt vmcnt(6)
	s_cmpk_lt_u32 s12, 0x100
	v_or_b32_e32 v0, v0, v14
	s_cselect_b64 s[12:13], -1, 0
	v_add_lshl_u32 v0, v0, v15, 1
	v_mov_b32_e32 v1, v167
	s_add_i32 s38, 0, 0x10000
	s_add_i32 s39, 0, 0x14000
	s_ashr_i32 s37, s52, 31
	v_lshl_add_u64 v[174:175], v[0:1], 0, s[0:1]
	v_mov_b64_e32 v[176:177], 0x200
	v_mov_b64_e32 v[178:179], 0x1ff
	v_add_u32_e32 v197, s38, v196
	v_add_u32_e32 v198, s39, v196
	v_add_u32_e32 v199, 0, v2
	s_barrier
	s_mov_b32 s101, 0
	s_branch .LBB0_1262

.LBB0_1272:
	s_add_u32 s44, s18, 0x100
	v_mov_b32_e32 v0, 0
	s_addc_u32 s45, s19, 0
	s_mov_b32 s46, -2
	s_cmp_lg_u32 s101, 0
	s_cbranch_scc0 .Lph1273_a
	v_mov_b32_e32 v1, v0
	v_mov_b32_e32 v2, v0
	v_mov_b32_e32 v3, v0
	v_mov_b32_e32 v4, v0
	v_mov_b32_e32 v5, v0
	v_mov_b32_e32 v6, v0
	v_mov_b32_e32 v7, v0
	v_mov_b32_e32 v12, v0
	v_mov_b32_e32 v13, v0
	v_mov_b32_e32 v14, v0
	v_mov_b32_e32 v15, v0
	v_mov_b32_e32 v20, v0
	v_mov_b32_e32 v21, v0
	v_mov_b32_e32 v22, v0
	v_mov_b32_e32 v23, v0
	v_mov_b32_e32 v28, v0
	v_mov_b32_e32 v29, v0
	v_mov_b32_e32 v30, v0
	v_mov_b32_e32 v31, v0
	v_mov_b32_e32 v36, v0
	v_mov_b32_e32 v37, v0
	v_mov_b32_e32 v38, v0
	v_mov_b32_e32 v39, v0
	v_mov_b32_e32 v44, v0
	v_mov_b32_e32 v45, v0
	v_mov_b32_e32 v46, v0
	v_mov_b32_e32 v47, v0
	v_mov_b32_e32 v52, v0
	v_mov_b32_e32 v53, v0
	v_mov_b32_e32 v54, v0
	v_mov_b32_e32 v55, v0
	v_mov_b32_e32 v8, v0
	v_mov_b32_e32 v9, v0
	v_mov_b32_e32 v10, v0
	v_mov_b32_e32 v11, v0
	v_mov_b32_e32 v16, v0
	v_mov_b32_e32 v17, v0
	v_mov_b32_e32 v18, v0
	v_mov_b32_e32 v19, v0
	v_mov_b32_e32 v24, v0
	v_mov_b32_e32 v25, v0
	v_mov_b32_e32 v26, v0
	v_mov_b32_e32 v27, v0
	v_mov_b32_e32 v32, v0
	v_mov_b32_e32 v33, v0
	v_mov_b32_e32 v34, v0
	v_mov_b32_e32 v35, v0
	v_mov_b32_e32 v40, v0
	v_mov_b32_e32 v41, v0
	v_mov_b32_e32 v42, v0
	v_mov_b32_e32 v43, v0
	v_mov_b32_e32 v48, v0
	v_mov_b32_e32 v49, v0
	v_mov_b32_e32 v50, v0
	v_mov_b32_e32 v51, v0
	v_mov_b32_e32 v56, v0
	v_mov_b32_e32 v57, v0
	v_mov_b32_e32 v58, v0
	v_mov_b32_e32 v59, v0
	v_mov_b32_e32 v60, v0
	v_mov_b32_e32 v61, v0
	v_mov_b32_e32 v62, v0
	v_mov_b32_e32 v63, v0
	v_mov_b32_e32 v64, v0
	v_mov_b32_e32 v65, v0
	v_mov_b32_e32 v66, v0
	v_mov_b32_e32 v67, v0
	v_mov_b32_e32 v68, v0
	v_mov_b32_e32 v69, v0
	v_mov_b32_e32 v70, v0
	v_mov_b32_e32 v71, v0
	v_mov_b32_e32 v76, v0
	v_mov_b32_e32 v77, v0
	v_mov_b32_e32 v78, v0
	v_mov_b32_e32 v79, v0
	v_mov_b32_e32 v84, v0
	v_mov_b32_e32 v85, v0
	v_mov_b32_e32 v86, v0
	v_mov_b32_e32 v87, v0
	v_mov_b32_e32 v92, v0
	v_mov_b32_e32 v93, v0
	v_mov_b32_e32 v94, v0
	v_mov_b32_e32 v95, v0
	v_mov_b32_e32 v100, v0
	v_mov_b32_e32 v101, v0
	v_mov_b32_e32 v102, v0
	v_mov_b32_e32 v103, v0
	v_mov_b32_e32 v108, v0
	v_mov_b32_e32 v109, v0
	v_mov_b32_e32 v110, v0
	v_mov_b32_e32 v111, v0
	v_mov_b32_e32 v116, v0
	v_mov_b32_e32 v117, v0
	v_mov_b32_e32 v118, v0
	v_mov_b32_e32 v119, v0
	v_mov_b32_e32 v72, v0
	v_mov_b32_e32 v73, v0
	v_mov_b32_e32 v74, v0
	v_mov_b32_e32 v75, v0
	v_mov_b32_e32 v80, v0
	v_mov_b32_e32 v81, v0
	v_mov_b32_e32 v82, v0
	v_mov_b32_e32 v83, v0
	v_mov_b32_e32 v88, v0
	v_mov_b32_e32 v89, v0
	v_mov_b32_e32 v90, v0
	v_mov_b32_e32 v91, v0
	v_mov_b32_e32 v96, v0
	v_mov_b32_e32 v97, v0
	v_mov_b32_e32 v98, v0
	v_mov_b32_e32 v99, v0
	v_mov_b32_e32 v104, v0
	v_mov_b32_e32 v105, v0
	v_mov_b32_e32 v106, v0
	v_mov_b32_e32 v107, v0
	v_mov_b32_e32 v112, v0
	v_mov_b32_e32 v113, v0
	v_mov_b32_e32 v114, v0
	v_mov_b32_e32 v115, v0
	v_mov_b32_e32 v120, v0
	v_mov_b32_e32 v121, v0
	v_mov_b32_e32 v122, v0
	v_mov_b32_e32 v123, v0
	v_mov_b32_e32 v124, v0
	v_mov_b32_e32 v125, v0
	v_mov_b32_e32 v126, v0
	v_mov_b32_e32 v127, v0
	s_barrier
	s_mov_b32 s101, 0
	s_branch .LBB0_1273
.Lph1273_a:
	s_add_u32 s18, s16, 0x100
	s_addc_u32 s19, s17, 0
	s_cmp_eq_u32 s46, 40
	s_cselect_b32 s23, s5, s19
	s_cselect_b32 s22, s4, s18
	s_cselect_b32 s21, s15, s45
	s_cselect_b32 s20, s14, s44
	v_lshl_add_u64 v[192:193], s[16:17], 0, v[172:173]
	s_add_i32 m0, s26, 0xc000
	s_nop 0
	global_load_lds_dwordx4 v[192:193], off
	v_lshl_add_u64 v[192:193], s[16:17], 0, v[174:175]
	s_add_i32 m0, s26, 0xe000
	s_nop 0
	global_load_lds_dwordx4 v[192:193], off
	ds_read_b128 v[128:131], v197
	ds_read_b128 v[132:135], v197 offset:1024
	ds_read_b128 v[136:139], v197 offset:2048
	ds_read_b128 v[140:143], v197 offset:3072
	ds_read_b128 v[144:147], v198
	ds_read_b128 v[148:151], v198 offset:1024
	ds_read_b128 v[152:155], v198 offset:2048
	ds_read_b128 v[156:159], v198 offset:3072
	ds_read_b128 v[160:163], v199
	ds_read_b128 v[180:183], v199 offset:1024
	ds_read_b128 v[184:187], v199 offset:2048
	ds_read_b128 v[188:191], v199 offset:3072
	ds_read_b128 v[200:203], v199 offset:4096
	ds_read_b128 v[204:207], v199 offset:5120
	ds_read_b128 v[208:211], v199 offset:6144
	ds_read_b128 v[212:215], v199 offset:7168
	v_mov_b32_e32 v1, v0
	v_mov_b32_e32 v2, v0
	v_mov_b32_e32 v3, v0
	v_mov_b32_e32 v4, v0
	v_mov_b32_e32 v5, v0
	v_mov_b32_e32 v6, v0
	v_mov_b32_e32 v7, v0
	v_mov_b32_e32 v12, v0
	v_mov_b32_e32 v13, v0
	v_mov_b32_e32 v14, v0
	v_mov_b32_e32 v15, v0
	v_mov_b32_e32 v20, v0
	v_mov_b32_e32 v21, v0
	v_mov_b32_e32 v22, v0
	v_mov_b32_e32 v23, v0
	v_mov_b32_e32 v28, v0
	v_mov_b32_e32 v29, v0
	v_mov_b32_e32 v30, v0
	v_mov_b32_e32 v31, v0
	v_mov_b32_e32 v36, v0
	v_mov_b32_e32 v37, v0
	v_mov_b32_e32 v38, v0
	v_mov_b32_e32 v39, v0
	v_mov_b32_e32 v44, v0
	v_mov_b32_e32 v45, v0
	v_mov_b32_e32 v46, v0
	v_mov_b32_e32 v47, v0
	v_mov_b32_e32 v52, v0
	v_mov_b32_e32 v53, v0
	v_mov_b32_e32 v54, v0
	v_mov_b32_e32 v55, v0
	v_mov_b32_e32 v8, v0
	v_mov_b32_e32 v9, v0
	v_mov_b32_e32 v10, v0
	v_mov_b32_e32 v11, v0
	v_mov_b32_e32 v16, v0
	v_mov_b32_e32 v17, v0
	v_mov_b32_e32 v18, v0
	v_mov_b32_e32 v19, v0
	v_mov_b32_e32 v24, v0
	v_mov_b32_e32 v25, v0
	v_mov_b32_e32 v26, v0
	v_mov_b32_e32 v27, v0
	v_mov_b32_e32 v32, v0
	v_mov_b32_e32 v33, v0
	v_mov_b32_e32 v34, v0
	v_mov_b32_e32 v35, v0
	v_mov_b32_e32 v40, v0
	v_mov_b32_e32 v41, v0
	v_mov_b32_e32 v42, v0
	v_mov_b32_e32 v43, v0
	v_mov_b32_e32 v48, v0
	v_mov_b32_e32 v49, v0
	v_mov_b32_e32 v50, v0
	v_mov_b32_e32 v51, v0
	v_mov_b32_e32 v56, v0
	v_mov_b32_e32 v57, v0
	v_mov_b32_e32 v58, v0
	v_mov_b32_e32 v59, v0
	v_mov_b32_e32 v60, v0
	v_mov_b32_e32 v61, v0
	v_mov_b32_e32 v62, v0
	v_mov_b32_e32 v63, v0
	v_mov_b32_e32 v64, v0
	v_mov_b32_e32 v65, v0
	v_mov_b32_e32 v66, v0
	v_mov_b32_e32 v67, v0
	v_mov_b32_e32 v68, v0
	v_mov_b32_e32 v69, v0
	v_mov_b32_e32 v70, v0
	v_mov_b32_e32 v71, v0
	v_mov_b32_e32 v76, v0
	v_mov_b32_e32 v77, v0
	v_mov_b32_e32 v78, v0
	v_mov_b32_e32 v79, v0
	v_mov_b32_e32 v84, v0
	v_mov_b32_e32 v85, v0
	v_mov_b32_e32 v86, v0
	v_mov_b32_e32 v87, v0
	v_mov_b32_e32 v92, v0
	v_mov_b32_e32 v93, v0
	v_mov_b32_e32 v94, v0
	v_mov_b32_e32 v95, v0
	v_mov_b32_e32 v100, v0
	v_mov_b32_e32 v101, v0
	v_mov_b32_e32 v102, v0
	v_mov_b32_e32 v103, v0
	v_mov_b32_e32 v108, v0
	v_mov_b32_e32 v109, v0
	v_mov_b32_e32 v110, v0
	v_mov_b32_e32 v111, v0
	v_mov_b32_e32 v116, v0
	v_mov_b32_e32 v117, v0
	v_mov_b32_e32 v118, v0
	v_mov_b32_e32 v119, v0
	v_mov_b32_e32 v72, v0
	v_mov_b32_e32 v73, v0
	v_mov_b32_e32 v74, v0
	v_mov_b32_e32 v75, v0
	v_mov_b32_e32 v80, v0
	v_mov_b32_e32 v81, v0
	v_mov_b32_e32 v82, v0
	v_mov_b32_e32 v83, v0
	v_mov_b32_e32 v88, v0
	v_mov_b32_e32 v89, v0
	v_mov_b32_e32 v90, v0
	v_mov_b32_e32 v91, v0
	v_mov_b32_e32 v96, v0
	v_mov_b32_e32 v97, v0
	v_mov_b32_e32 v98, v0
	v_mov_b32_e32 v99, v0
	v_mov_b32_e32 v104, v0
	v_mov_b32_e32 v105, v0
	v_mov_b32_e32 v106, v0
	v_mov_b32_e32 v107, v0
	v_mov_b32_e32 v112, v0
	v_mov_b32_e32 v113, v0
	v_mov_b32_e32 v114, v0
	v_mov_b32_e32 v115, v0
	v_mov_b32_e32 v120, v0
	v_mov_b32_e32 v121, v0
	v_mov_b32_e32 v122, v0
	v_mov_b32_e32 v123, v0
	v_mov_b32_e32 v124, v0
	v_mov_b32_e32 v125, v0
	v_mov_b32_e32 v126, v0
	v_mov_b32_e32 v127, v0
	s_branch .Lph1273_w

.Lph1273_w:
	s_nop 0
	s_nop 0
	s_waitcnt vmcnt(8)
	s_waitcnt lgkmcnt(0)
	s_setprio 1
	s_barrier
	v_mfma_f32_16x16x32_bf16 v[124:127], v[128:131], v[160:163], v[124:127]
	v_mfma_f32_16x16x32_bf16 v[120:123], v[136:139], v[160:163], v[120:123]
	v_mfma_f32_16x16x32_bf16 v[112:115], v[128:131], v[184:187], v[112:115]
	v_mfma_f32_16x16x32_bf16 v[104:107], v[136:139], v[184:187], v[104:107]
	v_mfma_f32_16x16x32_bf16 v[96:99], v[128:131], v[200:203], v[96:99]
	v_mfma_f32_16x16x32_bf16 v[88:91], v[136:139], v[200:203], v[88:91]
	v_mfma_f32_16x16x32_bf16 v[80:83], v[128:131], v[208:211], v[80:83]
	v_mfma_f32_16x16x32_bf16 v[72:75], v[136:139], v[208:211], v[72:75]
	v_mfma_f32_16x16x32_bf16 v[124:127], v[132:135], v[180:183], v[124:127]
	v_mfma_f32_16x16x32_bf16 v[120:123], v[140:143], v[180:183], v[120:123]
	v_mfma_f32_16x16x32_bf16 v[112:115], v[132:135], v[188:191], v[112:115]
	v_mfma_f32_16x16x32_bf16 v[104:107], v[140:143], v[188:191], v[104:107]
	v_mfma_f32_16x16x32_bf16 v[96:99], v[132:135], v[204:207], v[96:99]
	v_mfma_f32_16x16x32_bf16 v[88:91], v[140:143], v[204:207], v[88:91]
	v_mfma_f32_16x16x32_bf16 v[80:83], v[132:135], v[212:215], v[80:83]
	v_mfma_f32_16x16x32_bf16 v[72:75], v[140:143], v[212:215], v[72:75]
	s_setprio 0
	s_setprio 1
	v_mfma_f32_16x16x32_bf16 v[116:119], v[144:147], v[160:163], v[116:119]
	v_mfma_f32_16x16x32_bf16 v[108:111], v[152:155], v[160:163], v[108:111]
	v_mfma_f32_16x16x32_bf16 v[100:103], v[144:147], v[184:187], v[100:103]
	v_mfma_f32_16x16x32_bf16 v[92:95], v[152:155], v[184:187], v[92:95]
	v_mfma_f32_16x16x32_bf16 v[84:87], v[144:147], v[200:203], v[84:87]
	v_mfma_f32_16x16x32_bf16 v[76:79], v[152:155], v[200:203], v[76:79]
	v_mfma_f32_16x16x32_bf16 v[68:71], v[144:147], v[208:211], v[68:71]
	v_mfma_f32_16x16x32_bf16 v[64:67], v[152:155], v[208:211], v[64:67]
	v_mfma_f32_16x16x32_bf16 v[116:119], v[148:151], v[180:183], v[116:119]
	v_mfma_f32_16x16x32_bf16 v[108:111], v[156:159], v[180:183], v[108:111]
	v_mfma_f32_16x16x32_bf16 v[100:103], v[148:151], v[188:191], v[100:103]
	v_mfma_f32_16x16x32_bf16 v[92:95], v[156:159], v[188:191], v[92:95]
	v_mfma_f32_16x16x32_bf16 v[84:87], v[148:151], v[204:207], v[84:87]
	v_mfma_f32_16x16x32_bf16 v[76:79], v[156:159], v[204:207], v[76:79]
	v_mfma_f32_16x16x32_bf16 v[68:71], v[148:151], v[212:215], v[68:71]
	v_mfma_f32_16x16x32_bf16 v[64:67], v[156:159], v[212:215], v[64:67]
	s_barrier
	s_setprio 0
	s_add_i32 s16, s38, s25
	v_lshl_add_u64 v[192:193], s[20:21], 0, v[166:167]
	s_mov_b32 m0, s16
	s_nop 0
	global_load_lds_dwordx4 v[192:193], off
	s_add_i32 m0, s16, 0x2000
	s_add_u32 s16, s20, 0xb0000
	v_lshl_add_u64 v[216:217], s[20:21], 0, v[170:171]
	s_addc_u32 s17, s21, 0
	s_add_i32 s47, s39, s25
	global_load_lds_dwordx4 v[216:217], off
	v_lshl_add_u64 v[218:219], s[16:17], 0, v[166:167]
	s_mov_b32 m0, s47
	v_lshl_add_u64 v[220:221], s[22:23], 0, v[168:169]
	global_load_lds_dwordx4 v[218:219], off
	v_lshl_add_u64 v[218:219], s[16:17], 0, v[170:171]
	s_add_i32 m0, s47, 0x2000
	s_nop 0
	global_load_lds_dwordx4 v[218:219], off
	v_lshl_add_u64 v[218:219], s[22:23], 0, v[164:165]
	s_mov_b32 m0, s26
	s_nop 0
	global_load_lds_dwordx4 v[218:219], off
	s_mov_b32 m0, s27
	s_nop 0
	global_load_lds_dwordx4 v[220:221], off
	ds_read_b128 v[160:163], v199 offset:16384
	ds_read_b128 v[180:183], v199 offset:17408
	ds_read_b128 v[184:187], v199 offset:18432
	ds_read_b128 v[188:191], v199 offset:19456
	ds_read_b128 v[200:203], v199 offset:20480
	ds_read_b128 v[204:207], v199 offset:21504
	ds_read_b128 v[208:211], v199 offset:22528
	ds_read_b128 v[212:215], v199 offset:23552
	s_nop 0
	s_waitcnt vmcnt(8)
	s_waitcnt lgkmcnt(0)
	s_setprio 1
	s_barrier
	v_mfma_f32_16x16x32_bf16 v[60:63], v[128:131], v[160:163], v[60:63]
	v_mfma_f32_16x16x32_bf16 v[56:59], v[136:139], v[160:163], v[56:59]
	v_mfma_f32_16x16x32_bf16 v[48:51], v[128:131], v[184:187], v[48:51]
	v_mfma_f32_16x16x32_bf16 v[40:43], v[136:139], v[184:187], v[40:43]
	v_mfma_f32_16x16x32_bf16 v[32:35], v[128:131], v[200:203], v[32:35]
	v_mfma_f32_16x16x32_bf16 v[24:27], v[136:139], v[200:203], v[24:27]
	v_mfma_f32_16x16x32_bf16 v[16:19], v[128:131], v[208:211], v[16:19]
	v_mfma_f32_16x16x32_bf16 v[8:11], v[136:139], v[208:211], v[8:11]
	v_mfma_f32_16x16x32_bf16 v[60:63], v[132:135], v[180:183], v[60:63]
	v_mfma_f32_16x16x32_bf16 v[56:59], v[140:143], v[180:183], v[56:59]
	v_mfma_f32_16x16x32_bf16 v[48:51], v[132:135], v[188:191], v[48:51]
	v_mfma_f32_16x16x32_bf16 v[40:43], v[140:143], v[188:191], v[40:43]
	v_mfma_f32_16x16x32_bf16 v[32:35], v[132:135], v[204:207], v[32:35]
	v_mfma_f32_16x16x32_bf16 v[24:27], v[140:143], v[204:207], v[24:27]
	v_mfma_f32_16x16x32_bf16 v[16:19], v[132:135], v[212:215], v[16:19]
	v_mfma_f32_16x16x32_bf16 v[8:11], v[140:143], v[212:215], v[8:11]
	s_setprio 0
	s_setprio 1
	v_mfma_f32_16x16x32_bf16 v[52:55], v[144:147], v[160:163], v[52:55]
	v_mfma_f32_16x16x32_bf16 v[44:47], v[152:155], v[160:163], v[44:47]
	v_mfma_f32_16x16x32_bf16 v[36:39], v[144:147], v[184:187], v[36:39]
	v_mfma_f32_16x16x32_bf16 v[28:31], v[152:155], v[184:187], v[28:31]
	v_mfma_f32_16x16x32_bf16 v[20:23], v[144:147], v[200:203], v[20:23]
	v_mfma_f32_16x16x32_bf16 v[12:15], v[152:155], v[200:203], v[12:15]
	v_mfma_f32_16x16x32_bf16 v[4:7], v[144:147], v[208:211], v[4:7]
	v_mfma_f32_16x16x32_bf16 v[0:3], v[152:155], v[208:211], v[0:3]
	v_mfma_f32_16x16x32_bf16 v[52:55], v[148:151], v[180:183], v[52:55]
	v_mfma_f32_16x16x32_bf16 v[44:47], v[156:159], v[180:183], v[44:47]
	v_mfma_f32_16x16x32_bf16 v[36:39], v[148:151], v[188:191], v[36:39]
	v_mfma_f32_16x16x32_bf16 v[28:31], v[156:159], v[188:191], v[28:31]
	v_mfma_f32_16x16x32_bf16 v[20:23], v[148:151], v[204:207], v[20:23]
	v_mfma_f32_16x16x32_bf16 v[12:15], v[156:159], v[204:207], v[12:15]
	v_mfma_f32_16x16x32_bf16 v[4:7], v[148:151], v[212:215], v[4:7]
	v_mfma_f32_16x16x32_bf16 v[0:3], v[156:159], v[212:215], v[0:3]
	s_barrier
	s_setprio 0
	s_add_i32 s47, 0, 0x18000
	s_add_i32 s48, 0, 0x1c000
	s_add_u32 s16, s22, 0xb0000
	s_addc_u32 s17, s23, 0
	s_mov_b32 m0, s28
	v_lshl_add_u64 v[222:223], s[16:17], 0, v[164:165]
	global_load_lds_dwordx4 v[222:223], off
	v_lshl_add_u64 v[222:223], s[16:17], 0, v[168:169]
	s_mov_b32 m0, s29
	s_nop 0
	global_load_lds_dwordx4 v[222:223], off
	v_add_u32_e32 v140, s47, v196
	v_add_u32_e32 v156, s48, v196
	ds_read_b128 v[128:131], v140
	ds_read_b128 v[132:135], v140 offset:1024
	ds_read_b128 v[136:139], v140 offset:2048
	ds_read_b128 v[140:143], v140 offset:3072
	ds_read_b128 v[144:147], v156
	ds_read_b128 v[148:151], v156 offset:1024
	ds_read_b128 v[152:155], v156 offset:2048
	ds_read_b128 v[156:159], v156 offset:3072
	ds_read_b128 v[160:163], v199 offset:32768
	ds_read_b128 v[180:183], v199 offset:33792
	ds_read_b128 v[184:187], v199 offset:34816
	ds_read_b128 v[188:191], v199 offset:35840
	ds_read_b128 v[200:203], v199 offset:36864
	ds_read_b128 v[204:207], v199 offset:37888
	ds_read_b128 v[208:211], v199 offset:38912
	ds_read_b128 v[212:215], v199 offset:39936
	s_waitcnt vmcnt(8)
	s_waitcnt lgkmcnt(0)
	s_setprio 1
	s_barrier
	v_mfma_f32_16x16x32_bf16 v[124:127], v[128:131], v[160:163], v[124:127]
	v_mfma_f32_16x16x32_bf16 v[120:123], v[136:139], v[160:163], v[120:123]
	v_mfma_f32_16x16x32_bf16 v[112:115], v[128:131], v[184:187], v[112:115]
	v_mfma_f32_16x16x32_bf16 v[104:107], v[136:139], v[184:187], v[104:107]
	v_mfma_f32_16x16x32_bf16 v[96:99], v[128:131], v[200:203], v[96:99]
	v_mfma_f32_16x16x32_bf16 v[88:91], v[136:139], v[200:203], v[88:91]
	v_mfma_f32_16x16x32_bf16 v[80:83], v[128:131], v[208:211], v[80:83]
	v_mfma_f32_16x16x32_bf16 v[72:75], v[136:139], v[208:211], v[72:75]
	v_mfma_f32_16x16x32_bf16 v[124:127], v[132:135], v[180:183], v[124:127]
	v_mfma_f32_16x16x32_bf16 v[120:123], v[140:143], v[180:183], v[120:123]
	v_mfma_f32_16x16x32_bf16 v[112:115], v[132:135], v[188:191], v[112:115]
	v_mfma_f32_16x16x32_bf16 v[104:107], v[140:143], v[188:191], v[104:107]
	v_mfma_f32_16x16x32_bf16 v[96:99], v[132:135], v[204:207], v[96:99]
	v_mfma_f32_16x16x32_bf16 v[88:91], v[140:143], v[204:207], v[88:91]
	v_mfma_f32_16x16x32_bf16 v[80:83], v[132:135], v[212:215], v[80:83]
	v_mfma_f32_16x16x32_bf16 v[72:75], v[140:143], v[212:215], v[72:75]
	s_setprio 0
	s_setprio 1
	v_mfma_f32_16x16x32_bf16 v[116:119], v[144:147], v[160:163], v[116:119]
	v_mfma_f32_16x16x32_bf16 v[108:111], v[152:155], v[160:163], v[108:111]
	v_mfma_f32_16x16x32_bf16 v[100:103], v[144:147], v[184:187], v[100:103]
	v_mfma_f32_16x16x32_bf16 v[92:95], v[152:155], v[184:187], v[92:95]
	v_mfma_f32_16x16x32_bf16 v[84:87], v[144:147], v[200:203], v[84:87]
	v_mfma_f32_16x16x32_bf16 v[76:79], v[152:155], v[200:203], v[76:79]
	v_mfma_f32_16x16x32_bf16 v[68:71], v[144:147], v[208:211], v[68:71]
	v_mfma_f32_16x16x32_bf16 v[64:67], v[152:155], v[208:211], v[64:67]
	v_mfma_f32_16x16x32_bf16 v[116:119], v[148:151], v[180:183], v[116:119]
	v_mfma_f32_16x16x32_bf16 v[108:111], v[156:159], v[180:183], v[108:111]
	v_mfma_f32_16x16x32_bf16 v[100:103], v[148:151], v[188:191], v[100:103]
	v_mfma_f32_16x16x32_bf16 v[92:95], v[156:159], v[188:191], v[92:95]
	v_mfma_f32_16x16x32_bf16 v[84:87], v[148:151], v[204:207], v[84:87]
	v_mfma_f32_16x16x32_bf16 v[76:79], v[156:159], v[204:207], v[76:79]
	v_mfma_f32_16x16x32_bf16 v[68:71], v[148:151], v[212:215], v[68:71]
	v_mfma_f32_16x16x32_bf16 v[64:67], v[156:159], v[212:215], v[64:67]
	s_barrier
	s_setprio 0
	s_add_i32 s16, s47, s25
	v_lshl_add_u64 v[192:193], v[192:193], 0, s[10:11]
	s_mov_b32 m0, s16
	s_nop 0
	global_load_lds_dwordx4 v[192:193], off
	s_add_i32 m0, s16, 0x2000
	s_add_u32 s16, s20, 0xb0080
	v_lshl_add_u64 v[192:193], v[216:217], 0, s[10:11]
	s_addc_u32 s17, s21, 0
	s_add_i32 s20, s48, s25
	global_load_lds_dwordx4 v[192:193], off
	v_lshl_add_u64 v[192:193], s[16:17], 0, v[166:167]
	s_mov_b32 m0, s20
	s_nop 0
	global_load_lds_dwordx4 v[192:193], off
	v_lshl_add_u64 v[192:193], s[16:17], 0, v[170:171]
	s_add_i32 m0, s20, 0x2000
	s_nop 0
	global_load_lds_dwordx4 v[192:193], off
	v_lshl_add_u64 v[192:193], v[218:219], 0, s[10:11]
	s_mov_b32 m0, s35
	s_nop 0
	global_load_lds_dwordx4 v[192:193], off
	v_lshl_add_u64 v[192:193], v[220:221], 0, s[10:11]
	s_mov_b32 m0, s36
	s_nop 0
	global_load_lds_dwordx4 v[192:193], off
	ds_read_b128 v[160:163], v199 offset:49152
	ds_read_b128 v[180:183], v199 offset:50176
	ds_read_b128 v[184:187], v199 offset:51200
	ds_read_b128 v[188:191], v199 offset:52224
	ds_read_b128 v[200:203], v199 offset:53248
	ds_read_b128 v[204:207], v199 offset:54272
	ds_read_b128 v[208:211], v199 offset:55296
	ds_read_b128 v[212:215], v199 offset:56320
	s_waitcnt vmcnt(8)
	s_waitcnt lgkmcnt(0)
	s_setprio 1
	s_barrier
	v_mfma_f32_16x16x32_bf16 v[60:63], v[128:131], v[160:163], v[60:63]
	v_mfma_f32_16x16x32_bf16 v[56:59], v[136:139], v[160:163], v[56:59]
	v_mfma_f32_16x16x32_bf16 v[48:51], v[128:131], v[184:187], v[48:51]
	v_mfma_f32_16x16x32_bf16 v[40:43], v[136:139], v[184:187], v[40:43]
	v_mfma_f32_16x16x32_bf16 v[32:35], v[128:131], v[200:203], v[32:35]
	v_mfma_f32_16x16x32_bf16 v[24:27], v[136:139], v[200:203], v[24:27]
	v_mfma_f32_16x16x32_bf16 v[16:19], v[128:131], v[208:211], v[16:19]
	v_mfma_f32_16x16x32_bf16 v[8:11], v[136:139], v[208:211], v[8:11]
	v_mfma_f32_16x16x32_bf16 v[60:63], v[132:135], v[180:183], v[60:63]
	v_mfma_f32_16x16x32_bf16 v[56:59], v[140:143], v[180:183], v[56:59]
	v_mfma_f32_16x16x32_bf16 v[48:51], v[132:135], v[188:191], v[48:51]
	v_mfma_f32_16x16x32_bf16 v[40:43], v[140:143], v[188:191], v[40:43]
	v_mfma_f32_16x16x32_bf16 v[32:35], v[132:135], v[204:207], v[32:35]
	v_mfma_f32_16x16x32_bf16 v[24:27], v[140:143], v[204:207], v[24:27]
	v_mfma_f32_16x16x32_bf16 v[16:19], v[132:135], v[212:215], v[16:19]
	v_mfma_f32_16x16x32_bf16 v[8:11], v[140:143], v[212:215], v[8:11]
	s_setprio 0
	s_setprio 1
	v_mfma_f32_16x16x32_bf16 v[52:55], v[144:147], v[160:163], v[52:55]
	v_mfma_f32_16x16x32_bf16 v[44:47], v[152:155], v[160:163], v[44:47]
	v_mfma_f32_16x16x32_bf16 v[36:39], v[144:147], v[184:187], v[36:39]
	v_mfma_f32_16x16x32_bf16 v[28:31], v[152:155], v[184:187], v[28:31]
	v_mfma_f32_16x16x32_bf16 v[20:23], v[144:147], v[200:203], v[20:23]
	v_mfma_f32_16x16x32_bf16 v[12:15], v[152:155], v[200:203], v[12:15]
	v_mfma_f32_16x16x32_bf16 v[4:7], v[144:147], v[208:211], v[4:7]
	v_mfma_f32_16x16x32_bf16 v[0:3], v[152:155], v[208:211], v[0:3]
	v_mfma_f32_16x16x32_bf16 v[52:55], v[148:151], v[180:183], v[52:55]
	v_mfma_f32_16x16x32_bf16 v[44:47], v[156:159], v[180:183], v[44:47]
	v_mfma_f32_16x16x32_bf16 v[36:39], v[148:151], v[188:191], v[36:39]
	v_mfma_f32_16x16x32_bf16 v[28:31], v[156:159], v[188:191], v[28:31]
	v_mfma_f32_16x16x32_bf16 v[20:23], v[148:151], v[204:207], v[20:23]
	v_mfma_f32_16x16x32_bf16 v[12:15], v[156:159], v[204:207], v[12:15]
	v_mfma_f32_16x16x32_bf16 v[4:7], v[148:151], v[212:215], v[4:7]
	v_mfma_f32_16x16x32_bf16 v[0:3], v[156:159], v[212:215], v[0:3]
	s_barrier
	s_setprio 0
	s_add_i32 s46, s46, 2
	s_add_u32 s44, s44, 0x100
	s_addc_u32 s45, s45, 0
	s_cmp_gt_u32 s46, 41
	s_mov_b64 s[16:17], s[18:19]
	s_cbranch_scc0 .LBB0_1273
	s_and_b64 vcc, exec, s[12:13]
	s_cbranch_vccz .LBB0_1276
	s_barrier
.LBB0_1276:
	v_mov_b32_e32 v128, v194
	v_mov_b32_e32 v129, v195
	s_lshl_b32 s16, s43, 8
	s_add_i32 s16, s16, s31
	v_add_u32_e32 v128, s16, v128
	s_lshl_b32 s16, s42, 8
	s_or_b32 s16, s16, s34
	v_lshl_add_u32 v130, v129, 3, s16
	v_ashrrev_i32_e32 v131, 31, v130
	v_ashrrev_i32_e32 v129, 31, v128
	v_lshl_add_u64 v[132:133], v[130:131], 1, s[58:59]
	v_lshlrev_b64 v[134:135], 11, v[128:129]
	v_add_u32_e32 v228, 16, v128
	v_lshl_add_u64 v[134:135], v[132:133], 0, v[134:135]
	v_ashrrev_i32_e32 v229, 31, v228
	global_load_dwordx4 v[200:203], v[134:135], off
	global_load_dwordx4 v[204:207], v[134:135], off offset:256
	v_lshlrev_b64 v[134:135], 11, v[228:229]
	v_lshl_add_u64 v[134:135], v[132:133], 0, v[134:135]
	global_load_dwordx4 v[208:211], v[134:135], off
	v_add_u32_e32 v192, 32, v128
	v_ashrrev_i32_e32 v193, 31, v192
	global_load_dwordx4 v[212:215], v[134:135], off offset:256
	v_lshlrev_b64 v[182:183], 2, v[130:131]
	v_lshlrev_b64 v[130:131], 11, v[192:193]
	v_lshl_add_u64 v[130:131], v[132:133], 0, v[130:131]
	global_load_dwordx4 v[216:219], v[130:131], off
	v_add_u32_e32 v190, 48, v128
	v_add_u32_e32 v188, 0x80, v128
	v_add_u32_e32 v186, 0x90, v128
	v_add_u32_e32 v184, 0xa0, v128
	v_add_u32_e32 v180, 0xb0, v128
	v_ashrrev_i32_e32 v191, 31, v190
	v_ashrrev_i32_e32 v189, 31, v188
	v_ashrrev_i32_e32 v187, 31, v186
	v_ashrrev_i32_e32 v185, 31, v184
	v_ashrrev_i32_e32 v181, 31, v180
	v_lshlrev_b64 v[128:129], 12, v[128:129]
	v_lshlrev_b64 v[134:135], 11, v[190:191]
	v_lshlrev_b64 v[136:137], 11, v[188:189]
	v_lshlrev_b64 v[138:139], 11, v[186:187]
	v_lshlrev_b64 v[140:141], 11, v[184:185]
	v_lshlrev_b64 v[142:143], 11, v[180:181]
	v_lshl_add_u64 v[128:129], s[6:7], 0, v[128:129]
	v_lshl_add_u64 v[134:135], v[132:133], 0, v[134:135]
	v_lshl_add_u64 v[136:137], v[132:133], 0, v[136:137]
	v_lshl_add_u64 v[138:139], v[132:133], 0, v[138:139]
	v_lshl_add_u64 v[230:231], v[132:133], 0, v[140:141]
	v_lshl_add_u64 v[232:233], v[132:133], 0, v[142:143]
	v_lshl_add_u64 v[234:235], v[128:129], 0, v[182:183]
	global_load_dwordx4 v[220:223], v[130:131], off offset:256
	global_load_dwordx4 v[224:227], v[134:135], off
	global_load_dwordx4 v[160:163], v[134:135], off offset:256
	global_load_dwordx4 v[156:159], v[136:137], off
	global_load_dwordx4 v[152:155], v[136:137], off offset:256
	global_load_dwordx4 v[148:151], v[138:139], off
	global_load_dwordx4 v[144:147], v[138:139], off offset:256
	global_load_dwordx4 v[140:143], v[230:231], off
	s_nop 0
	global_load_dwordx4 v[136:139], v[230:231], off offset:256
	global_load_dwordx4 v[132:135], v[232:233], off
	global_load_dwordx4 v[128:131], v[232:233], off offset:256
	s_and_b64 vcc, exec, s[0:1]
	s_mov_b64 s[0:1], -1
	s_waitcnt vmcnt(0)
	v_lshlrev_b32_e32 v230, 16, v200
	v_and_b32_e32 v231, 0xffff0000, v200
	v_lshlrev_b32_e32 v200, 16, v201
	v_and_b32_e32 v201, 0xffff0000, v201
	v_lshlrev_b32_e32 v238, 16, v206
	v_and_b32_e32 v239, 0xffff0000, v206
	v_lshlrev_b32_e32 v232, 16, v202
	v_and_b32_e32 v233, 0xffff0000, v202
	v_lshlrev_b32_e32 v202, 16, v203
	v_and_b32_e32 v203, 0xffff0000, v203
	v_lshlrev_b32_e32 v236, 16, v204
	v_and_b32_e32 v237, 0xffff0000, v204
	v_lshlrev_b32_e32 v204, 16, v205
	v_and_b32_e32 v205, 0xffff0000, v205
	v_lshlrev_b32_e32 v206, 16, v207
	v_and_b32_e32 v207, 0xffff0000, v207
	v_pk_add_f32 v[126:127], v[126:127], v[200:201]
	v_pk_add_f32 v[124:125], v[124:125], v[230:231]
	v_pk_add_f32 v[108:109], v[108:109], v[238:239]
	v_pk_add_f32 v[122:123], v[122:123], v[202:203]
	v_pk_add_f32 v[120:121], v[120:121], v[232:233]
	v_pk_add_f32 v[118:119], v[118:119], v[204:205]
	v_pk_add_f32 v[116:117], v[116:117], v[236:237]
	v_pk_add_f32 v[110:111], v[110:111], v[206:207]
	global_store_dwordx4 v[234:235], v[124:127], off nt
	global_store_dwordx4 v[234:235], v[120:123], off offset:16 nt
	global_store_dwordx4 v[234:235], v[116:119], off offset:512 nt
	global_store_dwordx4 v[234:235], v[108:111], off offset:528 nt
	s_nop 0
	v_lshlrev_b32_e32 v116, 16, v210
	v_lshlrev_b32_e32 v108, 16, v208
	v_and_b32_e32 v109, 0xffff0000, v208
	v_pk_add_f32 v[108:109], v[112:113], v[108:109]
	v_lshlrev_b64 v[112:113], 12, v[228:229]
	v_lshlrev_b32_e32 v110, 16, v209
	v_and_b32_e32 v111, 0xffff0000, v209
	v_and_b32_e32 v117, 0xffff0000, v210
	v_lshlrev_b32_e32 v118, 16, v211
	v_and_b32_e32 v119, 0xffff0000, v211
	v_lshl_add_u64 v[112:113], s[6:7], 0, v[112:113]
	v_pk_add_f32 v[110:111], v[114:115], v[110:111]
	v_pk_add_f32 v[106:107], v[106:107], v[118:119]
	v_pk_add_f32 v[104:105], v[104:105], v[116:117]
	v_lshl_add_u64 v[112:113], v[112:113], 0, v[182:183]
	global_store_dwordx4 v[112:113], v[108:111], off nt
	global_store_dwordx4 v[112:113], v[104:107], off offset:16 nt
	s_nop 0
	v_lshlrev_b32_e32 v108, 16, v214
	v_lshlrev_b32_e32 v104, 16, v212
	v_and_b32_e32 v105, 0xffff0000, v212
	v_lshlrev_b32_e32 v106, 16, v213
	v_and_b32_e32 v107, 0xffff0000, v213
	v_and_b32_e32 v109, 0xffff0000, v214
	v_lshlrev_b32_e32 v110, 16, v215
	v_and_b32_e32 v111, 0xffff0000, v215
	v_pk_add_f32 v[102:103], v[102:103], v[106:107]
	v_pk_add_f32 v[100:101], v[100:101], v[104:105]
	v_pk_add_f32 v[92:93], v[92:93], v[108:109]
	v_pk_add_f32 v[94:95], v[94:95], v[110:111]
	global_store_dwordx4 v[112:113], v[100:103], off offset:512 nt
	global_store_dwordx4 v[112:113], v[92:95], off offset:528 nt
	s_nop 0
	v_lshlrev_b32_e32 v100, 16, v218
	v_lshlrev_b32_e32 v92, 16, v216
	v_and_b32_e32 v93, 0xffff0000, v216
	v_pk_add_f32 v[92:93], v[96:97], v[92:93]
	v_lshlrev_b64 v[96:97], 12, v[192:193]
	v_lshlrev_b32_e32 v94, 16, v217
	v_and_b32_e32 v95, 0xffff0000, v217
	v_and_b32_e32 v101, 0xffff0000, v218
	v_lshlrev_b32_e32 v102, 16, v219
	v_and_b32_e32 v103, 0xffff0000, v219
	v_lshl_add_u64 v[96:97], s[6:7], 0, v[96:97]
	v_pk_add_f32 v[94:95], v[98:99], v[94:95]
	v_pk_add_f32 v[90:91], v[90:91], v[102:103]
	v_pk_add_f32 v[88:89], v[88:89], v[100:101]
	v_lshl_add_u64 v[96:97], v[96:97], 0, v[182:183]
	global_store_dwordx4 v[96:97], v[92:95], off nt
	global_store_dwordx4 v[96:97], v[88:91], off offset:16 nt
	s_nop 0
	v_lshlrev_b32_e32 v92, 16, v222
	v_lshlrev_b32_e32 v88, 16, v220
	v_and_b32_e32 v89, 0xffff0000, v220
	v_lshlrev_b32_e32 v90, 16, v221
	v_and_b32_e32 v91, 0xffff0000, v221
	v_and_b32_e32 v93, 0xffff0000, v222
	v_lshlrev_b32_e32 v94, 16, v223
	v_and_b32_e32 v95, 0xffff0000, v223
	v_pk_add_f32 v[86:87], v[86:87], v[90:91]
	v_pk_add_f32 v[84:85], v[84:85], v[88:89]
	v_pk_add_f32 v[76:77], v[76:77], v[92:93]
	v_pk_add_f32 v[78:79], v[78:79], v[94:95]
	global_store_dwordx4 v[96:97], v[84:87], off offset:512 nt
	global_store_dwordx4 v[96:97], v[76:79], off offset:528 nt
	s_nop 0
	v_lshlrev_b32_e32 v84, 16, v226
	v_lshlrev_b32_e32 v76, 16, v224
	v_and_b32_e32 v77, 0xffff0000, v224
	v_pk_add_f32 v[76:77], v[80:81], v[76:77]
	v_lshlrev_b64 v[80:81], 12, v[190:191]
	v_lshlrev_b32_e32 v78, 16, v225
	v_and_b32_e32 v79, 0xffff0000, v225
	v_and_b32_e32 v85, 0xffff0000, v226
	v_lshlrev_b32_e32 v86, 16, v227
	v_and_b32_e32 v87, 0xffff0000, v227
	v_lshl_add_u64 v[80:81], s[6:7], 0, v[80:81]
	v_pk_add_f32 v[78:79], v[82:83], v[78:79]
	v_pk_add_f32 v[74:75], v[74:75], v[86:87]
	v_pk_add_f32 v[72:73], v[72:73], v[84:85]
	v_lshl_add_u64 v[80:81], v[80:81], 0, v[182:183]
	global_store_dwordx4 v[80:81], v[76:79], off nt
	global_store_dwordx4 v[80:81], v[72:75], off offset:16 nt
	s_nop 0
	v_lshlrev_b32_e32 v76, 16, v162
	v_lshlrev_b32_e32 v72, 16, v160
	v_and_b32_e32 v73, 0xffff0000, v160
	v_lshlrev_b32_e32 v74, 16, v161
	v_and_b32_e32 v75, 0xffff0000, v161
	v_and_b32_e32 v77, 0xffff0000, v162
	v_lshlrev_b32_e32 v78, 16, v163
	v_and_b32_e32 v79, 0xffff0000, v163
	v_pk_add_f32 v[70:71], v[70:71], v[74:75]
	v_pk_add_f32 v[68:69], v[68:69], v[72:73]
	v_pk_add_f32 v[64:65], v[64:65], v[76:77]
	v_pk_add_f32 v[66:67], v[66:67], v[78:79]
	global_store_dwordx4 v[80:81], v[68:71], off offset:512 nt
	global_store_dwordx4 v[80:81], v[64:67], off offset:528 nt
	s_nop 0
	v_lshlrev_b32_e32 v68, 16, v158
	v_lshlrev_b32_e32 v64, 16, v156
	v_and_b32_e32 v65, 0xffff0000, v156
	v_pk_add_f32 v[60:61], v[60:61], v[64:65]
	v_lshlrev_b64 v[64:65], 12, v[188:189]
	v_lshlrev_b32_e32 v66, 16, v157
	v_and_b32_e32 v67, 0xffff0000, v157
	v_and_b32_e32 v69, 0xffff0000, v158
	v_lshlrev_b32_e32 v70, 16, v159
	v_and_b32_e32 v71, 0xffff0000, v159
	v_lshl_add_u64 v[64:65], s[6:7], 0, v[64:65]
	v_pk_add_f32 v[62:63], v[62:63], v[66:67]
	v_pk_add_f32 v[58:59], v[58:59], v[70:71]
	v_pk_add_f32 v[56:57], v[56:57], v[68:69]
	v_lshl_add_u64 v[64:65], v[64:65], 0, v[182:183]
	global_store_dwordx4 v[64:65], v[60:63], off nt
	global_store_dwordx4 v[64:65], v[56:59], off offset:16 nt
	s_nop 0
	v_lshlrev_b32_e32 v60, 16, v154
	v_lshlrev_b32_e32 v56, 16, v152
	v_and_b32_e32 v57, 0xffff0000, v152
	v_lshlrev_b32_e32 v58, 16, v153
	v_and_b32_e32 v59, 0xffff0000, v153
	v_and_b32_e32 v61, 0xffff0000, v154
	v_lshlrev_b32_e32 v62, 16, v155
	v_and_b32_e32 v63, 0xffff0000, v155
	v_pk_add_f32 v[54:55], v[54:55], v[58:59]
	v_pk_add_f32 v[52:53], v[52:53], v[56:57]
	v_pk_add_f32 v[44:45], v[44:45], v[60:61]
	v_pk_add_f32 v[46:47], v[46:47], v[62:63]
	global_store_dwordx4 v[64:65], v[52:55], off offset:512 nt
	global_store_dwordx4 v[64:65], v[44:47], off offset:528 nt
	s_nop 0
	v_lshlrev_b32_e32 v52, 16, v150
	v_lshlrev_b32_e32 v44, 16, v148
	v_and_b32_e32 v45, 0xffff0000, v148
	v_pk_add_f32 v[44:45], v[48:49], v[44:45]
	v_lshlrev_b64 v[48:49], 12, v[186:187]
	v_lshlrev_b32_e32 v46, 16, v149
	v_and_b32_e32 v47, 0xffff0000, v149
	v_and_b32_e32 v53, 0xffff0000, v150
	v_lshlrev_b32_e32 v54, 16, v151
	v_and_b32_e32 v55, 0xffff0000, v151
	v_lshl_add_u64 v[48:49], s[6:7], 0, v[48:49]
	v_pk_add_f32 v[46:47], v[50:51], v[46:47]
	v_pk_add_f32 v[42:43], v[42:43], v[54:55]
	v_pk_add_f32 v[40:41], v[40:41], v[52:53]
	v_lshl_add_u64 v[48:49], v[48:49], 0, v[182:183]
	global_store_dwordx4 v[48:49], v[44:47], off nt
	global_store_dwordx4 v[48:49], v[40:43], off offset:16 nt
	s_nop 0
	v_lshlrev_b32_e32 v44, 16, v146
	v_lshlrev_b32_e32 v40, 16, v144
	v_and_b32_e32 v41, 0xffff0000, v144
	v_lshlrev_b32_e32 v42, 16, v145
	v_and_b32_e32 v43, 0xffff0000, v145
	v_and_b32_e32 v45, 0xffff0000, v146
	v_lshlrev_b32_e32 v46, 16, v147
	v_and_b32_e32 v47, 0xffff0000, v147
	v_pk_add_f32 v[38:39], v[38:39], v[42:43]
	v_pk_add_f32 v[36:37], v[36:37], v[40:41]
	v_pk_add_f32 v[28:29], v[28:29], v[44:45]
	v_pk_add_f32 v[30:31], v[30:31], v[46:47]
	global_store_dwordx4 v[48:49], v[36:39], off offset:512 nt
	global_store_dwordx4 v[48:49], v[28:31], off offset:528 nt
	s_nop 0
	v_lshlrev_b32_e32 v36, 16, v142
	v_lshlrev_b32_e32 v28, 16, v140
	v_and_b32_e32 v29, 0xffff0000, v140
	v_pk_add_f32 v[28:29], v[32:33], v[28:29]
	v_lshlrev_b64 v[32:33], 12, v[184:185]
	v_lshlrev_b32_e32 v30, 16, v141
	v_and_b32_e32 v31, 0xffff0000, v141
	v_and_b32_e32 v37, 0xffff0000, v142
	v_lshlrev_b32_e32 v38, 16, v143
	v_and_b32_e32 v39, 0xffff0000, v143
	v_lshl_add_u64 v[32:33], s[6:7], 0, v[32:33]
	v_pk_add_f32 v[30:31], v[34:35], v[30:31]
	v_pk_add_f32 v[26:27], v[26:27], v[38:39]
	v_pk_add_f32 v[24:25], v[24:25], v[36:37]
	v_lshl_add_u64 v[32:33], v[32:33], 0, v[182:183]
	global_store_dwordx4 v[32:33], v[28:31], off nt
	global_store_dwordx4 v[32:33], v[24:27], off offset:16 nt
	s_nop 0
	v_lshlrev_b32_e32 v28, 16, v138
	v_lshlrev_b32_e32 v24, 16, v136
	v_and_b32_e32 v25, 0xffff0000, v136
	v_lshlrev_b32_e32 v26, 16, v137
	v_and_b32_e32 v27, 0xffff0000, v137
	v_and_b32_e32 v29, 0xffff0000, v138
	v_lshlrev_b32_e32 v30, 16, v139
	v_and_b32_e32 v31, 0xffff0000, v139
	v_pk_add_f32 v[22:23], v[22:23], v[26:27]
	v_pk_add_f32 v[20:21], v[20:21], v[24:25]
	v_pk_add_f32 v[12:13], v[12:13], v[28:29]
	v_pk_add_f32 v[14:15], v[14:15], v[30:31]
	global_store_dwordx4 v[32:33], v[20:23], off offset:512 nt
	global_store_dwordx4 v[32:33], v[12:15], off offset:528 nt
	s_nop 0
	v_lshlrev_b32_e32 v20, 16, v134
	v_lshlrev_b32_e32 v12, 16, v132
	v_and_b32_e32 v13, 0xffff0000, v132
	v_pk_add_f32 v[12:13], v[16:17], v[12:13]
	v_lshlrev_b64 v[16:17], 12, v[180:181]
	v_lshlrev_b32_e32 v14, 16, v133
	v_and_b32_e32 v15, 0xffff0000, v133
	v_and_b32_e32 v21, 0xffff0000, v134
	v_lshlrev_b32_e32 v22, 16, v135
	v_and_b32_e32 v23, 0xffff0000, v135
	v_lshl_add_u64 v[16:17], s[6:7], 0, v[16:17]
	v_pk_add_f32 v[14:15], v[18:19], v[14:15]
	v_pk_add_f32 v[10:11], v[10:11], v[22:23]
	v_pk_add_f32 v[8:9], v[8:9], v[20:21]
	v_lshl_add_u64 v[16:17], v[16:17], 0, v[182:183]
	global_store_dwordx4 v[16:17], v[12:15], off nt
	global_store_dwordx4 v[16:17], v[8:11], off offset:16 nt
	s_nop 0
	v_lshlrev_b32_e32 v12, 16, v130
	v_lshlrev_b32_e32 v8, 16, v128
	v_and_b32_e32 v9, 0xffff0000, v128
	v_lshlrev_b32_e32 v10, 16, v129
	v_and_b32_e32 v11, 0xffff0000, v129
	v_and_b32_e32 v13, 0xffff0000, v130
	v_lshlrev_b32_e32 v14, 16, v131
	v_and_b32_e32 v15, 0xffff0000, v131
	v_pk_add_f32 v[6:7], v[6:7], v[10:11]
	v_pk_add_f32 v[4:5], v[4:5], v[8:9]
	v_pk_add_f32 v[2:3], v[2:3], v[14:15]
	v_pk_add_f32 v[0:1], v[0:1], v[12:13]
	global_store_dwordx4 v[16:17], v[4:7], off offset:512 nt
	global_store_dwordx4 v[16:17], v[0:3], off offset:528 nt
	s_cbranch_vccnz .LBB0_1261
	s_mov_b32 s101, 0
	s_andn2_b64 vcc, exec, s[8:9]
	s_cbranch_vccnz .LBB0_1260
	s_mov_b32 s101, 1
	s_branch .LBB0_1260
